# k3_cpv_lds
# speedup vs baseline: 1.0436x; 1.0147x over previous
; DI void phase_peer_b(const Params& p, int layer, const float* gnext, bool last) {
;     ...
; #pragma unroll 1
;   for (size_t row = (size_t)blockIdx.x * 4 + wave; row < (size_t)T; row += (size_t)gridDim.x * 4) {
;     const int i0 = ibuf[row * 128 + lane], i1 = ibuf[row * 128 + 64 + lane];
;     const float w0 = wbuf[row * 128 + lane], w1 = wbuf[row * 128 + 64 + lane];
;     float acc[16];
; #pragma unroll
;     for (int i = 0; i < 16; ++i) acc[i] = 0.f;
; #pragma unroll 1
;     for (int bt = 0; bt < 8; ++bt) {
;       u32x4 vr[16];
; #pragma unroll
;       for (int j = 0; j < 16; ++j) {
;         const int e = bt * 16 + j;
;         const int eidx = __builtin_amdgcn_readlane(e < 64 ? i0 : i1, e & 63);
;         vr[j] = *(const u32x4*)(EV + (size_t)eidx * DM + lane * 16);
;       }
.LBB0_501:
	s_or_b64 exec, exec, s[10:11]
	s_add_u32 s58, s68, 0x294a0800
	s_addc_u32 s59, s69, 0
	s_mov_b32 s3, 0
	v_mov_b32_e32 v181, 0
	s_add_u32 s60, s68, 0x2b4b0800
	v_lshl_add_u64 v[192:193], s[2:3], 2, v[180:181]
	s_mov_b64 s[10:11], 0x10080
	s_addc_u32 s61, s69, 0
	v_cmp_gt_u64_e64 s[10:11], s[10:11], v[192:193]
	v_lshlrev_b32_e32 v196, 6, v176
	s_barrier
	s_mov_b64 exec, -1
	v_mbcnt_lo_u32_b32 v165, -1, 0
	v_mbcnt_hi_u32_b32 v165, -1, v165
	v_and_b32_e32 v160, 7, v165
	v_lshlrev_b32_e32 v167, 6, v160
	v_lshlrev_b32_e32 v160, 4, v160
	v_lshrrev_b32_e32 v166, 3, v165
	s_and_b32 s24, s95, 7
	s_lshr_b32 s22, s95, 3
	s_lshr_b32 s23, s70, 3
	s_cmp_ge_u32 s22, s23
	s_cbranch_scc1 .Lpv0_end
	s_lshl_b32 s22, s22, 2
	s_add_u32 s22, s22, s94
	s_lshl_b32 s23, s23, 2
	s_lshl_b32 s25, s24, 21
	s_add_u32 s25, s25, 0x190c0000
	s_add_u32 s14, s68, s25
	s_addc_u32 s15, s69, 0
	s_add_u32 s16, s68, 0x2b4b0800
	s_addc_u32 s17, s69, 0
	s_add_u32 s18, s68, 0x294a0800
	s_addc_u32 s19, s69, 0
	s_lshl_b32 s25, s24, 9
	s_add_u32 s20, s68, s25
	s_addc_u32 s21, s69, 0
	s_mul_i32 s25, s94, 8320
	v_lshlrev_b32_e32 v162, 4, v165
	v_add_u32_e32 v162, s25, v162
	v_mul_u32_u24_e32 v163, 1040, v166
	v_add_u32_e32 v163, s25, v163
	v_and_b32_e32 v161, 31, v165
	v_lshlrev_b32_e32 v161, 4, v161
	v_mov_b32_e32 v168, s16
	v_mov_b32_e32 v169, s17
	v_mov_b32_e32 v170, s18
	v_mov_b32_e32 v171, s19
	v_cmp_gt_u32_e32 vcc, 32, v165
	s_nop 1
	v_cndmask_b32_e32 v168, v170, v168, vcc
	v_cndmask_b32_e32 v169, v171, v169, vcc
	v_add_co_u32_e32 v168, vcc, v168, v161
	s_nop 1
	v_addc_co_u32_e32 v169, vcc, 0, v169, vcc
	s_cmpk_ge_u32 s22, 0x2010
	s_cbranch_scc1 .Lpv0_end
.Lpv0_item:
	s_lshl_b32 s24, s22, 12
	s_mov_b32 s25, 0
	v_lshl_add_u64 v[170:171], v[168:169], 0, s[24:25]
	global_load_dwordx4 v[80:83], v[170:171], off offset:0
	global_load_dwordx4 v[84:87], v[170:171], off offset:512
	global_load_dwordx4 v[88:91], v[170:171], off offset:1024
	global_load_dwordx4 v[92:95], v[170:171], off offset:1536
	global_load_dwordx4 v[96:99], v[170:171], off offset:2048
	global_load_dwordx4 v[100:103], v[170:171], off offset:2560
	global_load_dwordx4 v[104:107], v[170:171], off offset:3072
	global_load_dwordx4 v[108:111], v[170:171], off offset:3584
	v_mov_b32_e32 v164, s22
	v_lshl_add_u32 v164, v164, 3, v166
	v_lshl_add_u32 v164, v164, 12, v167
	v_mov_b32_e32 v0, 0
	v_mov_b32_e32 v1, 0
	v_mov_b32_e32 v2, 0
	v_mov_b32_e32 v3, 0
	v_mov_b32_e32 v4, 0
	v_mov_b32_e32 v5, 0
	v_mov_b32_e32 v6, 0
	v_mov_b32_e32 v7, 0
	v_mov_b32_e32 v8, 0
	v_mov_b32_e32 v9, 0
	v_mov_b32_e32 v10, 0
	v_mov_b32_e32 v11, 0
	v_mov_b32_e32 v12, 0
	v_mov_b32_e32 v13, 0
	v_mov_b32_e32 v14, 0
	v_mov_b32_e32 v15, 0
	s_waitcnt vmcnt(0)
	ds_write_b128 v162, v[80:83]
	ds_write_b128 v162, v[84:87] offset:1040
	ds_write_b128 v162, v[88:91] offset:2080
	ds_write_b128 v162, v[92:95] offset:3120
	ds_write_b128 v162, v[96:99] offset:4160
	ds_write_b128 v162, v[100:103] offset:5200
	ds_write_b128 v162, v[104:107] offset:6240
	ds_write_b128 v162, v[108:111] offset:7280
	s_waitcnt lgkmcnt(0)
	ds_read_b128 v[16:19], v163 offset:0
	ds_read_b128 v[20:23], v163 offset:16
	ds_read_b128 v[24:27], v163 offset:32
	ds_read_b128 v[28:31], v163 offset:48
	ds_read_b128 v[48:51], v163 offset:512
	ds_read_b128 v[52:55], v163 offset:528
	ds_read_b128 v[56:59], v163 offset:544
	ds_read_b128 v[60:63], v163 offset:560
	ds_read_b128 v[32:35], v163 offset:64
	ds_read_b128 v[36:39], v163 offset:80
	ds_read_b128 v[40:43], v163 offset:96
	ds_read_b128 v[44:47], v163 offset:112
	s_waitcnt lgkmcnt(0)
	v_lshl_add_u32 v161, v16, 7, v160
	global_load_dwordx4 v[80:83], v161, s[14:15]
	v_lshl_add_u32 v161, v17, 7, v160
	global_load_dwordx4 v[84:87], v161, s[14:15]
	v_lshl_add_u32 v161, v18, 7, v160
	global_load_dwordx4 v[88:91], v161, s[14:15]
	v_lshl_add_u32 v161, v19, 7, v160
	global_load_dwordx4 v[92:95], v161, s[14:15]
	v_lshl_add_u32 v161, v20, 7, v160
	global_load_dwordx4 v[96:99], v161, s[14:15]
	v_lshl_add_u32 v161, v21, 7, v160
	global_load_dwordx4 v[100:103], v161, s[14:15]
	v_lshl_add_u32 v161, v22, 7, v160
	global_load_dwordx4 v[104:107], v161, s[14:15]
	v_lshl_add_u32 v161, v23, 7, v160
	global_load_dwordx4 v[108:111], v161, s[14:15]
	v_lshl_add_u32 v161, v24, 7, v160
	global_load_dwordx4 v[112:115], v161, s[14:15]
	v_lshl_add_u32 v161, v25, 7, v160
	global_load_dwordx4 v[116:119], v161, s[14:15]
	v_lshl_add_u32 v161, v26, 7, v160
	global_load_dwordx4 v[120:123], v161, s[14:15]
	v_lshl_add_u32 v161, v27, 7, v160
	global_load_dwordx4 v[124:127], v161, s[14:15]
	v_lshl_add_u32 v161, v28, 7, v160
	global_load_dwordx4 v[128:131], v161, s[14:15]
	v_lshl_add_u32 v161, v29, 7, v160
	global_load_dwordx4 v[132:135], v161, s[14:15]
	v_lshl_add_u32 v161, v30, 7, v160
	global_load_dwordx4 v[136:139], v161, s[14:15]
	v_lshl_add_u32 v161, v31, 7, v160
	global_load_dwordx4 v[140:143], v161, s[14:15]
	ds_read_b128 v[16:19], v163 offset:128
	ds_read_b128 v[20:23], v163 offset:144
	ds_read_b128 v[24:27], v163 offset:160
	ds_read_b128 v[28:31], v163 offset:176
	ds_read_b128 v[64:67], v163 offset:576
	ds_read_b128 v[68:71], v163 offset:592
	ds_read_b128 v[72:75], v163 offset:608
	ds_read_b128 v[76:79], v163 offset:624
	s_waitcnt vmcnt(15)
; DI void phase_peer_b(const Params& p, int layer, const float* gnext, bool last) {
;     ...
;     for (int bt = 0; bt < 8; ++bt) {
;       u32x4 vr[16];
; #pragma unroll
;       for (int j = 0; j < 16; ++j) {
;         const int e = bt * 16 + j;
;         const int eidx = __builtin_amdgcn_readlane(e < 64 ? i0 : i1, e & 63);
;         vr[j] = *(const u32x4*)(EV + (size_t)eidx * DM + lane * 16);
;       }
; #pragma unroll
;       for (int j = 0; j < 16; ++j) {
;         const int e = bt * 16 + j;
;         const float wj = __int_as_float(__builtin_amdgcn_readlane(__float_as_int(e < 64 ? w0 : w1), e & 63));
; #pragma unroll
;         for (int w = 0; w < 4; ++w) {
;           const f32x2 lo = __builtin_amdgcn_cvt_pk_f32_fp8((int)vr[j][w], false);
;           const f32x2 hi = __builtin_amdgcn_cvt_pk_f32_fp8((int)vr[j][w], true);
;           acc[4 * w] += wj * lo[0]; acc[4 * w + 1] += wj * lo[1]; acc[4 * w + 2] += wj * hi[0]; acc[4 * w + 3] += wj * hi[1];
;         }
;       }
	v_cvt_pk_f32_fp8_e32 v[144:145], v80
	v_cvt_pk_f32_fp8_sdwa v[146:147], v80 src0_sel:WORD_1
	v_cvt_pk_f32_fp8_e32 v[148:149], v81
	v_cvt_pk_f32_fp8_sdwa v[150:151], v81 src0_sel:WORD_1
	v_cvt_pk_f32_fp8_e32 v[152:153], v82
	v_cvt_pk_f32_fp8_sdwa v[154:155], v82 src0_sel:WORD_1
	v_cvt_pk_f32_fp8_e32 v[156:157], v83
	v_cvt_pk_f32_fp8_sdwa v[158:159], v83 src0_sel:WORD_1
	v_fmac_f32_e32 v0, v48, v144
	v_fmac_f32_e32 v1, v48, v145
	v_fmac_f32_e32 v2, v48, v146
	v_fmac_f32_e32 v3, v48, v147
	v_fmac_f32_e32 v4, v48, v148
	v_fmac_f32_e32 v5, v48, v149
	v_fmac_f32_e32 v6, v48, v150
	v_fmac_f32_e32 v7, v48, v151
	v_fmac_f32_e32 v8, v48, v152
	v_fmac_f32_e32 v9, v48, v153
	v_fmac_f32_e32 v10, v48, v154
	v_fmac_f32_e32 v11, v48, v155
	v_fmac_f32_e32 v12, v48, v156
	v_fmac_f32_e32 v13, v48, v157
	v_fmac_f32_e32 v14, v48, v158
	v_fmac_f32_e32 v15, v48, v159
	v_lshl_add_u32 v161, v32, 7, v160
	global_load_dwordx4 v[80:83], v161, s[14:15]
	s_waitcnt vmcnt(15)
	v_cvt_pk_f32_fp8_e32 v[144:145], v84
	v_cvt_pk_f32_fp8_sdwa v[146:147], v84 src0_sel:WORD_1
	v_cvt_pk_f32_fp8_e32 v[148:149], v85
	v_cvt_pk_f32_fp8_sdwa v[150:151], v85 src0_sel:WORD_1
	v_cvt_pk_f32_fp8_e32 v[152:153], v86
	v_cvt_pk_f32_fp8_sdwa v[154:155], v86 src0_sel:WORD_1
	v_cvt_pk_f32_fp8_e32 v[156:157], v87
	v_cvt_pk_f32_fp8_sdwa v[158:159], v87 src0_sel:WORD_1
	v_fmac_f32_e32 v0, v49, v144
	v_fmac_f32_e32 v1, v49, v145
	v_fmac_f32_e32 v2, v49, v146
	v_fmac_f32_e32 v3, v49, v147
	v_fmac_f32_e32 v4, v49, v148
	v_fmac_f32_e32 v5, v49, v149
	v_fmac_f32_e32 v6, v49, v150
	v_fmac_f32_e32 v7, v49, v151
	v_fmac_f32_e32 v8, v49, v152
	v_fmac_f32_e32 v9, v49, v153
	v_fmac_f32_e32 v10, v49, v154
	v_fmac_f32_e32 v11, v49, v155
	v_fmac_f32_e32 v12, v49, v156
	v_fmac_f32_e32 v13, v49, v157
	v_fmac_f32_e32 v14, v49, v158
	v_fmac_f32_e32 v15, v49, v159
	v_lshl_add_u32 v161, v33, 7, v160
	global_load_dwordx4 v[84:87], v161, s[14:15]
	s_waitcnt vmcnt(15)
	v_cvt_pk_f32_fp8_e32 v[144:145], v88
	v_cvt_pk_f32_fp8_sdwa v[146:147], v88 src0_sel:WORD_1
	v_cvt_pk_f32_fp8_e32 v[148:149], v89
	v_cvt_pk_f32_fp8_sdwa v[150:151], v89 src0_sel:WORD_1
	v_cvt_pk_f32_fp8_e32 v[152:153], v90
	v_cvt_pk_f32_fp8_sdwa v[154:155], v90 src0_sel:WORD_1
	v_cvt_pk_f32_fp8_e32 v[156:157], v91
	v_cvt_pk_f32_fp8_sdwa v[158:159], v91 src0_sel:WORD_1
	v_fmac_f32_e32 v0, v50, v144
	v_fmac_f32_e32 v1, v50, v145
	v_fmac_f32_e32 v2, v50, v146
	v_fmac_f32_e32 v3, v50, v147
	v_fmac_f32_e32 v4, v50, v148
	v_fmac_f32_e32 v5, v50, v149
	v_fmac_f32_e32 v6, v50, v150
	v_fmac_f32_e32 v7, v50, v151
	v_fmac_f32_e32 v8, v50, v152
	v_fmac_f32_e32 v9, v50, v153
	v_fmac_f32_e32 v10, v50, v154
	v_fmac_f32_e32 v11, v50, v155
	v_fmac_f32_e32 v12, v50, v156
	v_fmac_f32_e32 v13, v50, v157
	v_fmac_f32_e32 v14, v50, v158
	v_fmac_f32_e32 v15, v50, v159
	v_lshl_add_u32 v161, v34, 7, v160
	global_load_dwordx4 v[88:91], v161, s[14:15]
	s_waitcnt vmcnt(15)
	v_cvt_pk_f32_fp8_e32 v[144:145], v92
	v_cvt_pk_f32_fp8_sdwa v[146:147], v92 src0_sel:WORD_1
	v_cvt_pk_f32_fp8_e32 v[148:149], v93
	v_cvt_pk_f32_fp8_sdwa v[150:151], v93 src0_sel:WORD_1
	v_cvt_pk_f32_fp8_e32 v[152:153], v94
	v_cvt_pk_f32_fp8_sdwa v[154:155], v94 src0_sel:WORD_1
	v_cvt_pk_f32_fp8_e32 v[156:157], v95
	v_cvt_pk_f32_fp8_sdwa v[158:159], v95 src0_sel:WORD_1
	v_fmac_f32_e32 v0, v51, v144
	v_fmac_f32_e32 v1, v51, v145
	v_fmac_f32_e32 v2, v51, v146
	v_fmac_f32_e32 v3, v51, v147
	v_fmac_f32_e32 v4, v51, v148
	v_fmac_f32_e32 v5, v51, v149
	v_fmac_f32_e32 v6, v51, v150
	v_fmac_f32_e32 v7, v51, v151
	v_fmac_f32_e32 v8, v51, v152
	v_fmac_f32_e32 v9, v51, v153
	v_fmac_f32_e32 v10, v51, v154
	v_fmac_f32_e32 v11, v51, v155
	v_fmac_f32_e32 v12, v51, v156
	v_fmac_f32_e32 v13, v51, v157
	v_fmac_f32_e32 v14, v51, v158
	v_fmac_f32_e32 v15, v51, v159
	v_lshl_add_u32 v161, v35, 7, v160
	global_load_dwordx4 v[92:95], v161, s[14:15]
	s_waitcnt vmcnt(15)
	v_cvt_pk_f32_fp8_e32 v[144:145], v96
	v_cvt_pk_f32_fp8_sdwa v[146:147], v96 src0_sel:WORD_1
	v_cvt_pk_f32_fp8_e32 v[148:149], v97
	v_cvt_pk_f32_fp8_sdwa v[150:151], v97 src0_sel:WORD_1
	v_cvt_pk_f32_fp8_e32 v[152:153], v98
	v_cvt_pk_f32_fp8_sdwa v[154:155], v98 src0_sel:WORD_1
	v_cvt_pk_f32_fp8_e32 v[156:157], v99
	v_cvt_pk_f32_fp8_sdwa v[158:159], v99 src0_sel:WORD_1
	v_fmac_f32_e32 v0, v52, v144
	v_fmac_f32_e32 v1, v52, v145
	v_fmac_f32_e32 v2, v52, v146
	v_fmac_f32_e32 v3, v52, v147
	v_fmac_f32_e32 v4, v52, v148
	v_fmac_f32_e32 v5, v52, v149
	v_fmac_f32_e32 v6, v52, v150
	v_fmac_f32_e32 v7, v52, v151
	v_fmac_f32_e32 v8, v52, v152
	v_fmac_f32_e32 v9, v52, v153
	v_fmac_f32_e32 v10, v52, v154
	v_fmac_f32_e32 v11, v52, v155
	v_fmac_f32_e32 v12, v52, v156
	v_fmac_f32_e32 v13, v52, v157
	v_fmac_f32_e32 v14, v52, v158
	v_fmac_f32_e32 v15, v52, v159
	v_lshl_add_u32 v161, v36, 7, v160
	global_load_dwordx4 v[96:99], v161, s[14:15]
	s_waitcnt vmcnt(15)
	v_cvt_pk_f32_fp8_e32 v[144:145], v100
	v_cvt_pk_f32_fp8_sdwa v[146:147], v100 src0_sel:WORD_1
	v_cvt_pk_f32_fp8_e32 v[148:149], v101
	v_cvt_pk_f32_fp8_sdwa v[150:151], v101 src0_sel:WORD_1
	v_cvt_pk_f32_fp8_e32 v[152:153], v102
	v_cvt_pk_f32_fp8_sdwa v[154:155], v102 src0_sel:WORD_1
	v_cvt_pk_f32_fp8_e32 v[156:157], v103
	v_cvt_pk_f32_fp8_sdwa v[158:159], v103 src0_sel:WORD_1
	v_fmac_f32_e32 v0, v53, v144
	v_fmac_f32_e32 v1, v53, v145
	v_fmac_f32_e32 v2, v53, v146
	v_fmac_f32_e32 v3, v53, v147
	v_fmac_f32_e32 v4, v53, v148
	v_fmac_f32_e32 v5, v53, v149
	v_fmac_f32_e32 v6, v53, v150
	v_fmac_f32_e32 v7, v53, v151
	v_fmac_f32_e32 v8, v53, v152
	v_fmac_f32_e32 v9, v53, v153
	v_fmac_f32_e32 v10, v53, v154
	v_fmac_f32_e32 v11, v53, v155
	v_fmac_f32_e32 v12, v53, v156
	v_fmac_f32_e32 v13, v53, v157
	v_fmac_f32_e32 v14, v53, v158
	v_fmac_f32_e32 v15, v53, v159
	v_lshl_add_u32 v161, v37, 7, v160
	global_load_dwordx4 v[100:103], v161, s[14:15]
	s_waitcnt vmcnt(15)
; DI void phase_peer_b(const Params& p, int layer, const float* gnext, bool last) {
;     ...
;     for (int bt = 0; bt < 8; ++bt) {
;       u32x4 vr[16];
; #pragma unroll
;       for (int j = 0; j < 16; ++j) {
;         const int e = bt * 16 + j;
;         const int eidx = __builtin_amdgcn_readlane(e < 64 ? i0 : i1, e & 63);
;         vr[j] = *(const u32x4*)(EV + (size_t)eidx * DM + lane * 16);
;       }
; #pragma unroll
;       for (int j = 0; j < 16; ++j) {
;         const int e = bt * 16 + j;
;         const float wj = __int_as_float(__builtin_amdgcn_readlane(__float_as_int(e < 64 ? w0 : w1), e & 63));
; #pragma unroll
;         for (int w = 0; w < 4; ++w) {
;           const f32x2 lo = __builtin_amdgcn_cvt_pk_f32_fp8((int)vr[j][w], false);
;           const f32x2 hi = __builtin_amdgcn_cvt_pk_f32_fp8((int)vr[j][w], true);
;           acc[4 * w] += wj * lo[0]; acc[4 * w + 1] += wj * lo[1]; acc[4 * w + 2] += wj * hi[0]; acc[4 * w + 3] += wj * hi[1];
;         }
;       }
	v_cvt_pk_f32_fp8_e32 v[144:145], v104
	v_cvt_pk_f32_fp8_sdwa v[146:147], v104 src0_sel:WORD_1
	v_cvt_pk_f32_fp8_e32 v[148:149], v105
	v_cvt_pk_f32_fp8_sdwa v[150:151], v105 src0_sel:WORD_1
	v_cvt_pk_f32_fp8_e32 v[152:153], v106
	v_cvt_pk_f32_fp8_sdwa v[154:155], v106 src0_sel:WORD_1
	v_cvt_pk_f32_fp8_e32 v[156:157], v107
	v_cvt_pk_f32_fp8_sdwa v[158:159], v107 src0_sel:WORD_1
	v_fmac_f32_e32 v0, v54, v144
	v_fmac_f32_e32 v1, v54, v145
	v_fmac_f32_e32 v2, v54, v146
	v_fmac_f32_e32 v3, v54, v147
	v_fmac_f32_e32 v4, v54, v148
	v_fmac_f32_e32 v5, v54, v149
	v_fmac_f32_e32 v6, v54, v150
	v_fmac_f32_e32 v7, v54, v151
	v_fmac_f32_e32 v8, v54, v152
	v_fmac_f32_e32 v9, v54, v153
	v_fmac_f32_e32 v10, v54, v154
	v_fmac_f32_e32 v11, v54, v155
	v_fmac_f32_e32 v12, v54, v156
	v_fmac_f32_e32 v13, v54, v157
	v_fmac_f32_e32 v14, v54, v158
	v_fmac_f32_e32 v15, v54, v159
	v_lshl_add_u32 v161, v38, 7, v160
	global_load_dwordx4 v[104:107], v161, s[14:15]
	s_waitcnt vmcnt(15)
	v_cvt_pk_f32_fp8_e32 v[144:145], v108
	v_cvt_pk_f32_fp8_sdwa v[146:147], v108 src0_sel:WORD_1
	v_cvt_pk_f32_fp8_e32 v[148:149], v109
	v_cvt_pk_f32_fp8_sdwa v[150:151], v109 src0_sel:WORD_1
	v_cvt_pk_f32_fp8_e32 v[152:153], v110
	v_cvt_pk_f32_fp8_sdwa v[154:155], v110 src0_sel:WORD_1
	v_cvt_pk_f32_fp8_e32 v[156:157], v111
	v_cvt_pk_f32_fp8_sdwa v[158:159], v111 src0_sel:WORD_1
	v_fmac_f32_e32 v0, v55, v144
	v_fmac_f32_e32 v1, v55, v145
	v_fmac_f32_e32 v2, v55, v146
	v_fmac_f32_e32 v3, v55, v147
	v_fmac_f32_e32 v4, v55, v148
	v_fmac_f32_e32 v5, v55, v149
	v_fmac_f32_e32 v6, v55, v150
	v_fmac_f32_e32 v7, v55, v151
	v_fmac_f32_e32 v8, v55, v152
	v_fmac_f32_e32 v9, v55, v153
	v_fmac_f32_e32 v10, v55, v154
	v_fmac_f32_e32 v11, v55, v155
	v_fmac_f32_e32 v12, v55, v156
	v_fmac_f32_e32 v13, v55, v157
	v_fmac_f32_e32 v14, v55, v158
	v_fmac_f32_e32 v15, v55, v159
	v_lshl_add_u32 v161, v39, 7, v160
	global_load_dwordx4 v[108:111], v161, s[14:15]
	s_waitcnt vmcnt(15)
	v_cvt_pk_f32_fp8_e32 v[144:145], v112
	v_cvt_pk_f32_fp8_sdwa v[146:147], v112 src0_sel:WORD_1
	v_cvt_pk_f32_fp8_e32 v[148:149], v113
	v_cvt_pk_f32_fp8_sdwa v[150:151], v113 src0_sel:WORD_1
	v_cvt_pk_f32_fp8_e32 v[152:153], v114
	v_cvt_pk_f32_fp8_sdwa v[154:155], v114 src0_sel:WORD_1
	v_cvt_pk_f32_fp8_e32 v[156:157], v115
	v_cvt_pk_f32_fp8_sdwa v[158:159], v115 src0_sel:WORD_1
	v_fmac_f32_e32 v0, v56, v144
	v_fmac_f32_e32 v1, v56, v145
	v_fmac_f32_e32 v2, v56, v146
	v_fmac_f32_e32 v3, v56, v147
	v_fmac_f32_e32 v4, v56, v148
	v_fmac_f32_e32 v5, v56, v149
	v_fmac_f32_e32 v6, v56, v150
	v_fmac_f32_e32 v7, v56, v151
	v_fmac_f32_e32 v8, v56, v152
	v_fmac_f32_e32 v9, v56, v153
	v_fmac_f32_e32 v10, v56, v154
	v_fmac_f32_e32 v11, v56, v155
	v_fmac_f32_e32 v12, v56, v156
	v_fmac_f32_e32 v13, v56, v157
	v_fmac_f32_e32 v14, v56, v158
	v_fmac_f32_e32 v15, v56, v159
	v_lshl_add_u32 v161, v40, 7, v160
	global_load_dwordx4 v[112:115], v161, s[14:15]
	s_waitcnt vmcnt(15)
	v_cvt_pk_f32_fp8_e32 v[144:145], v116
	v_cvt_pk_f32_fp8_sdwa v[146:147], v116 src0_sel:WORD_1
	v_cvt_pk_f32_fp8_e32 v[148:149], v117
	v_cvt_pk_f32_fp8_sdwa v[150:151], v117 src0_sel:WORD_1
	v_cvt_pk_f32_fp8_e32 v[152:153], v118
	v_cvt_pk_f32_fp8_sdwa v[154:155], v118 src0_sel:WORD_1
	v_cvt_pk_f32_fp8_e32 v[156:157], v119
	v_cvt_pk_f32_fp8_sdwa v[158:159], v119 src0_sel:WORD_1
	v_fmac_f32_e32 v0, v57, v144
	v_fmac_f32_e32 v1, v57, v145
	v_fmac_f32_e32 v2, v57, v146
	v_fmac_f32_e32 v3, v57, v147
	v_fmac_f32_e32 v4, v57, v148
	v_fmac_f32_e32 v5, v57, v149
	v_fmac_f32_e32 v6, v57, v150
	v_fmac_f32_e32 v7, v57, v151
	v_fmac_f32_e32 v8, v57, v152
	v_fmac_f32_e32 v9, v57, v153
	v_fmac_f32_e32 v10, v57, v154
	v_fmac_f32_e32 v11, v57, v155
	v_fmac_f32_e32 v12, v57, v156
	v_fmac_f32_e32 v13, v57, v157
	v_fmac_f32_e32 v14, v57, v158
	v_fmac_f32_e32 v15, v57, v159
	v_lshl_add_u32 v161, v41, 7, v160
	global_load_dwordx4 v[116:119], v161, s[14:15]
	s_waitcnt vmcnt(15)
	v_cvt_pk_f32_fp8_e32 v[144:145], v120
	v_cvt_pk_f32_fp8_sdwa v[146:147], v120 src0_sel:WORD_1
	v_cvt_pk_f32_fp8_e32 v[148:149], v121
	v_cvt_pk_f32_fp8_sdwa v[150:151], v121 src0_sel:WORD_1
	v_cvt_pk_f32_fp8_e32 v[152:153], v122
	v_cvt_pk_f32_fp8_sdwa v[154:155], v122 src0_sel:WORD_1
	v_cvt_pk_f32_fp8_e32 v[156:157], v123
	v_cvt_pk_f32_fp8_sdwa v[158:159], v123 src0_sel:WORD_1
	v_fmac_f32_e32 v0, v58, v144
	v_fmac_f32_e32 v1, v58, v145
	v_fmac_f32_e32 v2, v58, v146
	v_fmac_f32_e32 v3, v58, v147
	v_fmac_f32_e32 v4, v58, v148
	v_fmac_f32_e32 v5, v58, v149
	v_fmac_f32_e32 v6, v58, v150
	v_fmac_f32_e32 v7, v58, v151
	v_fmac_f32_e32 v8, v58, v152
	v_fmac_f32_e32 v9, v58, v153
	v_fmac_f32_e32 v10, v58, v154
	v_fmac_f32_e32 v11, v58, v155
	v_fmac_f32_e32 v12, v58, v156
	v_fmac_f32_e32 v13, v58, v157
	v_fmac_f32_e32 v14, v58, v158
	v_fmac_f32_e32 v15, v58, v159
	v_lshl_add_u32 v161, v42, 7, v160
	global_load_dwordx4 v[120:123], v161, s[14:15]
	s_waitcnt vmcnt(15)
	v_cvt_pk_f32_fp8_e32 v[144:145], v124
	v_cvt_pk_f32_fp8_sdwa v[146:147], v124 src0_sel:WORD_1
	v_cvt_pk_f32_fp8_e32 v[148:149], v125
	v_cvt_pk_f32_fp8_sdwa v[150:151], v125 src0_sel:WORD_1
	v_cvt_pk_f32_fp8_e32 v[152:153], v126
	v_cvt_pk_f32_fp8_sdwa v[154:155], v126 src0_sel:WORD_1
	v_cvt_pk_f32_fp8_e32 v[156:157], v127
	v_cvt_pk_f32_fp8_sdwa v[158:159], v127 src0_sel:WORD_1
	v_fmac_f32_e32 v0, v59, v144
	v_fmac_f32_e32 v1, v59, v145
	v_fmac_f32_e32 v2, v59, v146
	v_fmac_f32_e32 v3, v59, v147
	v_fmac_f32_e32 v4, v59, v148
	v_fmac_f32_e32 v5, v59, v149
	v_fmac_f32_e32 v6, v59, v150
	v_fmac_f32_e32 v7, v59, v151
	v_fmac_f32_e32 v8, v59, v152
	v_fmac_f32_e32 v9, v59, v153
	v_fmac_f32_e32 v10, v59, v154
	v_fmac_f32_e32 v11, v59, v155
	v_fmac_f32_e32 v12, v59, v156
	v_fmac_f32_e32 v13, v59, v157
	v_fmac_f32_e32 v14, v59, v158
	v_fmac_f32_e32 v15, v59, v159
	v_lshl_add_u32 v161, v43, 7, v160
	global_load_dwordx4 v[124:127], v161, s[14:15]
	s_waitcnt vmcnt(15)
; DI void phase_peer_b(const Params& p, int layer, const float* gnext, bool last) {
;     ...
;     for (int bt = 0; bt < 8; ++bt) {
;       u32x4 vr[16];
; #pragma unroll
;       for (int j = 0; j < 16; ++j) {
;         const int e = bt * 16 + j;
;         const int eidx = __builtin_amdgcn_readlane(e < 64 ? i0 : i1, e & 63);
;         vr[j] = *(const u32x4*)(EV + (size_t)eidx * DM + lane * 16);
;       }
; #pragma unroll
;       for (int j = 0; j < 16; ++j) {
;         const int e = bt * 16 + j;
;         const float wj = __int_as_float(__builtin_amdgcn_readlane(__float_as_int(e < 64 ? w0 : w1), e & 63));
; #pragma unroll
;         for (int w = 0; w < 4; ++w) {
;           const f32x2 lo = __builtin_amdgcn_cvt_pk_f32_fp8((int)vr[j][w], false);
;           const f32x2 hi = __builtin_amdgcn_cvt_pk_f32_fp8((int)vr[j][w], true);
;           acc[4 * w] += wj * lo[0]; acc[4 * w + 1] += wj * lo[1]; acc[4 * w + 2] += wj * hi[0]; acc[4 * w + 3] += wj * hi[1];
;         }
;       }
	v_cvt_pk_f32_fp8_e32 v[144:145], v128
	v_cvt_pk_f32_fp8_sdwa v[146:147], v128 src0_sel:WORD_1
	v_cvt_pk_f32_fp8_e32 v[148:149], v129
	v_cvt_pk_f32_fp8_sdwa v[150:151], v129 src0_sel:WORD_1
	v_cvt_pk_f32_fp8_e32 v[152:153], v130
	v_cvt_pk_f32_fp8_sdwa v[154:155], v130 src0_sel:WORD_1
	v_cvt_pk_f32_fp8_e32 v[156:157], v131
	v_cvt_pk_f32_fp8_sdwa v[158:159], v131 src0_sel:WORD_1
	v_fmac_f32_e32 v0, v60, v144
	v_fmac_f32_e32 v1, v60, v145
	v_fmac_f32_e32 v2, v60, v146
	v_fmac_f32_e32 v3, v60, v147
	v_fmac_f32_e32 v4, v60, v148
	v_fmac_f32_e32 v5, v60, v149
	v_fmac_f32_e32 v6, v60, v150
	v_fmac_f32_e32 v7, v60, v151
	v_fmac_f32_e32 v8, v60, v152
	v_fmac_f32_e32 v9, v60, v153
	v_fmac_f32_e32 v10, v60, v154
	v_fmac_f32_e32 v11, v60, v155
	v_fmac_f32_e32 v12, v60, v156
	v_fmac_f32_e32 v13, v60, v157
	v_fmac_f32_e32 v14, v60, v158
	v_fmac_f32_e32 v15, v60, v159
	v_lshl_add_u32 v161, v44, 7, v160
	global_load_dwordx4 v[128:131], v161, s[14:15]
	s_waitcnt vmcnt(15)
	v_cvt_pk_f32_fp8_e32 v[144:145], v132
	v_cvt_pk_f32_fp8_sdwa v[146:147], v132 src0_sel:WORD_1
	v_cvt_pk_f32_fp8_e32 v[148:149], v133
	v_cvt_pk_f32_fp8_sdwa v[150:151], v133 src0_sel:WORD_1
	v_cvt_pk_f32_fp8_e32 v[152:153], v134
	v_cvt_pk_f32_fp8_sdwa v[154:155], v134 src0_sel:WORD_1
	v_cvt_pk_f32_fp8_e32 v[156:157], v135
	v_cvt_pk_f32_fp8_sdwa v[158:159], v135 src0_sel:WORD_1
	v_fmac_f32_e32 v0, v61, v144
	v_fmac_f32_e32 v1, v61, v145
	v_fmac_f32_e32 v2, v61, v146
	v_fmac_f32_e32 v3, v61, v147
	v_fmac_f32_e32 v4, v61, v148
	v_fmac_f32_e32 v5, v61, v149
	v_fmac_f32_e32 v6, v61, v150
	v_fmac_f32_e32 v7, v61, v151
	v_fmac_f32_e32 v8, v61, v152
	v_fmac_f32_e32 v9, v61, v153
	v_fmac_f32_e32 v10, v61, v154
	v_fmac_f32_e32 v11, v61, v155
	v_fmac_f32_e32 v12, v61, v156
	v_fmac_f32_e32 v13, v61, v157
	v_fmac_f32_e32 v14, v61, v158
	v_fmac_f32_e32 v15, v61, v159
	v_lshl_add_u32 v161, v45, 7, v160
	global_load_dwordx4 v[132:135], v161, s[14:15]
	s_waitcnt vmcnt(15)
	v_cvt_pk_f32_fp8_e32 v[144:145], v136
	v_cvt_pk_f32_fp8_sdwa v[146:147], v136 src0_sel:WORD_1
	v_cvt_pk_f32_fp8_e32 v[148:149], v137
	v_cvt_pk_f32_fp8_sdwa v[150:151], v137 src0_sel:WORD_1
	v_cvt_pk_f32_fp8_e32 v[152:153], v138
	v_cvt_pk_f32_fp8_sdwa v[154:155], v138 src0_sel:WORD_1
	v_cvt_pk_f32_fp8_e32 v[156:157], v139
	v_cvt_pk_f32_fp8_sdwa v[158:159], v139 src0_sel:WORD_1
	v_fmac_f32_e32 v0, v62, v144
	v_fmac_f32_e32 v1, v62, v145
	v_fmac_f32_e32 v2, v62, v146
	v_fmac_f32_e32 v3, v62, v147
	v_fmac_f32_e32 v4, v62, v148
	v_fmac_f32_e32 v5, v62, v149
	v_fmac_f32_e32 v6, v62, v150
	v_fmac_f32_e32 v7, v62, v151
	v_fmac_f32_e32 v8, v62, v152
	v_fmac_f32_e32 v9, v62, v153
	v_fmac_f32_e32 v10, v62, v154
	v_fmac_f32_e32 v11, v62, v155
	v_fmac_f32_e32 v12, v62, v156
	v_fmac_f32_e32 v13, v62, v157
	v_fmac_f32_e32 v14, v62, v158
	v_fmac_f32_e32 v15, v62, v159
	v_lshl_add_u32 v161, v46, 7, v160
	global_load_dwordx4 v[136:139], v161, s[14:15]
	s_waitcnt vmcnt(15)
	v_cvt_pk_f32_fp8_e32 v[144:145], v140
	v_cvt_pk_f32_fp8_sdwa v[146:147], v140 src0_sel:WORD_1
	v_cvt_pk_f32_fp8_e32 v[148:149], v141
	v_cvt_pk_f32_fp8_sdwa v[150:151], v141 src0_sel:WORD_1
	v_cvt_pk_f32_fp8_e32 v[152:153], v142
	v_cvt_pk_f32_fp8_sdwa v[154:155], v142 src0_sel:WORD_1
	v_cvt_pk_f32_fp8_e32 v[156:157], v143
	v_cvt_pk_f32_fp8_sdwa v[158:159], v143 src0_sel:WORD_1
	v_fmac_f32_e32 v0, v63, v144
	v_fmac_f32_e32 v1, v63, v145
	v_fmac_f32_e32 v2, v63, v146
	v_fmac_f32_e32 v3, v63, v147
	v_fmac_f32_e32 v4, v63, v148
	v_fmac_f32_e32 v5, v63, v149
	v_fmac_f32_e32 v6, v63, v150
	v_fmac_f32_e32 v7, v63, v151
	v_fmac_f32_e32 v8, v63, v152
	v_fmac_f32_e32 v9, v63, v153
	v_fmac_f32_e32 v10, v63, v154
	v_fmac_f32_e32 v11, v63, v155
	v_fmac_f32_e32 v12, v63, v156
	v_fmac_f32_e32 v13, v63, v157
	v_fmac_f32_e32 v14, v63, v158
	v_fmac_f32_e32 v15, v63, v159
	v_lshl_add_u32 v161, v47, 7, v160
	global_load_dwordx4 v[140:143], v161, s[14:15]
	s_waitcnt lgkmcnt(0)
	ds_read_b128 v[32:35], v163 offset:192
	ds_read_b128 v[36:39], v163 offset:208
	ds_read_b128 v[40:43], v163 offset:224
	ds_read_b128 v[44:47], v163 offset:240
	ds_read_b128 v[48:51], v163 offset:640
	ds_read_b128 v[52:55], v163 offset:656
	ds_read_b128 v[56:59], v163 offset:672
	ds_read_b128 v[60:63], v163 offset:688
	s_waitcnt vmcnt(15)
	v_cvt_pk_f32_fp8_e32 v[144:145], v80
	v_cvt_pk_f32_fp8_sdwa v[146:147], v80 src0_sel:WORD_1
	v_cvt_pk_f32_fp8_e32 v[148:149], v81
	v_cvt_pk_f32_fp8_sdwa v[150:151], v81 src0_sel:WORD_1
	v_cvt_pk_f32_fp8_e32 v[152:153], v82
	v_cvt_pk_f32_fp8_sdwa v[154:155], v82 src0_sel:WORD_1
	v_cvt_pk_f32_fp8_e32 v[156:157], v83
	v_cvt_pk_f32_fp8_sdwa v[158:159], v83 src0_sel:WORD_1
	v_fmac_f32_e32 v0, v64, v144
	v_fmac_f32_e32 v1, v64, v145
	v_fmac_f32_e32 v2, v64, v146
	v_fmac_f32_e32 v3, v64, v147
	v_fmac_f32_e32 v4, v64, v148
	v_fmac_f32_e32 v5, v64, v149
	v_fmac_f32_e32 v6, v64, v150
	v_fmac_f32_e32 v7, v64, v151
	v_fmac_f32_e32 v8, v64, v152
	v_fmac_f32_e32 v9, v64, v153
	v_fmac_f32_e32 v10, v64, v154
	v_fmac_f32_e32 v11, v64, v155
	v_fmac_f32_e32 v12, v64, v156
	v_fmac_f32_e32 v13, v64, v157
	v_fmac_f32_e32 v14, v64, v158
	v_fmac_f32_e32 v15, v64, v159
	v_lshl_add_u32 v161, v16, 7, v160
	global_load_dwordx4 v[80:83], v161, s[14:15]
	s_waitcnt vmcnt(15)
; DI void phase_peer_b(const Params& p, int layer, const float* gnext, bool last) {
;     ...
;     for (int bt = 0; bt < 8; ++bt) {
;       u32x4 vr[16];
; #pragma unroll
;       for (int j = 0; j < 16; ++j) {
;         const int e = bt * 16 + j;
;         const int eidx = __builtin_amdgcn_readlane(e < 64 ? i0 : i1, e & 63);
;         vr[j] = *(const u32x4*)(EV + (size_t)eidx * DM + lane * 16);
;       }
; #pragma unroll
;       for (int j = 0; j < 16; ++j) {
;         const int e = bt * 16 + j;
;         const float wj = __int_as_float(__builtin_amdgcn_readlane(__float_as_int(e < 64 ? w0 : w1), e & 63));
; #pragma unroll
;         for (int w = 0; w < 4; ++w) {
;           const f32x2 lo = __builtin_amdgcn_cvt_pk_f32_fp8((int)vr[j][w], false);
;           const f32x2 hi = __builtin_amdgcn_cvt_pk_f32_fp8((int)vr[j][w], true);
;           acc[4 * w] += wj * lo[0]; acc[4 * w + 1] += wj * lo[1]; acc[4 * w + 2] += wj * hi[0]; acc[4 * w + 3] += wj * hi[1];
;         }
;       }
	v_cvt_pk_f32_fp8_e32 v[144:145], v84
	v_cvt_pk_f32_fp8_sdwa v[146:147], v84 src0_sel:WORD_1
	v_cvt_pk_f32_fp8_e32 v[148:149], v85
	v_cvt_pk_f32_fp8_sdwa v[150:151], v85 src0_sel:WORD_1
	v_cvt_pk_f32_fp8_e32 v[152:153], v86
	v_cvt_pk_f32_fp8_sdwa v[154:155], v86 src0_sel:WORD_1
	v_cvt_pk_f32_fp8_e32 v[156:157], v87
	v_cvt_pk_f32_fp8_sdwa v[158:159], v87 src0_sel:WORD_1
	v_fmac_f32_e32 v0, v65, v144
	v_fmac_f32_e32 v1, v65, v145
	v_fmac_f32_e32 v2, v65, v146
	v_fmac_f32_e32 v3, v65, v147
	v_fmac_f32_e32 v4, v65, v148
	v_fmac_f32_e32 v5, v65, v149
	v_fmac_f32_e32 v6, v65, v150
	v_fmac_f32_e32 v7, v65, v151
	v_fmac_f32_e32 v8, v65, v152
	v_fmac_f32_e32 v9, v65, v153
	v_fmac_f32_e32 v10, v65, v154
	v_fmac_f32_e32 v11, v65, v155
	v_fmac_f32_e32 v12, v65, v156
	v_fmac_f32_e32 v13, v65, v157
	v_fmac_f32_e32 v14, v65, v158
	v_fmac_f32_e32 v15, v65, v159
	v_lshl_add_u32 v161, v17, 7, v160
	global_load_dwordx4 v[84:87], v161, s[14:15]
	s_waitcnt vmcnt(15)
	v_cvt_pk_f32_fp8_e32 v[144:145], v88
	v_cvt_pk_f32_fp8_sdwa v[146:147], v88 src0_sel:WORD_1
	v_cvt_pk_f32_fp8_e32 v[148:149], v89
	v_cvt_pk_f32_fp8_sdwa v[150:151], v89 src0_sel:WORD_1
	v_cvt_pk_f32_fp8_e32 v[152:153], v90
	v_cvt_pk_f32_fp8_sdwa v[154:155], v90 src0_sel:WORD_1
	v_cvt_pk_f32_fp8_e32 v[156:157], v91
	v_cvt_pk_f32_fp8_sdwa v[158:159], v91 src0_sel:WORD_1
	v_fmac_f32_e32 v0, v66, v144
	v_fmac_f32_e32 v1, v66, v145
	v_fmac_f32_e32 v2, v66, v146
	v_fmac_f32_e32 v3, v66, v147
	v_fmac_f32_e32 v4, v66, v148
	v_fmac_f32_e32 v5, v66, v149
	v_fmac_f32_e32 v6, v66, v150
	v_fmac_f32_e32 v7, v66, v151
	v_fmac_f32_e32 v8, v66, v152
	v_fmac_f32_e32 v9, v66, v153
	v_fmac_f32_e32 v10, v66, v154
	v_fmac_f32_e32 v11, v66, v155
	v_fmac_f32_e32 v12, v66, v156
	v_fmac_f32_e32 v13, v66, v157
	v_fmac_f32_e32 v14, v66, v158
	v_fmac_f32_e32 v15, v66, v159
	v_lshl_add_u32 v161, v18, 7, v160
	global_load_dwordx4 v[88:91], v161, s[14:15]
	s_waitcnt vmcnt(15)
	v_cvt_pk_f32_fp8_e32 v[144:145], v92
	v_cvt_pk_f32_fp8_sdwa v[146:147], v92 src0_sel:WORD_1
	v_cvt_pk_f32_fp8_e32 v[148:149], v93
	v_cvt_pk_f32_fp8_sdwa v[150:151], v93 src0_sel:WORD_1
	v_cvt_pk_f32_fp8_e32 v[152:153], v94
	v_cvt_pk_f32_fp8_sdwa v[154:155], v94 src0_sel:WORD_1
	v_cvt_pk_f32_fp8_e32 v[156:157], v95
	v_cvt_pk_f32_fp8_sdwa v[158:159], v95 src0_sel:WORD_1
	v_fmac_f32_e32 v0, v67, v144
	v_fmac_f32_e32 v1, v67, v145
	v_fmac_f32_e32 v2, v67, v146
	v_fmac_f32_e32 v3, v67, v147
	v_fmac_f32_e32 v4, v67, v148
	v_fmac_f32_e32 v5, v67, v149
	v_fmac_f32_e32 v6, v67, v150
	v_fmac_f32_e32 v7, v67, v151
	v_fmac_f32_e32 v8, v67, v152
	v_fmac_f32_e32 v9, v67, v153
	v_fmac_f32_e32 v10, v67, v154
	v_fmac_f32_e32 v11, v67, v155
	v_fmac_f32_e32 v12, v67, v156
	v_fmac_f32_e32 v13, v67, v157
	v_fmac_f32_e32 v14, v67, v158
	v_fmac_f32_e32 v15, v67, v159
	v_lshl_add_u32 v161, v19, 7, v160
	global_load_dwordx4 v[92:95], v161, s[14:15]
	s_waitcnt vmcnt(15)
	v_cvt_pk_f32_fp8_e32 v[144:145], v96
	v_cvt_pk_f32_fp8_sdwa v[146:147], v96 src0_sel:WORD_1
	v_cvt_pk_f32_fp8_e32 v[148:149], v97
	v_cvt_pk_f32_fp8_sdwa v[150:151], v97 src0_sel:WORD_1
	v_cvt_pk_f32_fp8_e32 v[152:153], v98
	v_cvt_pk_f32_fp8_sdwa v[154:155], v98 src0_sel:WORD_1
	v_cvt_pk_f32_fp8_e32 v[156:157], v99
	v_cvt_pk_f32_fp8_sdwa v[158:159], v99 src0_sel:WORD_1
	v_fmac_f32_e32 v0, v68, v144
	v_fmac_f32_e32 v1, v68, v145
	v_fmac_f32_e32 v2, v68, v146
	v_fmac_f32_e32 v3, v68, v147
	v_fmac_f32_e32 v4, v68, v148
	v_fmac_f32_e32 v5, v68, v149
	v_fmac_f32_e32 v6, v68, v150
	v_fmac_f32_e32 v7, v68, v151
	v_fmac_f32_e32 v8, v68, v152
	v_fmac_f32_e32 v9, v68, v153
	v_fmac_f32_e32 v10, v68, v154
	v_fmac_f32_e32 v11, v68, v155
	v_fmac_f32_e32 v12, v68, v156
	v_fmac_f32_e32 v13, v68, v157
	v_fmac_f32_e32 v14, v68, v158
	v_fmac_f32_e32 v15, v68, v159
	v_lshl_add_u32 v161, v20, 7, v160
	global_load_dwordx4 v[96:99], v161, s[14:15]
	s_waitcnt vmcnt(15)
	v_cvt_pk_f32_fp8_e32 v[144:145], v100
	v_cvt_pk_f32_fp8_sdwa v[146:147], v100 src0_sel:WORD_1
	v_cvt_pk_f32_fp8_e32 v[148:149], v101
	v_cvt_pk_f32_fp8_sdwa v[150:151], v101 src0_sel:WORD_1
	v_cvt_pk_f32_fp8_e32 v[152:153], v102
	v_cvt_pk_f32_fp8_sdwa v[154:155], v102 src0_sel:WORD_1
	v_cvt_pk_f32_fp8_e32 v[156:157], v103
	v_cvt_pk_f32_fp8_sdwa v[158:159], v103 src0_sel:WORD_1
	v_fmac_f32_e32 v0, v69, v144
	v_fmac_f32_e32 v1, v69, v145
	v_fmac_f32_e32 v2, v69, v146
	v_fmac_f32_e32 v3, v69, v147
	v_fmac_f32_e32 v4, v69, v148
	v_fmac_f32_e32 v5, v69, v149
	v_fmac_f32_e32 v6, v69, v150
	v_fmac_f32_e32 v7, v69, v151
	v_fmac_f32_e32 v8, v69, v152
	v_fmac_f32_e32 v9, v69, v153
	v_fmac_f32_e32 v10, v69, v154
	v_fmac_f32_e32 v11, v69, v155
	v_fmac_f32_e32 v12, v69, v156
	v_fmac_f32_e32 v13, v69, v157
	v_fmac_f32_e32 v14, v69, v158
	v_fmac_f32_e32 v15, v69, v159
	v_lshl_add_u32 v161, v21, 7, v160
	global_load_dwordx4 v[100:103], v161, s[14:15]
	s_waitcnt vmcnt(15)
	v_cvt_pk_f32_fp8_e32 v[144:145], v104
	v_cvt_pk_f32_fp8_sdwa v[146:147], v104 src0_sel:WORD_1
	v_cvt_pk_f32_fp8_e32 v[148:149], v105
	v_cvt_pk_f32_fp8_sdwa v[150:151], v105 src0_sel:WORD_1
	v_cvt_pk_f32_fp8_e32 v[152:153], v106
	v_cvt_pk_f32_fp8_sdwa v[154:155], v106 src0_sel:WORD_1
	v_cvt_pk_f32_fp8_e32 v[156:157], v107
	v_cvt_pk_f32_fp8_sdwa v[158:159], v107 src0_sel:WORD_1
	v_fmac_f32_e32 v0, v70, v144
	v_fmac_f32_e32 v1, v70, v145
	v_fmac_f32_e32 v2, v70, v146
	v_fmac_f32_e32 v3, v70, v147
	v_fmac_f32_e32 v4, v70, v148
	v_fmac_f32_e32 v5, v70, v149
	v_fmac_f32_e32 v6, v70, v150
	v_fmac_f32_e32 v7, v70, v151
	v_fmac_f32_e32 v8, v70, v152
	v_fmac_f32_e32 v9, v70, v153
	v_fmac_f32_e32 v10, v70, v154
	v_fmac_f32_e32 v11, v70, v155
	v_fmac_f32_e32 v12, v70, v156
	v_fmac_f32_e32 v13, v70, v157
	v_fmac_f32_e32 v14, v70, v158
	v_fmac_f32_e32 v15, v70, v159
	v_lshl_add_u32 v161, v22, 7, v160
	global_load_dwordx4 v[104:107], v161, s[14:15]
	s_waitcnt vmcnt(15)
; DI void phase_peer_b(const Params& p, int layer, const float* gnext, bool last) {
;     ...
;     for (int bt = 0; bt < 8; ++bt) {
;       u32x4 vr[16];
; #pragma unroll
;       for (int j = 0; j < 16; ++j) {
;         const int e = bt * 16 + j;
;         const int eidx = __builtin_amdgcn_readlane(e < 64 ? i0 : i1, e & 63);
;         vr[j] = *(const u32x4*)(EV + (size_t)eidx * DM + lane * 16);
;       }
; #pragma unroll
;       for (int j = 0; j < 16; ++j) {
;         const int e = bt * 16 + j;
;         const float wj = __int_as_float(__builtin_amdgcn_readlane(__float_as_int(e < 64 ? w0 : w1), e & 63));
; #pragma unroll
;         for (int w = 0; w < 4; ++w) {
;           const f32x2 lo = __builtin_amdgcn_cvt_pk_f32_fp8((int)vr[j][w], false);
;           const f32x2 hi = __builtin_amdgcn_cvt_pk_f32_fp8((int)vr[j][w], true);
;           acc[4 * w] += wj * lo[0]; acc[4 * w + 1] += wj * lo[1]; acc[4 * w + 2] += wj * hi[0]; acc[4 * w + 3] += wj * hi[1];
;         }
;       }
	v_cvt_pk_f32_fp8_e32 v[144:145], v108
	v_cvt_pk_f32_fp8_sdwa v[146:147], v108 src0_sel:WORD_1
	v_cvt_pk_f32_fp8_e32 v[148:149], v109
	v_cvt_pk_f32_fp8_sdwa v[150:151], v109 src0_sel:WORD_1
	v_cvt_pk_f32_fp8_e32 v[152:153], v110
	v_cvt_pk_f32_fp8_sdwa v[154:155], v110 src0_sel:WORD_1
	v_cvt_pk_f32_fp8_e32 v[156:157], v111
	v_cvt_pk_f32_fp8_sdwa v[158:159], v111 src0_sel:WORD_1
	v_fmac_f32_e32 v0, v71, v144
	v_fmac_f32_e32 v1, v71, v145
	v_fmac_f32_e32 v2, v71, v146
	v_fmac_f32_e32 v3, v71, v147
	v_fmac_f32_e32 v4, v71, v148
	v_fmac_f32_e32 v5, v71, v149
	v_fmac_f32_e32 v6, v71, v150
	v_fmac_f32_e32 v7, v71, v151
	v_fmac_f32_e32 v8, v71, v152
	v_fmac_f32_e32 v9, v71, v153
	v_fmac_f32_e32 v10, v71, v154
	v_fmac_f32_e32 v11, v71, v155
	v_fmac_f32_e32 v12, v71, v156
	v_fmac_f32_e32 v13, v71, v157
	v_fmac_f32_e32 v14, v71, v158
	v_fmac_f32_e32 v15, v71, v159
	v_lshl_add_u32 v161, v23, 7, v160
	global_load_dwordx4 v[108:111], v161, s[14:15]
	s_waitcnt vmcnt(15)
	v_cvt_pk_f32_fp8_e32 v[144:145], v112
	v_cvt_pk_f32_fp8_sdwa v[146:147], v112 src0_sel:WORD_1
	v_cvt_pk_f32_fp8_e32 v[148:149], v113
	v_cvt_pk_f32_fp8_sdwa v[150:151], v113 src0_sel:WORD_1
	v_cvt_pk_f32_fp8_e32 v[152:153], v114
	v_cvt_pk_f32_fp8_sdwa v[154:155], v114 src0_sel:WORD_1
	v_cvt_pk_f32_fp8_e32 v[156:157], v115
	v_cvt_pk_f32_fp8_sdwa v[158:159], v115 src0_sel:WORD_1
	v_fmac_f32_e32 v0, v72, v144
	v_fmac_f32_e32 v1, v72, v145
	v_fmac_f32_e32 v2, v72, v146
	v_fmac_f32_e32 v3, v72, v147
	v_fmac_f32_e32 v4, v72, v148
	v_fmac_f32_e32 v5, v72, v149
	v_fmac_f32_e32 v6, v72, v150
	v_fmac_f32_e32 v7, v72, v151
	v_fmac_f32_e32 v8, v72, v152
	v_fmac_f32_e32 v9, v72, v153
	v_fmac_f32_e32 v10, v72, v154
	v_fmac_f32_e32 v11, v72, v155
	v_fmac_f32_e32 v12, v72, v156
	v_fmac_f32_e32 v13, v72, v157
	v_fmac_f32_e32 v14, v72, v158
	v_fmac_f32_e32 v15, v72, v159
	v_lshl_add_u32 v161, v24, 7, v160
	global_load_dwordx4 v[112:115], v161, s[14:15]
	s_waitcnt vmcnt(15)
	v_cvt_pk_f32_fp8_e32 v[144:145], v116
	v_cvt_pk_f32_fp8_sdwa v[146:147], v116 src0_sel:WORD_1
	v_cvt_pk_f32_fp8_e32 v[148:149], v117
	v_cvt_pk_f32_fp8_sdwa v[150:151], v117 src0_sel:WORD_1
	v_cvt_pk_f32_fp8_e32 v[152:153], v118
	v_cvt_pk_f32_fp8_sdwa v[154:155], v118 src0_sel:WORD_1
	v_cvt_pk_f32_fp8_e32 v[156:157], v119
	v_cvt_pk_f32_fp8_sdwa v[158:159], v119 src0_sel:WORD_1
	v_fmac_f32_e32 v0, v73, v144
	v_fmac_f32_e32 v1, v73, v145
	v_fmac_f32_e32 v2, v73, v146
	v_fmac_f32_e32 v3, v73, v147
	v_fmac_f32_e32 v4, v73, v148
	v_fmac_f32_e32 v5, v73, v149
	v_fmac_f32_e32 v6, v73, v150
	v_fmac_f32_e32 v7, v73, v151
	v_fmac_f32_e32 v8, v73, v152
	v_fmac_f32_e32 v9, v73, v153
	v_fmac_f32_e32 v10, v73, v154
	v_fmac_f32_e32 v11, v73, v155
	v_fmac_f32_e32 v12, v73, v156
	v_fmac_f32_e32 v13, v73, v157
	v_fmac_f32_e32 v14, v73, v158
	v_fmac_f32_e32 v15, v73, v159
	v_lshl_add_u32 v161, v25, 7, v160
	global_load_dwordx4 v[116:119], v161, s[14:15]
	s_waitcnt vmcnt(15)
	v_cvt_pk_f32_fp8_e32 v[144:145], v120
	v_cvt_pk_f32_fp8_sdwa v[146:147], v120 src0_sel:WORD_1
	v_cvt_pk_f32_fp8_e32 v[148:149], v121
	v_cvt_pk_f32_fp8_sdwa v[150:151], v121 src0_sel:WORD_1
	v_cvt_pk_f32_fp8_e32 v[152:153], v122
	v_cvt_pk_f32_fp8_sdwa v[154:155], v122 src0_sel:WORD_1
	v_cvt_pk_f32_fp8_e32 v[156:157], v123
	v_cvt_pk_f32_fp8_sdwa v[158:159], v123 src0_sel:WORD_1
	v_fmac_f32_e32 v0, v74, v144
	v_fmac_f32_e32 v1, v74, v145
	v_fmac_f32_e32 v2, v74, v146
	v_fmac_f32_e32 v3, v74, v147
	v_fmac_f32_e32 v4, v74, v148
	v_fmac_f32_e32 v5, v74, v149
	v_fmac_f32_e32 v6, v74, v150
	v_fmac_f32_e32 v7, v74, v151
	v_fmac_f32_e32 v8, v74, v152
	v_fmac_f32_e32 v9, v74, v153
	v_fmac_f32_e32 v10, v74, v154
	v_fmac_f32_e32 v11, v74, v155
	v_fmac_f32_e32 v12, v74, v156
	v_fmac_f32_e32 v13, v74, v157
	v_fmac_f32_e32 v14, v74, v158
	v_fmac_f32_e32 v15, v74, v159
	v_lshl_add_u32 v161, v26, 7, v160
	global_load_dwordx4 v[120:123], v161, s[14:15]
	s_waitcnt vmcnt(15)
	v_cvt_pk_f32_fp8_e32 v[144:145], v124
	v_cvt_pk_f32_fp8_sdwa v[146:147], v124 src0_sel:WORD_1
	v_cvt_pk_f32_fp8_e32 v[148:149], v125
	v_cvt_pk_f32_fp8_sdwa v[150:151], v125 src0_sel:WORD_1
	v_cvt_pk_f32_fp8_e32 v[152:153], v126
	v_cvt_pk_f32_fp8_sdwa v[154:155], v126 src0_sel:WORD_1
	v_cvt_pk_f32_fp8_e32 v[156:157], v127
	v_cvt_pk_f32_fp8_sdwa v[158:159], v127 src0_sel:WORD_1
	v_fmac_f32_e32 v0, v75, v144
	v_fmac_f32_e32 v1, v75, v145
	v_fmac_f32_e32 v2, v75, v146
	v_fmac_f32_e32 v3, v75, v147
	v_fmac_f32_e32 v4, v75, v148
	v_fmac_f32_e32 v5, v75, v149
	v_fmac_f32_e32 v6, v75, v150
	v_fmac_f32_e32 v7, v75, v151
	v_fmac_f32_e32 v8, v75, v152
	v_fmac_f32_e32 v9, v75, v153
	v_fmac_f32_e32 v10, v75, v154
	v_fmac_f32_e32 v11, v75, v155
	v_fmac_f32_e32 v12, v75, v156
	v_fmac_f32_e32 v13, v75, v157
	v_fmac_f32_e32 v14, v75, v158
	v_fmac_f32_e32 v15, v75, v159
	v_lshl_add_u32 v161, v27, 7, v160
	global_load_dwordx4 v[124:127], v161, s[14:15]
	s_waitcnt vmcnt(15)
	v_cvt_pk_f32_fp8_e32 v[144:145], v128
	v_cvt_pk_f32_fp8_sdwa v[146:147], v128 src0_sel:WORD_1
	v_cvt_pk_f32_fp8_e32 v[148:149], v129
	v_cvt_pk_f32_fp8_sdwa v[150:151], v129 src0_sel:WORD_1
	v_cvt_pk_f32_fp8_e32 v[152:153], v130
	v_cvt_pk_f32_fp8_sdwa v[154:155], v130 src0_sel:WORD_1
	v_cvt_pk_f32_fp8_e32 v[156:157], v131
	v_cvt_pk_f32_fp8_sdwa v[158:159], v131 src0_sel:WORD_1
	v_fmac_f32_e32 v0, v76, v144
	v_fmac_f32_e32 v1, v76, v145
	v_fmac_f32_e32 v2, v76, v146
	v_fmac_f32_e32 v3, v76, v147
	v_fmac_f32_e32 v4, v76, v148
	v_fmac_f32_e32 v5, v76, v149
	v_fmac_f32_e32 v6, v76, v150
	v_fmac_f32_e32 v7, v76, v151
	v_fmac_f32_e32 v8, v76, v152
	v_fmac_f32_e32 v9, v76, v153
	v_fmac_f32_e32 v10, v76, v154
	v_fmac_f32_e32 v11, v76, v155
	v_fmac_f32_e32 v12, v76, v156
	v_fmac_f32_e32 v13, v76, v157
	v_fmac_f32_e32 v14, v76, v158
	v_fmac_f32_e32 v15, v76, v159
	v_lshl_add_u32 v161, v28, 7, v160
	global_load_dwordx4 v[128:131], v161, s[14:15]
	s_waitcnt vmcnt(15)
; DI void phase_peer_b(const Params& p, int layer, const float* gnext, bool last) {
;     ...
;     for (int bt = 0; bt < 8; ++bt) {
;       u32x4 vr[16];
; #pragma unroll
;       for (int j = 0; j < 16; ++j) {
;         const int e = bt * 16 + j;
;         const int eidx = __builtin_amdgcn_readlane(e < 64 ? i0 : i1, e & 63);
;         vr[j] = *(const u32x4*)(EV + (size_t)eidx * DM + lane * 16);
;       }
; #pragma unroll
;       for (int j = 0; j < 16; ++j) {
;         const int e = bt * 16 + j;
;         const float wj = __int_as_float(__builtin_amdgcn_readlane(__float_as_int(e < 64 ? w0 : w1), e & 63));
; #pragma unroll
;         for (int w = 0; w < 4; ++w) {
;           const f32x2 lo = __builtin_amdgcn_cvt_pk_f32_fp8((int)vr[j][w], false);
;           const f32x2 hi = __builtin_amdgcn_cvt_pk_f32_fp8((int)vr[j][w], true);
;           acc[4 * w] += wj * lo[0]; acc[4 * w + 1] += wj * lo[1]; acc[4 * w + 2] += wj * hi[0]; acc[4 * w + 3] += wj * hi[1];
;         }
;       }
	v_cvt_pk_f32_fp8_e32 v[144:145], v132
	v_cvt_pk_f32_fp8_sdwa v[146:147], v132 src0_sel:WORD_1
	v_cvt_pk_f32_fp8_e32 v[148:149], v133
	v_cvt_pk_f32_fp8_sdwa v[150:151], v133 src0_sel:WORD_1
	v_cvt_pk_f32_fp8_e32 v[152:153], v134
	v_cvt_pk_f32_fp8_sdwa v[154:155], v134 src0_sel:WORD_1
	v_cvt_pk_f32_fp8_e32 v[156:157], v135
	v_cvt_pk_f32_fp8_sdwa v[158:159], v135 src0_sel:WORD_1
	v_fmac_f32_e32 v0, v77, v144
	v_fmac_f32_e32 v1, v77, v145
	v_fmac_f32_e32 v2, v77, v146
	v_fmac_f32_e32 v3, v77, v147
	v_fmac_f32_e32 v4, v77, v148
	v_fmac_f32_e32 v5, v77, v149
	v_fmac_f32_e32 v6, v77, v150
	v_fmac_f32_e32 v7, v77, v151
	v_fmac_f32_e32 v8, v77, v152
	v_fmac_f32_e32 v9, v77, v153
	v_fmac_f32_e32 v10, v77, v154
	v_fmac_f32_e32 v11, v77, v155
	v_fmac_f32_e32 v12, v77, v156
	v_fmac_f32_e32 v13, v77, v157
	v_fmac_f32_e32 v14, v77, v158
	v_fmac_f32_e32 v15, v77, v159
	v_lshl_add_u32 v161, v29, 7, v160
	global_load_dwordx4 v[132:135], v161, s[14:15]
	s_waitcnt vmcnt(15)
	v_cvt_pk_f32_fp8_e32 v[144:145], v136
	v_cvt_pk_f32_fp8_sdwa v[146:147], v136 src0_sel:WORD_1
	v_cvt_pk_f32_fp8_e32 v[148:149], v137
	v_cvt_pk_f32_fp8_sdwa v[150:151], v137 src0_sel:WORD_1
	v_cvt_pk_f32_fp8_e32 v[152:153], v138
	v_cvt_pk_f32_fp8_sdwa v[154:155], v138 src0_sel:WORD_1
	v_cvt_pk_f32_fp8_e32 v[156:157], v139
	v_cvt_pk_f32_fp8_sdwa v[158:159], v139 src0_sel:WORD_1
	v_fmac_f32_e32 v0, v78, v144
	v_fmac_f32_e32 v1, v78, v145
	v_fmac_f32_e32 v2, v78, v146
	v_fmac_f32_e32 v3, v78, v147
	v_fmac_f32_e32 v4, v78, v148
	v_fmac_f32_e32 v5, v78, v149
	v_fmac_f32_e32 v6, v78, v150
	v_fmac_f32_e32 v7, v78, v151
	v_fmac_f32_e32 v8, v78, v152
	v_fmac_f32_e32 v9, v78, v153
	v_fmac_f32_e32 v10, v78, v154
	v_fmac_f32_e32 v11, v78, v155
	v_fmac_f32_e32 v12, v78, v156
	v_fmac_f32_e32 v13, v78, v157
	v_fmac_f32_e32 v14, v78, v158
	v_fmac_f32_e32 v15, v78, v159
	v_lshl_add_u32 v161, v30, 7, v160
	global_load_dwordx4 v[136:139], v161, s[14:15]
	s_waitcnt vmcnt(15)
	v_cvt_pk_f32_fp8_e32 v[144:145], v140
	v_cvt_pk_f32_fp8_sdwa v[146:147], v140 src0_sel:WORD_1
	v_cvt_pk_f32_fp8_e32 v[148:149], v141
	v_cvt_pk_f32_fp8_sdwa v[150:151], v141 src0_sel:WORD_1
	v_cvt_pk_f32_fp8_e32 v[152:153], v142
	v_cvt_pk_f32_fp8_sdwa v[154:155], v142 src0_sel:WORD_1
	v_cvt_pk_f32_fp8_e32 v[156:157], v143
	v_cvt_pk_f32_fp8_sdwa v[158:159], v143 src0_sel:WORD_1
	v_fmac_f32_e32 v0, v79, v144
	v_fmac_f32_e32 v1, v79, v145
	v_fmac_f32_e32 v2, v79, v146
	v_fmac_f32_e32 v3, v79, v147
	v_fmac_f32_e32 v4, v79, v148
	v_fmac_f32_e32 v5, v79, v149
	v_fmac_f32_e32 v6, v79, v150
	v_fmac_f32_e32 v7, v79, v151
	v_fmac_f32_e32 v8, v79, v152
	v_fmac_f32_e32 v9, v79, v153
	v_fmac_f32_e32 v10, v79, v154
	v_fmac_f32_e32 v11, v79, v155
	v_fmac_f32_e32 v12, v79, v156
	v_fmac_f32_e32 v13, v79, v157
	v_fmac_f32_e32 v14, v79, v158
	v_fmac_f32_e32 v15, v79, v159
	v_lshl_add_u32 v161, v31, 7, v160
	global_load_dwordx4 v[140:143], v161, s[14:15]
	s_waitcnt lgkmcnt(0)
	ds_read_b128 v[16:19], v163 offset:256
	ds_read_b128 v[20:23], v163 offset:272
	ds_read_b128 v[24:27], v163 offset:288
	ds_read_b128 v[28:31], v163 offset:304
	ds_read_b128 v[64:67], v163 offset:704
	ds_read_b128 v[68:71], v163 offset:720
	ds_read_b128 v[72:75], v163 offset:736
	ds_read_b128 v[76:79], v163 offset:752
	s_waitcnt vmcnt(15)
	v_cvt_pk_f32_fp8_e32 v[144:145], v80
	v_cvt_pk_f32_fp8_sdwa v[146:147], v80 src0_sel:WORD_1
	v_cvt_pk_f32_fp8_e32 v[148:149], v81
	v_cvt_pk_f32_fp8_sdwa v[150:151], v81 src0_sel:WORD_1
	v_cvt_pk_f32_fp8_e32 v[152:153], v82
	v_cvt_pk_f32_fp8_sdwa v[154:155], v82 src0_sel:WORD_1
	v_cvt_pk_f32_fp8_e32 v[156:157], v83
	v_cvt_pk_f32_fp8_sdwa v[158:159], v83 src0_sel:WORD_1
	v_fmac_f32_e32 v0, v48, v144
	v_fmac_f32_e32 v1, v48, v145
	v_fmac_f32_e32 v2, v48, v146
	v_fmac_f32_e32 v3, v48, v147
	v_fmac_f32_e32 v4, v48, v148
	v_fmac_f32_e32 v5, v48, v149
	v_fmac_f32_e32 v6, v48, v150
	v_fmac_f32_e32 v7, v48, v151
	v_fmac_f32_e32 v8, v48, v152
	v_fmac_f32_e32 v9, v48, v153
	v_fmac_f32_e32 v10, v48, v154
	v_fmac_f32_e32 v11, v48, v155
	v_fmac_f32_e32 v12, v48, v156
	v_fmac_f32_e32 v13, v48, v157
	v_fmac_f32_e32 v14, v48, v158
	v_fmac_f32_e32 v15, v48, v159
	v_lshl_add_u32 v161, v32, 7, v160
	global_load_dwordx4 v[80:83], v161, s[14:15]
	s_waitcnt vmcnt(15)
	v_cvt_pk_f32_fp8_e32 v[144:145], v84
	v_cvt_pk_f32_fp8_sdwa v[146:147], v84 src0_sel:WORD_1
	v_cvt_pk_f32_fp8_e32 v[148:149], v85
	v_cvt_pk_f32_fp8_sdwa v[150:151], v85 src0_sel:WORD_1
	v_cvt_pk_f32_fp8_e32 v[152:153], v86
	v_cvt_pk_f32_fp8_sdwa v[154:155], v86 src0_sel:WORD_1
	v_cvt_pk_f32_fp8_e32 v[156:157], v87
	v_cvt_pk_f32_fp8_sdwa v[158:159], v87 src0_sel:WORD_1
	v_fmac_f32_e32 v0, v49, v144
	v_fmac_f32_e32 v1, v49, v145
	v_fmac_f32_e32 v2, v49, v146
	v_fmac_f32_e32 v3, v49, v147
	v_fmac_f32_e32 v4, v49, v148
	v_fmac_f32_e32 v5, v49, v149
	v_fmac_f32_e32 v6, v49, v150
	v_fmac_f32_e32 v7, v49, v151
	v_fmac_f32_e32 v8, v49, v152
	v_fmac_f32_e32 v9, v49, v153
	v_fmac_f32_e32 v10, v49, v154
	v_fmac_f32_e32 v11, v49, v155
	v_fmac_f32_e32 v12, v49, v156
	v_fmac_f32_e32 v13, v49, v157
	v_fmac_f32_e32 v14, v49, v158
	v_fmac_f32_e32 v15, v49, v159
	v_lshl_add_u32 v161, v33, 7, v160
	global_load_dwordx4 v[84:87], v161, s[14:15]
	s_waitcnt vmcnt(15)
; DI void phase_peer_b(const Params& p, int layer, const float* gnext, bool last) {
;     ...
;     for (int bt = 0; bt < 8; ++bt) {
;       u32x4 vr[16];
; #pragma unroll
;       for (int j = 0; j < 16; ++j) {
;         const int e = bt * 16 + j;
;         const int eidx = __builtin_amdgcn_readlane(e < 64 ? i0 : i1, e & 63);
;         vr[j] = *(const u32x4*)(EV + (size_t)eidx * DM + lane * 16);
;       }
; #pragma unroll
;       for (int j = 0; j < 16; ++j) {
;         const int e = bt * 16 + j;
;         const float wj = __int_as_float(__builtin_amdgcn_readlane(__float_as_int(e < 64 ? w0 : w1), e & 63));
; #pragma unroll
;         for (int w = 0; w < 4; ++w) {
;           const f32x2 lo = __builtin_amdgcn_cvt_pk_f32_fp8((int)vr[j][w], false);
;           const f32x2 hi = __builtin_amdgcn_cvt_pk_f32_fp8((int)vr[j][w], true);
;           acc[4 * w] += wj * lo[0]; acc[4 * w + 1] += wj * lo[1]; acc[4 * w + 2] += wj * hi[0]; acc[4 * w + 3] += wj * hi[1];
;         }
;       }
	v_cvt_pk_f32_fp8_e32 v[144:145], v88
	v_cvt_pk_f32_fp8_sdwa v[146:147], v88 src0_sel:WORD_1
	v_cvt_pk_f32_fp8_e32 v[148:149], v89
	v_cvt_pk_f32_fp8_sdwa v[150:151], v89 src0_sel:WORD_1
	v_cvt_pk_f32_fp8_e32 v[152:153], v90
	v_cvt_pk_f32_fp8_sdwa v[154:155], v90 src0_sel:WORD_1
	v_cvt_pk_f32_fp8_e32 v[156:157], v91
	v_cvt_pk_f32_fp8_sdwa v[158:159], v91 src0_sel:WORD_1
	v_fmac_f32_e32 v0, v50, v144
	v_fmac_f32_e32 v1, v50, v145
	v_fmac_f32_e32 v2, v50, v146
	v_fmac_f32_e32 v3, v50, v147
	v_fmac_f32_e32 v4, v50, v148
	v_fmac_f32_e32 v5, v50, v149
	v_fmac_f32_e32 v6, v50, v150
	v_fmac_f32_e32 v7, v50, v151
	v_fmac_f32_e32 v8, v50, v152
	v_fmac_f32_e32 v9, v50, v153
	v_fmac_f32_e32 v10, v50, v154
	v_fmac_f32_e32 v11, v50, v155
	v_fmac_f32_e32 v12, v50, v156
	v_fmac_f32_e32 v13, v50, v157
	v_fmac_f32_e32 v14, v50, v158
	v_fmac_f32_e32 v15, v50, v159
	v_lshl_add_u32 v161, v34, 7, v160
	global_load_dwordx4 v[88:91], v161, s[14:15]
	s_waitcnt vmcnt(15)
	v_cvt_pk_f32_fp8_e32 v[144:145], v92
	v_cvt_pk_f32_fp8_sdwa v[146:147], v92 src0_sel:WORD_1
	v_cvt_pk_f32_fp8_e32 v[148:149], v93
	v_cvt_pk_f32_fp8_sdwa v[150:151], v93 src0_sel:WORD_1
	v_cvt_pk_f32_fp8_e32 v[152:153], v94
	v_cvt_pk_f32_fp8_sdwa v[154:155], v94 src0_sel:WORD_1
	v_cvt_pk_f32_fp8_e32 v[156:157], v95
	v_cvt_pk_f32_fp8_sdwa v[158:159], v95 src0_sel:WORD_1
	v_fmac_f32_e32 v0, v51, v144
	v_fmac_f32_e32 v1, v51, v145
	v_fmac_f32_e32 v2, v51, v146
	v_fmac_f32_e32 v3, v51, v147
	v_fmac_f32_e32 v4, v51, v148
	v_fmac_f32_e32 v5, v51, v149
	v_fmac_f32_e32 v6, v51, v150
	v_fmac_f32_e32 v7, v51, v151
	v_fmac_f32_e32 v8, v51, v152
	v_fmac_f32_e32 v9, v51, v153
	v_fmac_f32_e32 v10, v51, v154
	v_fmac_f32_e32 v11, v51, v155
	v_fmac_f32_e32 v12, v51, v156
	v_fmac_f32_e32 v13, v51, v157
	v_fmac_f32_e32 v14, v51, v158
	v_fmac_f32_e32 v15, v51, v159
	v_lshl_add_u32 v161, v35, 7, v160
	global_load_dwordx4 v[92:95], v161, s[14:15]
	s_waitcnt vmcnt(15)
	v_cvt_pk_f32_fp8_e32 v[144:145], v96
	v_cvt_pk_f32_fp8_sdwa v[146:147], v96 src0_sel:WORD_1
	v_cvt_pk_f32_fp8_e32 v[148:149], v97
	v_cvt_pk_f32_fp8_sdwa v[150:151], v97 src0_sel:WORD_1
	v_cvt_pk_f32_fp8_e32 v[152:153], v98
	v_cvt_pk_f32_fp8_sdwa v[154:155], v98 src0_sel:WORD_1
	v_cvt_pk_f32_fp8_e32 v[156:157], v99
	v_cvt_pk_f32_fp8_sdwa v[158:159], v99 src0_sel:WORD_1
	v_fmac_f32_e32 v0, v52, v144
	v_fmac_f32_e32 v1, v52, v145
	v_fmac_f32_e32 v2, v52, v146
	v_fmac_f32_e32 v3, v52, v147
	v_fmac_f32_e32 v4, v52, v148
	v_fmac_f32_e32 v5, v52, v149
	v_fmac_f32_e32 v6, v52, v150
	v_fmac_f32_e32 v7, v52, v151
	v_fmac_f32_e32 v8, v52, v152
	v_fmac_f32_e32 v9, v52, v153
	v_fmac_f32_e32 v10, v52, v154
	v_fmac_f32_e32 v11, v52, v155
	v_fmac_f32_e32 v12, v52, v156
	v_fmac_f32_e32 v13, v52, v157
	v_fmac_f32_e32 v14, v52, v158
	v_fmac_f32_e32 v15, v52, v159
	v_lshl_add_u32 v161, v36, 7, v160
	global_load_dwordx4 v[96:99], v161, s[14:15]
	s_waitcnt vmcnt(15)
	v_cvt_pk_f32_fp8_e32 v[144:145], v100
	v_cvt_pk_f32_fp8_sdwa v[146:147], v100 src0_sel:WORD_1
	v_cvt_pk_f32_fp8_e32 v[148:149], v101
	v_cvt_pk_f32_fp8_sdwa v[150:151], v101 src0_sel:WORD_1
	v_cvt_pk_f32_fp8_e32 v[152:153], v102
	v_cvt_pk_f32_fp8_sdwa v[154:155], v102 src0_sel:WORD_1
	v_cvt_pk_f32_fp8_e32 v[156:157], v103
	v_cvt_pk_f32_fp8_sdwa v[158:159], v103 src0_sel:WORD_1
	v_fmac_f32_e32 v0, v53, v144
	v_fmac_f32_e32 v1, v53, v145
	v_fmac_f32_e32 v2, v53, v146
	v_fmac_f32_e32 v3, v53, v147
	v_fmac_f32_e32 v4, v53, v148
	v_fmac_f32_e32 v5, v53, v149
	v_fmac_f32_e32 v6, v53, v150
	v_fmac_f32_e32 v7, v53, v151
	v_fmac_f32_e32 v8, v53, v152
	v_fmac_f32_e32 v9, v53, v153
	v_fmac_f32_e32 v10, v53, v154
	v_fmac_f32_e32 v11, v53, v155
	v_fmac_f32_e32 v12, v53, v156
	v_fmac_f32_e32 v13, v53, v157
	v_fmac_f32_e32 v14, v53, v158
	v_fmac_f32_e32 v15, v53, v159
	v_lshl_add_u32 v161, v37, 7, v160
	global_load_dwordx4 v[100:103], v161, s[14:15]
	s_waitcnt vmcnt(15)
	v_cvt_pk_f32_fp8_e32 v[144:145], v104
	v_cvt_pk_f32_fp8_sdwa v[146:147], v104 src0_sel:WORD_1
	v_cvt_pk_f32_fp8_e32 v[148:149], v105
	v_cvt_pk_f32_fp8_sdwa v[150:151], v105 src0_sel:WORD_1
	v_cvt_pk_f32_fp8_e32 v[152:153], v106
	v_cvt_pk_f32_fp8_sdwa v[154:155], v106 src0_sel:WORD_1
	v_cvt_pk_f32_fp8_e32 v[156:157], v107
	v_cvt_pk_f32_fp8_sdwa v[158:159], v107 src0_sel:WORD_1
	v_fmac_f32_e32 v0, v54, v144
	v_fmac_f32_e32 v1, v54, v145
	v_fmac_f32_e32 v2, v54, v146
	v_fmac_f32_e32 v3, v54, v147
	v_fmac_f32_e32 v4, v54, v148
	v_fmac_f32_e32 v5, v54, v149
	v_fmac_f32_e32 v6, v54, v150
	v_fmac_f32_e32 v7, v54, v151
	v_fmac_f32_e32 v8, v54, v152
	v_fmac_f32_e32 v9, v54, v153
	v_fmac_f32_e32 v10, v54, v154
	v_fmac_f32_e32 v11, v54, v155
	v_fmac_f32_e32 v12, v54, v156
	v_fmac_f32_e32 v13, v54, v157
	v_fmac_f32_e32 v14, v54, v158
	v_fmac_f32_e32 v15, v54, v159
	v_lshl_add_u32 v161, v38, 7, v160
	global_load_dwordx4 v[104:107], v161, s[14:15]
	s_waitcnt vmcnt(15)
	v_cvt_pk_f32_fp8_e32 v[144:145], v108
	v_cvt_pk_f32_fp8_sdwa v[146:147], v108 src0_sel:WORD_1
	v_cvt_pk_f32_fp8_e32 v[148:149], v109
	v_cvt_pk_f32_fp8_sdwa v[150:151], v109 src0_sel:WORD_1
	v_cvt_pk_f32_fp8_e32 v[152:153], v110
	v_cvt_pk_f32_fp8_sdwa v[154:155], v110 src0_sel:WORD_1
	v_cvt_pk_f32_fp8_e32 v[156:157], v111
	v_cvt_pk_f32_fp8_sdwa v[158:159], v111 src0_sel:WORD_1
	v_fmac_f32_e32 v0, v55, v144
	v_fmac_f32_e32 v1, v55, v145
	v_fmac_f32_e32 v2, v55, v146
	v_fmac_f32_e32 v3, v55, v147
	v_fmac_f32_e32 v4, v55, v148
	v_fmac_f32_e32 v5, v55, v149
	v_fmac_f32_e32 v6, v55, v150
	v_fmac_f32_e32 v7, v55, v151
	v_fmac_f32_e32 v8, v55, v152
	v_fmac_f32_e32 v9, v55, v153
	v_fmac_f32_e32 v10, v55, v154
	v_fmac_f32_e32 v11, v55, v155
	v_fmac_f32_e32 v12, v55, v156
	v_fmac_f32_e32 v13, v55, v157
	v_fmac_f32_e32 v14, v55, v158
	v_fmac_f32_e32 v15, v55, v159
	v_lshl_add_u32 v161, v39, 7, v160
	global_load_dwordx4 v[108:111], v161, s[14:15]
	s_waitcnt vmcnt(15)
; DI void phase_peer_b(const Params& p, int layer, const float* gnext, bool last) {
;     ...
;     for (int bt = 0; bt < 8; ++bt) {
;       u32x4 vr[16];
; #pragma unroll
;       for (int j = 0; j < 16; ++j) {
;         const int e = bt * 16 + j;
;         const int eidx = __builtin_amdgcn_readlane(e < 64 ? i0 : i1, e & 63);
;         vr[j] = *(const u32x4*)(EV + (size_t)eidx * DM + lane * 16);
;       }
; #pragma unroll
;       for (int j = 0; j < 16; ++j) {
;         const int e = bt * 16 + j;
;         const float wj = __int_as_float(__builtin_amdgcn_readlane(__float_as_int(e < 64 ? w0 : w1), e & 63));
; #pragma unroll
;         for (int w = 0; w < 4; ++w) {
;           const f32x2 lo = __builtin_amdgcn_cvt_pk_f32_fp8((int)vr[j][w], false);
;           const f32x2 hi = __builtin_amdgcn_cvt_pk_f32_fp8((int)vr[j][w], true);
;           acc[4 * w] += wj * lo[0]; acc[4 * w + 1] += wj * lo[1]; acc[4 * w + 2] += wj * hi[0]; acc[4 * w + 3] += wj * hi[1];
;         }
;       }
	v_cvt_pk_f32_fp8_e32 v[144:145], v112
	v_cvt_pk_f32_fp8_sdwa v[146:147], v112 src0_sel:WORD_1
	v_cvt_pk_f32_fp8_e32 v[148:149], v113
	v_cvt_pk_f32_fp8_sdwa v[150:151], v113 src0_sel:WORD_1
	v_cvt_pk_f32_fp8_e32 v[152:153], v114
	v_cvt_pk_f32_fp8_sdwa v[154:155], v114 src0_sel:WORD_1
	v_cvt_pk_f32_fp8_e32 v[156:157], v115
	v_cvt_pk_f32_fp8_sdwa v[158:159], v115 src0_sel:WORD_1
	v_fmac_f32_e32 v0, v56, v144
	v_fmac_f32_e32 v1, v56, v145
	v_fmac_f32_e32 v2, v56, v146
	v_fmac_f32_e32 v3, v56, v147
	v_fmac_f32_e32 v4, v56, v148
	v_fmac_f32_e32 v5, v56, v149
	v_fmac_f32_e32 v6, v56, v150
	v_fmac_f32_e32 v7, v56, v151
	v_fmac_f32_e32 v8, v56, v152
	v_fmac_f32_e32 v9, v56, v153
	v_fmac_f32_e32 v10, v56, v154
	v_fmac_f32_e32 v11, v56, v155
	v_fmac_f32_e32 v12, v56, v156
	v_fmac_f32_e32 v13, v56, v157
	v_fmac_f32_e32 v14, v56, v158
	v_fmac_f32_e32 v15, v56, v159
	v_lshl_add_u32 v161, v40, 7, v160
	global_load_dwordx4 v[112:115], v161, s[14:15]
	s_waitcnt vmcnt(15)
	v_cvt_pk_f32_fp8_e32 v[144:145], v116
	v_cvt_pk_f32_fp8_sdwa v[146:147], v116 src0_sel:WORD_1
	v_cvt_pk_f32_fp8_e32 v[148:149], v117
	v_cvt_pk_f32_fp8_sdwa v[150:151], v117 src0_sel:WORD_1
	v_cvt_pk_f32_fp8_e32 v[152:153], v118
	v_cvt_pk_f32_fp8_sdwa v[154:155], v118 src0_sel:WORD_1
	v_cvt_pk_f32_fp8_e32 v[156:157], v119
	v_cvt_pk_f32_fp8_sdwa v[158:159], v119 src0_sel:WORD_1
	v_fmac_f32_e32 v0, v57, v144
	v_fmac_f32_e32 v1, v57, v145
	v_fmac_f32_e32 v2, v57, v146
	v_fmac_f32_e32 v3, v57, v147
	v_fmac_f32_e32 v4, v57, v148
	v_fmac_f32_e32 v5, v57, v149
	v_fmac_f32_e32 v6, v57, v150
	v_fmac_f32_e32 v7, v57, v151
	v_fmac_f32_e32 v8, v57, v152
	v_fmac_f32_e32 v9, v57, v153
	v_fmac_f32_e32 v10, v57, v154
	v_fmac_f32_e32 v11, v57, v155
	v_fmac_f32_e32 v12, v57, v156
	v_fmac_f32_e32 v13, v57, v157
	v_fmac_f32_e32 v14, v57, v158
	v_fmac_f32_e32 v15, v57, v159
	v_lshl_add_u32 v161, v41, 7, v160
	global_load_dwordx4 v[116:119], v161, s[14:15]
	s_waitcnt vmcnt(15)
	v_cvt_pk_f32_fp8_e32 v[144:145], v120
	v_cvt_pk_f32_fp8_sdwa v[146:147], v120 src0_sel:WORD_1
	v_cvt_pk_f32_fp8_e32 v[148:149], v121
	v_cvt_pk_f32_fp8_sdwa v[150:151], v121 src0_sel:WORD_1
	v_cvt_pk_f32_fp8_e32 v[152:153], v122
	v_cvt_pk_f32_fp8_sdwa v[154:155], v122 src0_sel:WORD_1
	v_cvt_pk_f32_fp8_e32 v[156:157], v123
	v_cvt_pk_f32_fp8_sdwa v[158:159], v123 src0_sel:WORD_1
	v_fmac_f32_e32 v0, v58, v144
	v_fmac_f32_e32 v1, v58, v145
	v_fmac_f32_e32 v2, v58, v146
	v_fmac_f32_e32 v3, v58, v147
	v_fmac_f32_e32 v4, v58, v148
	v_fmac_f32_e32 v5, v58, v149
	v_fmac_f32_e32 v6, v58, v150
	v_fmac_f32_e32 v7, v58, v151
	v_fmac_f32_e32 v8, v58, v152
	v_fmac_f32_e32 v9, v58, v153
	v_fmac_f32_e32 v10, v58, v154
	v_fmac_f32_e32 v11, v58, v155
	v_fmac_f32_e32 v12, v58, v156
	v_fmac_f32_e32 v13, v58, v157
	v_fmac_f32_e32 v14, v58, v158
	v_fmac_f32_e32 v15, v58, v159
	v_lshl_add_u32 v161, v42, 7, v160
	global_load_dwordx4 v[120:123], v161, s[14:15]
	s_waitcnt vmcnt(15)
	v_cvt_pk_f32_fp8_e32 v[144:145], v124
	v_cvt_pk_f32_fp8_sdwa v[146:147], v124 src0_sel:WORD_1
	v_cvt_pk_f32_fp8_e32 v[148:149], v125
	v_cvt_pk_f32_fp8_sdwa v[150:151], v125 src0_sel:WORD_1
	v_cvt_pk_f32_fp8_e32 v[152:153], v126
	v_cvt_pk_f32_fp8_sdwa v[154:155], v126 src0_sel:WORD_1
	v_cvt_pk_f32_fp8_e32 v[156:157], v127
	v_cvt_pk_f32_fp8_sdwa v[158:159], v127 src0_sel:WORD_1
	v_fmac_f32_e32 v0, v59, v144
	v_fmac_f32_e32 v1, v59, v145
	v_fmac_f32_e32 v2, v59, v146
	v_fmac_f32_e32 v3, v59, v147
	v_fmac_f32_e32 v4, v59, v148
	v_fmac_f32_e32 v5, v59, v149
	v_fmac_f32_e32 v6, v59, v150
	v_fmac_f32_e32 v7, v59, v151
	v_fmac_f32_e32 v8, v59, v152
	v_fmac_f32_e32 v9, v59, v153
	v_fmac_f32_e32 v10, v59, v154
	v_fmac_f32_e32 v11, v59, v155
	v_fmac_f32_e32 v12, v59, v156
	v_fmac_f32_e32 v13, v59, v157
	v_fmac_f32_e32 v14, v59, v158
	v_fmac_f32_e32 v15, v59, v159
	v_lshl_add_u32 v161, v43, 7, v160
	global_load_dwordx4 v[124:127], v161, s[14:15]
	s_waitcnt vmcnt(15)
	v_cvt_pk_f32_fp8_e32 v[144:145], v128
	v_cvt_pk_f32_fp8_sdwa v[146:147], v128 src0_sel:WORD_1
	v_cvt_pk_f32_fp8_e32 v[148:149], v129
	v_cvt_pk_f32_fp8_sdwa v[150:151], v129 src0_sel:WORD_1
	v_cvt_pk_f32_fp8_e32 v[152:153], v130
	v_cvt_pk_f32_fp8_sdwa v[154:155], v130 src0_sel:WORD_1
	v_cvt_pk_f32_fp8_e32 v[156:157], v131
	v_cvt_pk_f32_fp8_sdwa v[158:159], v131 src0_sel:WORD_1
	v_fmac_f32_e32 v0, v60, v144
	v_fmac_f32_e32 v1, v60, v145
	v_fmac_f32_e32 v2, v60, v146
	v_fmac_f32_e32 v3, v60, v147
	v_fmac_f32_e32 v4, v60, v148
	v_fmac_f32_e32 v5, v60, v149
	v_fmac_f32_e32 v6, v60, v150
	v_fmac_f32_e32 v7, v60, v151
	v_fmac_f32_e32 v8, v60, v152
	v_fmac_f32_e32 v9, v60, v153
	v_fmac_f32_e32 v10, v60, v154
	v_fmac_f32_e32 v11, v60, v155
	v_fmac_f32_e32 v12, v60, v156
	v_fmac_f32_e32 v13, v60, v157
	v_fmac_f32_e32 v14, v60, v158
	v_fmac_f32_e32 v15, v60, v159
	v_lshl_add_u32 v161, v44, 7, v160
	global_load_dwordx4 v[128:131], v161, s[14:15]
	s_waitcnt vmcnt(15)
	v_cvt_pk_f32_fp8_e32 v[144:145], v132
	v_cvt_pk_f32_fp8_sdwa v[146:147], v132 src0_sel:WORD_1
	v_cvt_pk_f32_fp8_e32 v[148:149], v133
	v_cvt_pk_f32_fp8_sdwa v[150:151], v133 src0_sel:WORD_1
	v_cvt_pk_f32_fp8_e32 v[152:153], v134
	v_cvt_pk_f32_fp8_sdwa v[154:155], v134 src0_sel:WORD_1
	v_cvt_pk_f32_fp8_e32 v[156:157], v135
	v_cvt_pk_f32_fp8_sdwa v[158:159], v135 src0_sel:WORD_1
	v_fmac_f32_e32 v0, v61, v144
	v_fmac_f32_e32 v1, v61, v145
	v_fmac_f32_e32 v2, v61, v146
	v_fmac_f32_e32 v3, v61, v147
	v_fmac_f32_e32 v4, v61, v148
	v_fmac_f32_e32 v5, v61, v149
	v_fmac_f32_e32 v6, v61, v150
	v_fmac_f32_e32 v7, v61, v151
	v_fmac_f32_e32 v8, v61, v152
	v_fmac_f32_e32 v9, v61, v153
	v_fmac_f32_e32 v10, v61, v154
	v_fmac_f32_e32 v11, v61, v155
	v_fmac_f32_e32 v12, v61, v156
	v_fmac_f32_e32 v13, v61, v157
	v_fmac_f32_e32 v14, v61, v158
	v_fmac_f32_e32 v15, v61, v159
	v_lshl_add_u32 v161, v45, 7, v160
	global_load_dwordx4 v[132:135], v161, s[14:15]
	s_waitcnt vmcnt(15)
; DI void phase_peer_b(const Params& p, int layer, const float* gnext, bool last) {
;     ...
;     for (int bt = 0; bt < 8; ++bt) {
;       u32x4 vr[16];
; #pragma unroll
;       for (int j = 0; j < 16; ++j) {
;         const int e = bt * 16 + j;
;         const int eidx = __builtin_amdgcn_readlane(e < 64 ? i0 : i1, e & 63);
;         vr[j] = *(const u32x4*)(EV + (size_t)eidx * DM + lane * 16);
;       }
; #pragma unroll
;       for (int j = 0; j < 16; ++j) {
;         const int e = bt * 16 + j;
;         const float wj = __int_as_float(__builtin_amdgcn_readlane(__float_as_int(e < 64 ? w0 : w1), e & 63));
; #pragma unroll
;         for (int w = 0; w < 4; ++w) {
;           const f32x2 lo = __builtin_amdgcn_cvt_pk_f32_fp8((int)vr[j][w], false);
;           const f32x2 hi = __builtin_amdgcn_cvt_pk_f32_fp8((int)vr[j][w], true);
;           acc[4 * w] += wj * lo[0]; acc[4 * w + 1] += wj * lo[1]; acc[4 * w + 2] += wj * hi[0]; acc[4 * w + 3] += wj * hi[1];
;         }
;       }
	v_cvt_pk_f32_fp8_e32 v[144:145], v136
	v_cvt_pk_f32_fp8_sdwa v[146:147], v136 src0_sel:WORD_1
	v_cvt_pk_f32_fp8_e32 v[148:149], v137
	v_cvt_pk_f32_fp8_sdwa v[150:151], v137 src0_sel:WORD_1
	v_cvt_pk_f32_fp8_e32 v[152:153], v138
	v_cvt_pk_f32_fp8_sdwa v[154:155], v138 src0_sel:WORD_1
	v_cvt_pk_f32_fp8_e32 v[156:157], v139
	v_cvt_pk_f32_fp8_sdwa v[158:159], v139 src0_sel:WORD_1
	v_fmac_f32_e32 v0, v62, v144
	v_fmac_f32_e32 v1, v62, v145
	v_fmac_f32_e32 v2, v62, v146
	v_fmac_f32_e32 v3, v62, v147
	v_fmac_f32_e32 v4, v62, v148
	v_fmac_f32_e32 v5, v62, v149
	v_fmac_f32_e32 v6, v62, v150
	v_fmac_f32_e32 v7, v62, v151
	v_fmac_f32_e32 v8, v62, v152
	v_fmac_f32_e32 v9, v62, v153
	v_fmac_f32_e32 v10, v62, v154
	v_fmac_f32_e32 v11, v62, v155
	v_fmac_f32_e32 v12, v62, v156
	v_fmac_f32_e32 v13, v62, v157
	v_fmac_f32_e32 v14, v62, v158
	v_fmac_f32_e32 v15, v62, v159
	v_lshl_add_u32 v161, v46, 7, v160
	global_load_dwordx4 v[136:139], v161, s[14:15]
	s_waitcnt vmcnt(15)
	v_cvt_pk_f32_fp8_e32 v[144:145], v140
	v_cvt_pk_f32_fp8_sdwa v[146:147], v140 src0_sel:WORD_1
	v_cvt_pk_f32_fp8_e32 v[148:149], v141
	v_cvt_pk_f32_fp8_sdwa v[150:151], v141 src0_sel:WORD_1
	v_cvt_pk_f32_fp8_e32 v[152:153], v142
	v_cvt_pk_f32_fp8_sdwa v[154:155], v142 src0_sel:WORD_1
	v_cvt_pk_f32_fp8_e32 v[156:157], v143
	v_cvt_pk_f32_fp8_sdwa v[158:159], v143 src0_sel:WORD_1
	v_fmac_f32_e32 v0, v63, v144
	v_fmac_f32_e32 v1, v63, v145
	v_fmac_f32_e32 v2, v63, v146
	v_fmac_f32_e32 v3, v63, v147
	v_fmac_f32_e32 v4, v63, v148
	v_fmac_f32_e32 v5, v63, v149
	v_fmac_f32_e32 v6, v63, v150
	v_fmac_f32_e32 v7, v63, v151
	v_fmac_f32_e32 v8, v63, v152
	v_fmac_f32_e32 v9, v63, v153
	v_fmac_f32_e32 v10, v63, v154
	v_fmac_f32_e32 v11, v63, v155
	v_fmac_f32_e32 v12, v63, v156
	v_fmac_f32_e32 v13, v63, v157
	v_fmac_f32_e32 v14, v63, v158
	v_fmac_f32_e32 v15, v63, v159
	v_lshl_add_u32 v161, v47, 7, v160
	global_load_dwordx4 v[140:143], v161, s[14:15]
	s_waitcnt lgkmcnt(0)
	ds_read_b128 v[32:35], v163 offset:320
	ds_read_b128 v[36:39], v163 offset:336
	ds_read_b128 v[40:43], v163 offset:352
	ds_read_b128 v[44:47], v163 offset:368
	ds_read_b128 v[48:51], v163 offset:768
	ds_read_b128 v[52:55], v163 offset:784
	ds_read_b128 v[56:59], v163 offset:800
	ds_read_b128 v[60:63], v163 offset:816
	s_waitcnt vmcnt(15)
	v_cvt_pk_f32_fp8_e32 v[144:145], v80
	v_cvt_pk_f32_fp8_sdwa v[146:147], v80 src0_sel:WORD_1
	v_cvt_pk_f32_fp8_e32 v[148:149], v81
	v_cvt_pk_f32_fp8_sdwa v[150:151], v81 src0_sel:WORD_1
	v_cvt_pk_f32_fp8_e32 v[152:153], v82
	v_cvt_pk_f32_fp8_sdwa v[154:155], v82 src0_sel:WORD_1
	v_cvt_pk_f32_fp8_e32 v[156:157], v83
	v_cvt_pk_f32_fp8_sdwa v[158:159], v83 src0_sel:WORD_1
	v_fmac_f32_e32 v0, v64, v144
	v_fmac_f32_e32 v1, v64, v145
	v_fmac_f32_e32 v2, v64, v146
	v_fmac_f32_e32 v3, v64, v147
	v_fmac_f32_e32 v4, v64, v148
	v_fmac_f32_e32 v5, v64, v149
	v_fmac_f32_e32 v6, v64, v150
	v_fmac_f32_e32 v7, v64, v151
	v_fmac_f32_e32 v8, v64, v152
	v_fmac_f32_e32 v9, v64, v153
	v_fmac_f32_e32 v10, v64, v154
	v_fmac_f32_e32 v11, v64, v155
	v_fmac_f32_e32 v12, v64, v156
	v_fmac_f32_e32 v13, v64, v157
	v_fmac_f32_e32 v14, v64, v158
	v_fmac_f32_e32 v15, v64, v159
	v_lshl_add_u32 v161, v16, 7, v160
	global_load_dwordx4 v[80:83], v161, s[14:15]
	s_waitcnt vmcnt(15)
	v_cvt_pk_f32_fp8_e32 v[144:145], v84
	v_cvt_pk_f32_fp8_sdwa v[146:147], v84 src0_sel:WORD_1
	v_cvt_pk_f32_fp8_e32 v[148:149], v85
	v_cvt_pk_f32_fp8_sdwa v[150:151], v85 src0_sel:WORD_1
	v_cvt_pk_f32_fp8_e32 v[152:153], v86
	v_cvt_pk_f32_fp8_sdwa v[154:155], v86 src0_sel:WORD_1
	v_cvt_pk_f32_fp8_e32 v[156:157], v87
	v_cvt_pk_f32_fp8_sdwa v[158:159], v87 src0_sel:WORD_1
	v_fmac_f32_e32 v0, v65, v144
	v_fmac_f32_e32 v1, v65, v145
	v_fmac_f32_e32 v2, v65, v146
	v_fmac_f32_e32 v3, v65, v147
	v_fmac_f32_e32 v4, v65, v148
	v_fmac_f32_e32 v5, v65, v149
	v_fmac_f32_e32 v6, v65, v150
	v_fmac_f32_e32 v7, v65, v151
	v_fmac_f32_e32 v8, v65, v152
	v_fmac_f32_e32 v9, v65, v153
	v_fmac_f32_e32 v10, v65, v154
	v_fmac_f32_e32 v11, v65, v155
	v_fmac_f32_e32 v12, v65, v156
	v_fmac_f32_e32 v13, v65, v157
	v_fmac_f32_e32 v14, v65, v158
	v_fmac_f32_e32 v15, v65, v159
	v_lshl_add_u32 v161, v17, 7, v160
	global_load_dwordx4 v[84:87], v161, s[14:15]
	s_waitcnt vmcnt(15)
	v_cvt_pk_f32_fp8_e32 v[144:145], v88
	v_cvt_pk_f32_fp8_sdwa v[146:147], v88 src0_sel:WORD_1
	v_cvt_pk_f32_fp8_e32 v[148:149], v89
	v_cvt_pk_f32_fp8_sdwa v[150:151], v89 src0_sel:WORD_1
	v_cvt_pk_f32_fp8_e32 v[152:153], v90
	v_cvt_pk_f32_fp8_sdwa v[154:155], v90 src0_sel:WORD_1
	v_cvt_pk_f32_fp8_e32 v[156:157], v91
	v_cvt_pk_f32_fp8_sdwa v[158:159], v91 src0_sel:WORD_1
	v_fmac_f32_e32 v0, v66, v144
	v_fmac_f32_e32 v1, v66, v145
	v_fmac_f32_e32 v2, v66, v146
	v_fmac_f32_e32 v3, v66, v147
	v_fmac_f32_e32 v4, v66, v148
	v_fmac_f32_e32 v5, v66, v149
	v_fmac_f32_e32 v6, v66, v150
	v_fmac_f32_e32 v7, v66, v151
	v_fmac_f32_e32 v8, v66, v152
	v_fmac_f32_e32 v9, v66, v153
	v_fmac_f32_e32 v10, v66, v154
	v_fmac_f32_e32 v11, v66, v155
	v_fmac_f32_e32 v12, v66, v156
	v_fmac_f32_e32 v13, v66, v157
	v_fmac_f32_e32 v14, v66, v158
	v_fmac_f32_e32 v15, v66, v159
	v_lshl_add_u32 v161, v18, 7, v160
	global_load_dwordx4 v[88:91], v161, s[14:15]
	s_waitcnt vmcnt(15)
; DI void phase_peer_b(const Params& p, int layer, const float* gnext, bool last) {
;     ...
;     for (int bt = 0; bt < 8; ++bt) {
;       u32x4 vr[16];
; #pragma unroll
;       for (int j = 0; j < 16; ++j) {
;         const int e = bt * 16 + j;
;         const int eidx = __builtin_amdgcn_readlane(e < 64 ? i0 : i1, e & 63);
;         vr[j] = *(const u32x4*)(EV + (size_t)eidx * DM + lane * 16);
;       }
; #pragma unroll
;       for (int j = 0; j < 16; ++j) {
;         const int e = bt * 16 + j;
;         const float wj = __int_as_float(__builtin_amdgcn_readlane(__float_as_int(e < 64 ? w0 : w1), e & 63));
; #pragma unroll
;         for (int w = 0; w < 4; ++w) {
;           const f32x2 lo = __builtin_amdgcn_cvt_pk_f32_fp8((int)vr[j][w], false);
;           const f32x2 hi = __builtin_amdgcn_cvt_pk_f32_fp8((int)vr[j][w], true);
;           acc[4 * w] += wj * lo[0]; acc[4 * w + 1] += wj * lo[1]; acc[4 * w + 2] += wj * hi[0]; acc[4 * w + 3] += wj * hi[1];
;         }
;       }
	v_cvt_pk_f32_fp8_e32 v[144:145], v92
	v_cvt_pk_f32_fp8_sdwa v[146:147], v92 src0_sel:WORD_1
	v_cvt_pk_f32_fp8_e32 v[148:149], v93
	v_cvt_pk_f32_fp8_sdwa v[150:151], v93 src0_sel:WORD_1
	v_cvt_pk_f32_fp8_e32 v[152:153], v94
	v_cvt_pk_f32_fp8_sdwa v[154:155], v94 src0_sel:WORD_1
	v_cvt_pk_f32_fp8_e32 v[156:157], v95
	v_cvt_pk_f32_fp8_sdwa v[158:159], v95 src0_sel:WORD_1
	v_fmac_f32_e32 v0, v67, v144
	v_fmac_f32_e32 v1, v67, v145
	v_fmac_f32_e32 v2, v67, v146
	v_fmac_f32_e32 v3, v67, v147
	v_fmac_f32_e32 v4, v67, v148
	v_fmac_f32_e32 v5, v67, v149
	v_fmac_f32_e32 v6, v67, v150
	v_fmac_f32_e32 v7, v67, v151
	v_fmac_f32_e32 v8, v67, v152
	v_fmac_f32_e32 v9, v67, v153
	v_fmac_f32_e32 v10, v67, v154
	v_fmac_f32_e32 v11, v67, v155
	v_fmac_f32_e32 v12, v67, v156
	v_fmac_f32_e32 v13, v67, v157
	v_fmac_f32_e32 v14, v67, v158
	v_fmac_f32_e32 v15, v67, v159
	v_lshl_add_u32 v161, v19, 7, v160
	global_load_dwordx4 v[92:95], v161, s[14:15]
	s_waitcnt vmcnt(15)
	v_cvt_pk_f32_fp8_e32 v[144:145], v96
	v_cvt_pk_f32_fp8_sdwa v[146:147], v96 src0_sel:WORD_1
	v_cvt_pk_f32_fp8_e32 v[148:149], v97
	v_cvt_pk_f32_fp8_sdwa v[150:151], v97 src0_sel:WORD_1
	v_cvt_pk_f32_fp8_e32 v[152:153], v98
	v_cvt_pk_f32_fp8_sdwa v[154:155], v98 src0_sel:WORD_1
	v_cvt_pk_f32_fp8_e32 v[156:157], v99
	v_cvt_pk_f32_fp8_sdwa v[158:159], v99 src0_sel:WORD_1
	v_fmac_f32_e32 v0, v68, v144
	v_fmac_f32_e32 v1, v68, v145
	v_fmac_f32_e32 v2, v68, v146
	v_fmac_f32_e32 v3, v68, v147
	v_fmac_f32_e32 v4, v68, v148
	v_fmac_f32_e32 v5, v68, v149
	v_fmac_f32_e32 v6, v68, v150
	v_fmac_f32_e32 v7, v68, v151
	v_fmac_f32_e32 v8, v68, v152
	v_fmac_f32_e32 v9, v68, v153
	v_fmac_f32_e32 v10, v68, v154
	v_fmac_f32_e32 v11, v68, v155
	v_fmac_f32_e32 v12, v68, v156
	v_fmac_f32_e32 v13, v68, v157
	v_fmac_f32_e32 v14, v68, v158
	v_fmac_f32_e32 v15, v68, v159
	v_lshl_add_u32 v161, v20, 7, v160
	global_load_dwordx4 v[96:99], v161, s[14:15]
	s_waitcnt vmcnt(15)
	v_cvt_pk_f32_fp8_e32 v[144:145], v100
	v_cvt_pk_f32_fp8_sdwa v[146:147], v100 src0_sel:WORD_1
	v_cvt_pk_f32_fp8_e32 v[148:149], v101
	v_cvt_pk_f32_fp8_sdwa v[150:151], v101 src0_sel:WORD_1
	v_cvt_pk_f32_fp8_e32 v[152:153], v102
	v_cvt_pk_f32_fp8_sdwa v[154:155], v102 src0_sel:WORD_1
	v_cvt_pk_f32_fp8_e32 v[156:157], v103
	v_cvt_pk_f32_fp8_sdwa v[158:159], v103 src0_sel:WORD_1
	v_fmac_f32_e32 v0, v69, v144
	v_fmac_f32_e32 v1, v69, v145
	v_fmac_f32_e32 v2, v69, v146
	v_fmac_f32_e32 v3, v69, v147
	v_fmac_f32_e32 v4, v69, v148
	v_fmac_f32_e32 v5, v69, v149
	v_fmac_f32_e32 v6, v69, v150
	v_fmac_f32_e32 v7, v69, v151
	v_fmac_f32_e32 v8, v69, v152
	v_fmac_f32_e32 v9, v69, v153
	v_fmac_f32_e32 v10, v69, v154
	v_fmac_f32_e32 v11, v69, v155
	v_fmac_f32_e32 v12, v69, v156
	v_fmac_f32_e32 v13, v69, v157
	v_fmac_f32_e32 v14, v69, v158
	v_fmac_f32_e32 v15, v69, v159
	v_lshl_add_u32 v161, v21, 7, v160
	global_load_dwordx4 v[100:103], v161, s[14:15]
	s_waitcnt vmcnt(15)
	v_cvt_pk_f32_fp8_e32 v[144:145], v104
	v_cvt_pk_f32_fp8_sdwa v[146:147], v104 src0_sel:WORD_1
	v_cvt_pk_f32_fp8_e32 v[148:149], v105
	v_cvt_pk_f32_fp8_sdwa v[150:151], v105 src0_sel:WORD_1
	v_cvt_pk_f32_fp8_e32 v[152:153], v106
	v_cvt_pk_f32_fp8_sdwa v[154:155], v106 src0_sel:WORD_1
	v_cvt_pk_f32_fp8_e32 v[156:157], v107
	v_cvt_pk_f32_fp8_sdwa v[158:159], v107 src0_sel:WORD_1
	v_fmac_f32_e32 v0, v70, v144
	v_fmac_f32_e32 v1, v70, v145
	v_fmac_f32_e32 v2, v70, v146
	v_fmac_f32_e32 v3, v70, v147
	v_fmac_f32_e32 v4, v70, v148
	v_fmac_f32_e32 v5, v70, v149
	v_fmac_f32_e32 v6, v70, v150
	v_fmac_f32_e32 v7, v70, v151
	v_fmac_f32_e32 v8, v70, v152
	v_fmac_f32_e32 v9, v70, v153
	v_fmac_f32_e32 v10, v70, v154
	v_fmac_f32_e32 v11, v70, v155
	v_fmac_f32_e32 v12, v70, v156
	v_fmac_f32_e32 v13, v70, v157
	v_fmac_f32_e32 v14, v70, v158
	v_fmac_f32_e32 v15, v70, v159
	v_lshl_add_u32 v161, v22, 7, v160
	global_load_dwordx4 v[104:107], v161, s[14:15]
	s_waitcnt vmcnt(15)
	v_cvt_pk_f32_fp8_e32 v[144:145], v108
	v_cvt_pk_f32_fp8_sdwa v[146:147], v108 src0_sel:WORD_1
	v_cvt_pk_f32_fp8_e32 v[148:149], v109
	v_cvt_pk_f32_fp8_sdwa v[150:151], v109 src0_sel:WORD_1
	v_cvt_pk_f32_fp8_e32 v[152:153], v110
	v_cvt_pk_f32_fp8_sdwa v[154:155], v110 src0_sel:WORD_1
	v_cvt_pk_f32_fp8_e32 v[156:157], v111
	v_cvt_pk_f32_fp8_sdwa v[158:159], v111 src0_sel:WORD_1
	v_fmac_f32_e32 v0, v71, v144
	v_fmac_f32_e32 v1, v71, v145
	v_fmac_f32_e32 v2, v71, v146
	v_fmac_f32_e32 v3, v71, v147
	v_fmac_f32_e32 v4, v71, v148
	v_fmac_f32_e32 v5, v71, v149
	v_fmac_f32_e32 v6, v71, v150
	v_fmac_f32_e32 v7, v71, v151
	v_fmac_f32_e32 v8, v71, v152
	v_fmac_f32_e32 v9, v71, v153
	v_fmac_f32_e32 v10, v71, v154
	v_fmac_f32_e32 v11, v71, v155
	v_fmac_f32_e32 v12, v71, v156
	v_fmac_f32_e32 v13, v71, v157
	v_fmac_f32_e32 v14, v71, v158
	v_fmac_f32_e32 v15, v71, v159
	v_lshl_add_u32 v161, v23, 7, v160
	global_load_dwordx4 v[108:111], v161, s[14:15]
	s_waitcnt vmcnt(15)
	v_cvt_pk_f32_fp8_e32 v[144:145], v112
	v_cvt_pk_f32_fp8_sdwa v[146:147], v112 src0_sel:WORD_1
	v_cvt_pk_f32_fp8_e32 v[148:149], v113
	v_cvt_pk_f32_fp8_sdwa v[150:151], v113 src0_sel:WORD_1
	v_cvt_pk_f32_fp8_e32 v[152:153], v114
	v_cvt_pk_f32_fp8_sdwa v[154:155], v114 src0_sel:WORD_1
	v_cvt_pk_f32_fp8_e32 v[156:157], v115
	v_cvt_pk_f32_fp8_sdwa v[158:159], v115 src0_sel:WORD_1
	v_fmac_f32_e32 v0, v72, v144
	v_fmac_f32_e32 v1, v72, v145
	v_fmac_f32_e32 v2, v72, v146
	v_fmac_f32_e32 v3, v72, v147
	v_fmac_f32_e32 v4, v72, v148
	v_fmac_f32_e32 v5, v72, v149
	v_fmac_f32_e32 v6, v72, v150
	v_fmac_f32_e32 v7, v72, v151
	v_fmac_f32_e32 v8, v72, v152
	v_fmac_f32_e32 v9, v72, v153
	v_fmac_f32_e32 v10, v72, v154
	v_fmac_f32_e32 v11, v72, v155
	v_fmac_f32_e32 v12, v72, v156
	v_fmac_f32_e32 v13, v72, v157
	v_fmac_f32_e32 v14, v72, v158
	v_fmac_f32_e32 v15, v72, v159
	v_lshl_add_u32 v161, v24, 7, v160
	global_load_dwordx4 v[112:115], v161, s[14:15]
	s_waitcnt vmcnt(15)
; DI void phase_peer_b(const Params& p, int layer, const float* gnext, bool last) {
;     ...
;     for (int bt = 0; bt < 8; ++bt) {
;       u32x4 vr[16];
; #pragma unroll
;       for (int j = 0; j < 16; ++j) {
;         const int e = bt * 16 + j;
;         const int eidx = __builtin_amdgcn_readlane(e < 64 ? i0 : i1, e & 63);
;         vr[j] = *(const u32x4*)(EV + (size_t)eidx * DM + lane * 16);
;       }
; #pragma unroll
;       for (int j = 0; j < 16; ++j) {
;         const int e = bt * 16 + j;
;         const float wj = __int_as_float(__builtin_amdgcn_readlane(__float_as_int(e < 64 ? w0 : w1), e & 63));
; #pragma unroll
;         for (int w = 0; w < 4; ++w) {
;           const f32x2 lo = __builtin_amdgcn_cvt_pk_f32_fp8((int)vr[j][w], false);
;           const f32x2 hi = __builtin_amdgcn_cvt_pk_f32_fp8((int)vr[j][w], true);
;           acc[4 * w] += wj * lo[0]; acc[4 * w + 1] += wj * lo[1]; acc[4 * w + 2] += wj * hi[0]; acc[4 * w + 3] += wj * hi[1];
;         }
;       }
	v_cvt_pk_f32_fp8_e32 v[144:145], v116
	v_cvt_pk_f32_fp8_sdwa v[146:147], v116 src0_sel:WORD_1
	v_cvt_pk_f32_fp8_e32 v[148:149], v117
	v_cvt_pk_f32_fp8_sdwa v[150:151], v117 src0_sel:WORD_1
	v_cvt_pk_f32_fp8_e32 v[152:153], v118
	v_cvt_pk_f32_fp8_sdwa v[154:155], v118 src0_sel:WORD_1
	v_cvt_pk_f32_fp8_e32 v[156:157], v119
	v_cvt_pk_f32_fp8_sdwa v[158:159], v119 src0_sel:WORD_1
	v_fmac_f32_e32 v0, v73, v144
	v_fmac_f32_e32 v1, v73, v145
	v_fmac_f32_e32 v2, v73, v146
	v_fmac_f32_e32 v3, v73, v147
	v_fmac_f32_e32 v4, v73, v148
	v_fmac_f32_e32 v5, v73, v149
	v_fmac_f32_e32 v6, v73, v150
	v_fmac_f32_e32 v7, v73, v151
	v_fmac_f32_e32 v8, v73, v152
	v_fmac_f32_e32 v9, v73, v153
	v_fmac_f32_e32 v10, v73, v154
	v_fmac_f32_e32 v11, v73, v155
	v_fmac_f32_e32 v12, v73, v156
	v_fmac_f32_e32 v13, v73, v157
	v_fmac_f32_e32 v14, v73, v158
	v_fmac_f32_e32 v15, v73, v159
	v_lshl_add_u32 v161, v25, 7, v160
	global_load_dwordx4 v[116:119], v161, s[14:15]
	s_waitcnt vmcnt(15)
	v_cvt_pk_f32_fp8_e32 v[144:145], v120
	v_cvt_pk_f32_fp8_sdwa v[146:147], v120 src0_sel:WORD_1
	v_cvt_pk_f32_fp8_e32 v[148:149], v121
	v_cvt_pk_f32_fp8_sdwa v[150:151], v121 src0_sel:WORD_1
	v_cvt_pk_f32_fp8_e32 v[152:153], v122
	v_cvt_pk_f32_fp8_sdwa v[154:155], v122 src0_sel:WORD_1
	v_cvt_pk_f32_fp8_e32 v[156:157], v123
	v_cvt_pk_f32_fp8_sdwa v[158:159], v123 src0_sel:WORD_1
	v_fmac_f32_e32 v0, v74, v144
	v_fmac_f32_e32 v1, v74, v145
	v_fmac_f32_e32 v2, v74, v146
	v_fmac_f32_e32 v3, v74, v147
	v_fmac_f32_e32 v4, v74, v148
	v_fmac_f32_e32 v5, v74, v149
	v_fmac_f32_e32 v6, v74, v150
	v_fmac_f32_e32 v7, v74, v151
	v_fmac_f32_e32 v8, v74, v152
	v_fmac_f32_e32 v9, v74, v153
	v_fmac_f32_e32 v10, v74, v154
	v_fmac_f32_e32 v11, v74, v155
	v_fmac_f32_e32 v12, v74, v156
	v_fmac_f32_e32 v13, v74, v157
	v_fmac_f32_e32 v14, v74, v158
	v_fmac_f32_e32 v15, v74, v159
	v_lshl_add_u32 v161, v26, 7, v160
	global_load_dwordx4 v[120:123], v161, s[14:15]
	s_waitcnt vmcnt(15)
	v_cvt_pk_f32_fp8_e32 v[144:145], v124
	v_cvt_pk_f32_fp8_sdwa v[146:147], v124 src0_sel:WORD_1
	v_cvt_pk_f32_fp8_e32 v[148:149], v125
	v_cvt_pk_f32_fp8_sdwa v[150:151], v125 src0_sel:WORD_1
	v_cvt_pk_f32_fp8_e32 v[152:153], v126
	v_cvt_pk_f32_fp8_sdwa v[154:155], v126 src0_sel:WORD_1
	v_cvt_pk_f32_fp8_e32 v[156:157], v127
	v_cvt_pk_f32_fp8_sdwa v[158:159], v127 src0_sel:WORD_1
	v_fmac_f32_e32 v0, v75, v144
	v_fmac_f32_e32 v1, v75, v145
	v_fmac_f32_e32 v2, v75, v146
	v_fmac_f32_e32 v3, v75, v147
	v_fmac_f32_e32 v4, v75, v148
	v_fmac_f32_e32 v5, v75, v149
	v_fmac_f32_e32 v6, v75, v150
	v_fmac_f32_e32 v7, v75, v151
	v_fmac_f32_e32 v8, v75, v152
	v_fmac_f32_e32 v9, v75, v153
	v_fmac_f32_e32 v10, v75, v154
	v_fmac_f32_e32 v11, v75, v155
	v_fmac_f32_e32 v12, v75, v156
	v_fmac_f32_e32 v13, v75, v157
	v_fmac_f32_e32 v14, v75, v158
	v_fmac_f32_e32 v15, v75, v159
	v_lshl_add_u32 v161, v27, 7, v160
	global_load_dwordx4 v[124:127], v161, s[14:15]
	s_waitcnt vmcnt(15)
	v_cvt_pk_f32_fp8_e32 v[144:145], v128
	v_cvt_pk_f32_fp8_sdwa v[146:147], v128 src0_sel:WORD_1
	v_cvt_pk_f32_fp8_e32 v[148:149], v129
	v_cvt_pk_f32_fp8_sdwa v[150:151], v129 src0_sel:WORD_1
	v_cvt_pk_f32_fp8_e32 v[152:153], v130
	v_cvt_pk_f32_fp8_sdwa v[154:155], v130 src0_sel:WORD_1
	v_cvt_pk_f32_fp8_e32 v[156:157], v131
	v_cvt_pk_f32_fp8_sdwa v[158:159], v131 src0_sel:WORD_1
	v_fmac_f32_e32 v0, v76, v144
	v_fmac_f32_e32 v1, v76, v145
	v_fmac_f32_e32 v2, v76, v146
	v_fmac_f32_e32 v3, v76, v147
	v_fmac_f32_e32 v4, v76, v148
	v_fmac_f32_e32 v5, v76, v149
	v_fmac_f32_e32 v6, v76, v150
	v_fmac_f32_e32 v7, v76, v151
	v_fmac_f32_e32 v8, v76, v152
	v_fmac_f32_e32 v9, v76, v153
	v_fmac_f32_e32 v10, v76, v154
	v_fmac_f32_e32 v11, v76, v155
	v_fmac_f32_e32 v12, v76, v156
	v_fmac_f32_e32 v13, v76, v157
	v_fmac_f32_e32 v14, v76, v158
	v_fmac_f32_e32 v15, v76, v159
	v_lshl_add_u32 v161, v28, 7, v160
	global_load_dwordx4 v[128:131], v161, s[14:15]
	s_waitcnt vmcnt(15)
	v_cvt_pk_f32_fp8_e32 v[144:145], v132
	v_cvt_pk_f32_fp8_sdwa v[146:147], v132 src0_sel:WORD_1
	v_cvt_pk_f32_fp8_e32 v[148:149], v133
	v_cvt_pk_f32_fp8_sdwa v[150:151], v133 src0_sel:WORD_1
	v_cvt_pk_f32_fp8_e32 v[152:153], v134
	v_cvt_pk_f32_fp8_sdwa v[154:155], v134 src0_sel:WORD_1
	v_cvt_pk_f32_fp8_e32 v[156:157], v135
	v_cvt_pk_f32_fp8_sdwa v[158:159], v135 src0_sel:WORD_1
	v_fmac_f32_e32 v0, v77, v144
	v_fmac_f32_e32 v1, v77, v145
	v_fmac_f32_e32 v2, v77, v146
	v_fmac_f32_e32 v3, v77, v147
	v_fmac_f32_e32 v4, v77, v148
	v_fmac_f32_e32 v5, v77, v149
	v_fmac_f32_e32 v6, v77, v150
	v_fmac_f32_e32 v7, v77, v151
	v_fmac_f32_e32 v8, v77, v152
	v_fmac_f32_e32 v9, v77, v153
	v_fmac_f32_e32 v10, v77, v154
	v_fmac_f32_e32 v11, v77, v155
	v_fmac_f32_e32 v12, v77, v156
	v_fmac_f32_e32 v13, v77, v157
	v_fmac_f32_e32 v14, v77, v158
	v_fmac_f32_e32 v15, v77, v159
	v_lshl_add_u32 v161, v29, 7, v160
	global_load_dwordx4 v[132:135], v161, s[14:15]
	s_waitcnt vmcnt(15)
	v_cvt_pk_f32_fp8_e32 v[144:145], v136
	v_cvt_pk_f32_fp8_sdwa v[146:147], v136 src0_sel:WORD_1
	v_cvt_pk_f32_fp8_e32 v[148:149], v137
	v_cvt_pk_f32_fp8_sdwa v[150:151], v137 src0_sel:WORD_1
	v_cvt_pk_f32_fp8_e32 v[152:153], v138
	v_cvt_pk_f32_fp8_sdwa v[154:155], v138 src0_sel:WORD_1
	v_cvt_pk_f32_fp8_e32 v[156:157], v139
	v_cvt_pk_f32_fp8_sdwa v[158:159], v139 src0_sel:WORD_1
	v_fmac_f32_e32 v0, v78, v144
	v_fmac_f32_e32 v1, v78, v145
	v_fmac_f32_e32 v2, v78, v146
	v_fmac_f32_e32 v3, v78, v147
	v_fmac_f32_e32 v4, v78, v148
	v_fmac_f32_e32 v5, v78, v149
	v_fmac_f32_e32 v6, v78, v150
	v_fmac_f32_e32 v7, v78, v151
	v_fmac_f32_e32 v8, v78, v152
	v_fmac_f32_e32 v9, v78, v153
	v_fmac_f32_e32 v10, v78, v154
	v_fmac_f32_e32 v11, v78, v155
	v_fmac_f32_e32 v12, v78, v156
	v_fmac_f32_e32 v13, v78, v157
	v_fmac_f32_e32 v14, v78, v158
	v_fmac_f32_e32 v15, v78, v159
	v_lshl_add_u32 v161, v30, 7, v160
	global_load_dwordx4 v[136:139], v161, s[14:15]
	s_waitcnt vmcnt(15)
; DI void phase_peer_b(const Params& p, int layer, const float* gnext, bool last) {
;     ...
;     for (int bt = 0; bt < 8; ++bt) {
;       u32x4 vr[16];
; #pragma unroll
;       for (int j = 0; j < 16; ++j) {
;         const int e = bt * 16 + j;
;         const int eidx = __builtin_amdgcn_readlane(e < 64 ? i0 : i1, e & 63);
;         vr[j] = *(const u32x4*)(EV + (size_t)eidx * DM + lane * 16);
;       }
; #pragma unroll
;       for (int j = 0; j < 16; ++j) {
;         const int e = bt * 16 + j;
;         const float wj = __int_as_float(__builtin_amdgcn_readlane(__float_as_int(e < 64 ? w0 : w1), e & 63));
; #pragma unroll
;         for (int w = 0; w < 4; ++w) {
;           const f32x2 lo = __builtin_amdgcn_cvt_pk_f32_fp8((int)vr[j][w], false);
;           const f32x2 hi = __builtin_amdgcn_cvt_pk_f32_fp8((int)vr[j][w], true);
;           acc[4 * w] += wj * lo[0]; acc[4 * w + 1] += wj * lo[1]; acc[4 * w + 2] += wj * hi[0]; acc[4 * w + 3] += wj * hi[1];
;         }
;       }
	v_cvt_pk_f32_fp8_e32 v[144:145], v140
	v_cvt_pk_f32_fp8_sdwa v[146:147], v140 src0_sel:WORD_1
	v_cvt_pk_f32_fp8_e32 v[148:149], v141
	v_cvt_pk_f32_fp8_sdwa v[150:151], v141 src0_sel:WORD_1
	v_cvt_pk_f32_fp8_e32 v[152:153], v142
	v_cvt_pk_f32_fp8_sdwa v[154:155], v142 src0_sel:WORD_1
	v_cvt_pk_f32_fp8_e32 v[156:157], v143
	v_cvt_pk_f32_fp8_sdwa v[158:159], v143 src0_sel:WORD_1
	v_fmac_f32_e32 v0, v79, v144
	v_fmac_f32_e32 v1, v79, v145
	v_fmac_f32_e32 v2, v79, v146
	v_fmac_f32_e32 v3, v79, v147
	v_fmac_f32_e32 v4, v79, v148
	v_fmac_f32_e32 v5, v79, v149
	v_fmac_f32_e32 v6, v79, v150
	v_fmac_f32_e32 v7, v79, v151
	v_fmac_f32_e32 v8, v79, v152
	v_fmac_f32_e32 v9, v79, v153
	v_fmac_f32_e32 v10, v79, v154
	v_fmac_f32_e32 v11, v79, v155
	v_fmac_f32_e32 v12, v79, v156
	v_fmac_f32_e32 v13, v79, v157
	v_fmac_f32_e32 v14, v79, v158
	v_fmac_f32_e32 v15, v79, v159
	v_lshl_add_u32 v161, v31, 7, v160
	global_load_dwordx4 v[140:143], v161, s[14:15]
	s_waitcnt lgkmcnt(0)
	ds_read_b128 v[16:19], v163 offset:384
	ds_read_b128 v[20:23], v163 offset:400
	ds_read_b128 v[24:27], v163 offset:416
	ds_read_b128 v[28:31], v163 offset:432
	ds_read_b128 v[64:67], v163 offset:832
	ds_read_b128 v[68:71], v163 offset:848
	ds_read_b128 v[72:75], v163 offset:864
	ds_read_b128 v[76:79], v163 offset:880
	s_waitcnt vmcnt(15)
	v_cvt_pk_f32_fp8_e32 v[144:145], v80
	v_cvt_pk_f32_fp8_sdwa v[146:147], v80 src0_sel:WORD_1
	v_cvt_pk_f32_fp8_e32 v[148:149], v81
	v_cvt_pk_f32_fp8_sdwa v[150:151], v81 src0_sel:WORD_1
	v_cvt_pk_f32_fp8_e32 v[152:153], v82
	v_cvt_pk_f32_fp8_sdwa v[154:155], v82 src0_sel:WORD_1
	v_cvt_pk_f32_fp8_e32 v[156:157], v83
	v_cvt_pk_f32_fp8_sdwa v[158:159], v83 src0_sel:WORD_1
	v_fmac_f32_e32 v0, v48, v144
	v_fmac_f32_e32 v1, v48, v145
	v_fmac_f32_e32 v2, v48, v146
	v_fmac_f32_e32 v3, v48, v147
	v_fmac_f32_e32 v4, v48, v148
	v_fmac_f32_e32 v5, v48, v149
	v_fmac_f32_e32 v6, v48, v150
	v_fmac_f32_e32 v7, v48, v151
	v_fmac_f32_e32 v8, v48, v152
	v_fmac_f32_e32 v9, v48, v153
	v_fmac_f32_e32 v10, v48, v154
	v_fmac_f32_e32 v11, v48, v155
	v_fmac_f32_e32 v12, v48, v156
	v_fmac_f32_e32 v13, v48, v157
	v_fmac_f32_e32 v14, v48, v158
	v_fmac_f32_e32 v15, v48, v159
	v_lshl_add_u32 v161, v32, 7, v160
	global_load_dwordx4 v[80:83], v161, s[14:15]
	s_waitcnt vmcnt(15)
	v_cvt_pk_f32_fp8_e32 v[144:145], v84
	v_cvt_pk_f32_fp8_sdwa v[146:147], v84 src0_sel:WORD_1
	v_cvt_pk_f32_fp8_e32 v[148:149], v85
	v_cvt_pk_f32_fp8_sdwa v[150:151], v85 src0_sel:WORD_1
	v_cvt_pk_f32_fp8_e32 v[152:153], v86
	v_cvt_pk_f32_fp8_sdwa v[154:155], v86 src0_sel:WORD_1
	v_cvt_pk_f32_fp8_e32 v[156:157], v87
	v_cvt_pk_f32_fp8_sdwa v[158:159], v87 src0_sel:WORD_1
	v_fmac_f32_e32 v0, v49, v144
	v_fmac_f32_e32 v1, v49, v145
	v_fmac_f32_e32 v2, v49, v146
	v_fmac_f32_e32 v3, v49, v147
	v_fmac_f32_e32 v4, v49, v148
	v_fmac_f32_e32 v5, v49, v149
	v_fmac_f32_e32 v6, v49, v150
	v_fmac_f32_e32 v7, v49, v151
	v_fmac_f32_e32 v8, v49, v152
	v_fmac_f32_e32 v9, v49, v153
	v_fmac_f32_e32 v10, v49, v154
	v_fmac_f32_e32 v11, v49, v155
	v_fmac_f32_e32 v12, v49, v156
	v_fmac_f32_e32 v13, v49, v157
	v_fmac_f32_e32 v14, v49, v158
	v_fmac_f32_e32 v15, v49, v159
	v_lshl_add_u32 v161, v33, 7, v160
	global_load_dwordx4 v[84:87], v161, s[14:15]
	s_waitcnt vmcnt(15)
	v_cvt_pk_f32_fp8_e32 v[144:145], v88
	v_cvt_pk_f32_fp8_sdwa v[146:147], v88 src0_sel:WORD_1
	v_cvt_pk_f32_fp8_e32 v[148:149], v89
	v_cvt_pk_f32_fp8_sdwa v[150:151], v89 src0_sel:WORD_1
	v_cvt_pk_f32_fp8_e32 v[152:153], v90
	v_cvt_pk_f32_fp8_sdwa v[154:155], v90 src0_sel:WORD_1
	v_cvt_pk_f32_fp8_e32 v[156:157], v91
	v_cvt_pk_f32_fp8_sdwa v[158:159], v91 src0_sel:WORD_1
	v_fmac_f32_e32 v0, v50, v144
	v_fmac_f32_e32 v1, v50, v145
	v_fmac_f32_e32 v2, v50, v146
	v_fmac_f32_e32 v3, v50, v147
	v_fmac_f32_e32 v4, v50, v148
	v_fmac_f32_e32 v5, v50, v149
	v_fmac_f32_e32 v6, v50, v150
	v_fmac_f32_e32 v7, v50, v151
	v_fmac_f32_e32 v8, v50, v152
	v_fmac_f32_e32 v9, v50, v153
	v_fmac_f32_e32 v10, v50, v154
	v_fmac_f32_e32 v11, v50, v155
	v_fmac_f32_e32 v12, v50, v156
	v_fmac_f32_e32 v13, v50, v157
	v_fmac_f32_e32 v14, v50, v158
	v_fmac_f32_e32 v15, v50, v159
	v_lshl_add_u32 v161, v34, 7, v160
	global_load_dwordx4 v[88:91], v161, s[14:15]
	s_waitcnt vmcnt(15)
	v_cvt_pk_f32_fp8_e32 v[144:145], v92
	v_cvt_pk_f32_fp8_sdwa v[146:147], v92 src0_sel:WORD_1
	v_cvt_pk_f32_fp8_e32 v[148:149], v93
	v_cvt_pk_f32_fp8_sdwa v[150:151], v93 src0_sel:WORD_1
	v_cvt_pk_f32_fp8_e32 v[152:153], v94
	v_cvt_pk_f32_fp8_sdwa v[154:155], v94 src0_sel:WORD_1
	v_cvt_pk_f32_fp8_e32 v[156:157], v95
	v_cvt_pk_f32_fp8_sdwa v[158:159], v95 src0_sel:WORD_1
	v_fmac_f32_e32 v0, v51, v144
	v_fmac_f32_e32 v1, v51, v145
	v_fmac_f32_e32 v2, v51, v146
	v_fmac_f32_e32 v3, v51, v147
	v_fmac_f32_e32 v4, v51, v148
	v_fmac_f32_e32 v5, v51, v149
	v_fmac_f32_e32 v6, v51, v150
	v_fmac_f32_e32 v7, v51, v151
	v_fmac_f32_e32 v8, v51, v152
	v_fmac_f32_e32 v9, v51, v153
	v_fmac_f32_e32 v10, v51, v154
	v_fmac_f32_e32 v11, v51, v155
	v_fmac_f32_e32 v12, v51, v156
	v_fmac_f32_e32 v13, v51, v157
	v_fmac_f32_e32 v14, v51, v158
	v_fmac_f32_e32 v15, v51, v159
	v_lshl_add_u32 v161, v35, 7, v160
	global_load_dwordx4 v[92:95], v161, s[14:15]
	s_waitcnt vmcnt(15)
	v_cvt_pk_f32_fp8_e32 v[144:145], v96
	v_cvt_pk_f32_fp8_sdwa v[146:147], v96 src0_sel:WORD_1
	v_cvt_pk_f32_fp8_e32 v[148:149], v97
	v_cvt_pk_f32_fp8_sdwa v[150:151], v97 src0_sel:WORD_1
	v_cvt_pk_f32_fp8_e32 v[152:153], v98
	v_cvt_pk_f32_fp8_sdwa v[154:155], v98 src0_sel:WORD_1
	v_cvt_pk_f32_fp8_e32 v[156:157], v99
	v_cvt_pk_f32_fp8_sdwa v[158:159], v99 src0_sel:WORD_1
	v_fmac_f32_e32 v0, v52, v144
	v_fmac_f32_e32 v1, v52, v145
	v_fmac_f32_e32 v2, v52, v146
	v_fmac_f32_e32 v3, v52, v147
	v_fmac_f32_e32 v4, v52, v148
	v_fmac_f32_e32 v5, v52, v149
	v_fmac_f32_e32 v6, v52, v150
	v_fmac_f32_e32 v7, v52, v151
	v_fmac_f32_e32 v8, v52, v152
	v_fmac_f32_e32 v9, v52, v153
	v_fmac_f32_e32 v10, v52, v154
	v_fmac_f32_e32 v11, v52, v155
	v_fmac_f32_e32 v12, v52, v156
	v_fmac_f32_e32 v13, v52, v157
	v_fmac_f32_e32 v14, v52, v158
	v_fmac_f32_e32 v15, v52, v159
	v_lshl_add_u32 v161, v36, 7, v160
	global_load_dwordx4 v[96:99], v161, s[14:15]
	s_waitcnt vmcnt(15)
; DI void phase_peer_b(const Params& p, int layer, const float* gnext, bool last) {
;     ...
; #pragma unroll
;       for (int j = 0; j < 16; ++j) {
;         const int e = bt * 16 + j;
;         const int eidx = __builtin_amdgcn_readlane(e < 64 ? i0 : i1, e & 63);
;         vr[j] = *(const u32x4*)(EV + (size_t)eidx * DM + lane * 16);
;       }
; #pragma unroll
;       for (int j = 0; j < 16; ++j) {
;         const int e = bt * 16 + j;
;         const float wj = __int_as_float(__builtin_amdgcn_readlane(__float_as_int(e < 64 ? w0 : w1), e & 63));
; #pragma unroll
;         for (int w = 0; w < 4; ++w) {
;           const f32x2 lo = __builtin_amdgcn_cvt_pk_f32_fp8((int)vr[j][w], false);
;           const f32x2 hi = __builtin_amdgcn_cvt_pk_f32_fp8((int)vr[j][w], true);
;           acc[4 * w] += wj * lo[0]; acc[4 * w + 1] += wj * lo[1]; acc[4 * w + 2] += wj * hi[0]; acc[4 * w + 3] += wj * hi[1];
;         }
	v_cvt_pk_f32_fp8_e32 v[144:145], v100
	v_cvt_pk_f32_fp8_sdwa v[146:147], v100 src0_sel:WORD_1
	v_cvt_pk_f32_fp8_e32 v[148:149], v101
	v_cvt_pk_f32_fp8_sdwa v[150:151], v101 src0_sel:WORD_1
	v_cvt_pk_f32_fp8_e32 v[152:153], v102
	v_cvt_pk_f32_fp8_sdwa v[154:155], v102 src0_sel:WORD_1
	v_cvt_pk_f32_fp8_e32 v[156:157], v103
	v_cvt_pk_f32_fp8_sdwa v[158:159], v103 src0_sel:WORD_1
	v_fmac_f32_e32 v0, v53, v144
	v_fmac_f32_e32 v1, v53, v145
	v_fmac_f32_e32 v2, v53, v146
	v_fmac_f32_e32 v3, v53, v147
	v_fmac_f32_e32 v4, v53, v148
	v_fmac_f32_e32 v5, v53, v149
	v_fmac_f32_e32 v6, v53, v150
	v_fmac_f32_e32 v7, v53, v151
	v_fmac_f32_e32 v8, v53, v152
	v_fmac_f32_e32 v9, v53, v153
	v_fmac_f32_e32 v10, v53, v154
	v_fmac_f32_e32 v11, v53, v155
	v_fmac_f32_e32 v12, v53, v156
	v_fmac_f32_e32 v13, v53, v157
	v_fmac_f32_e32 v14, v53, v158
	v_fmac_f32_e32 v15, v53, v159
	v_lshl_add_u32 v161, v37, 7, v160
	global_load_dwordx4 v[100:103], v161, s[14:15]
	s_waitcnt vmcnt(15)
	v_cvt_pk_f32_fp8_e32 v[144:145], v104
	v_cvt_pk_f32_fp8_sdwa v[146:147], v104 src0_sel:WORD_1
	v_cvt_pk_f32_fp8_e32 v[148:149], v105
	v_cvt_pk_f32_fp8_sdwa v[150:151], v105 src0_sel:WORD_1
	v_cvt_pk_f32_fp8_e32 v[152:153], v106
	v_cvt_pk_f32_fp8_sdwa v[154:155], v106 src0_sel:WORD_1
	v_cvt_pk_f32_fp8_e32 v[156:157], v107
	v_cvt_pk_f32_fp8_sdwa v[158:159], v107 src0_sel:WORD_1
	v_fmac_f32_e32 v0, v54, v144
	v_fmac_f32_e32 v1, v54, v145
	v_fmac_f32_e32 v2, v54, v146
	v_fmac_f32_e32 v3, v54, v147
	v_fmac_f32_e32 v4, v54, v148
	v_fmac_f32_e32 v5, v54, v149
	v_fmac_f32_e32 v6, v54, v150
	v_fmac_f32_e32 v7, v54, v151
	v_fmac_f32_e32 v8, v54, v152
	v_fmac_f32_e32 v9, v54, v153
	v_fmac_f32_e32 v10, v54, v154
	v_fmac_f32_e32 v11, v54, v155
	v_fmac_f32_e32 v12, v54, v156
	v_fmac_f32_e32 v13, v54, v157
	v_fmac_f32_e32 v14, v54, v158
	v_fmac_f32_e32 v15, v54, v159
	v_lshl_add_u32 v161, v38, 7, v160
	global_load_dwordx4 v[104:107], v161, s[14:15]
	s_waitcnt vmcnt(15)
	v_cvt_pk_f32_fp8_e32 v[144:145], v108
	v_cvt_pk_f32_fp8_sdwa v[146:147], v108 src0_sel:WORD_1
	v_cvt_pk_f32_fp8_e32 v[148:149], v109
	v_cvt_pk_f32_fp8_sdwa v[150:151], v109 src0_sel:WORD_1
	v_cvt_pk_f32_fp8_e32 v[152:153], v110
	v_cvt_pk_f32_fp8_sdwa v[154:155], v110 src0_sel:WORD_1
	v_cvt_pk_f32_fp8_e32 v[156:157], v111
	v_cvt_pk_f32_fp8_sdwa v[158:159], v111 src0_sel:WORD_1
	v_fmac_f32_e32 v0, v55, v144
	v_fmac_f32_e32 v1, v55, v145
	v_fmac_f32_e32 v2, v55, v146
	v_fmac_f32_e32 v3, v55, v147
	v_fmac_f32_e32 v4, v55, v148
	v_fmac_f32_e32 v5, v55, v149
	v_fmac_f32_e32 v6, v55, v150
	v_fmac_f32_e32 v7, v55, v151
	v_fmac_f32_e32 v8, v55, v152
	v_fmac_f32_e32 v9, v55, v153
	v_fmac_f32_e32 v10, v55, v154
	v_fmac_f32_e32 v11, v55, v155
	v_fmac_f32_e32 v12, v55, v156
	v_fmac_f32_e32 v13, v55, v157
	v_fmac_f32_e32 v14, v55, v158
	v_fmac_f32_e32 v15, v55, v159
	v_lshl_add_u32 v161, v39, 7, v160
	global_load_dwordx4 v[108:111], v161, s[14:15]
	s_waitcnt vmcnt(15)
	v_cvt_pk_f32_fp8_e32 v[144:145], v112
	v_cvt_pk_f32_fp8_sdwa v[146:147], v112 src0_sel:WORD_1
	v_cvt_pk_f32_fp8_e32 v[148:149], v113
	v_cvt_pk_f32_fp8_sdwa v[150:151], v113 src0_sel:WORD_1
	v_cvt_pk_f32_fp8_e32 v[152:153], v114
	v_cvt_pk_f32_fp8_sdwa v[154:155], v114 src0_sel:WORD_1
	v_cvt_pk_f32_fp8_e32 v[156:157], v115
	v_cvt_pk_f32_fp8_sdwa v[158:159], v115 src0_sel:WORD_1
	v_fmac_f32_e32 v0, v56, v144
	v_fmac_f32_e32 v1, v56, v145
	v_fmac_f32_e32 v2, v56, v146
	v_fmac_f32_e32 v3, v56, v147
	v_fmac_f32_e32 v4, v56, v148
	v_fmac_f32_e32 v5, v56, v149
	v_fmac_f32_e32 v6, v56, v150
	v_fmac_f32_e32 v7, v56, v151
	v_fmac_f32_e32 v8, v56, v152
	v_fmac_f32_e32 v9, v56, v153
	v_fmac_f32_e32 v10, v56, v154
	v_fmac_f32_e32 v11, v56, v155
	v_fmac_f32_e32 v12, v56, v156
	v_fmac_f32_e32 v13, v56, v157
	v_fmac_f32_e32 v14, v56, v158
	v_fmac_f32_e32 v15, v56, v159
	v_lshl_add_u32 v161, v40, 7, v160
	global_load_dwordx4 v[112:115], v161, s[14:15]
	s_waitcnt vmcnt(15)
	v_cvt_pk_f32_fp8_e32 v[144:145], v116
	v_cvt_pk_f32_fp8_sdwa v[146:147], v116 src0_sel:WORD_1
	v_cvt_pk_f32_fp8_e32 v[148:149], v117
	v_cvt_pk_f32_fp8_sdwa v[150:151], v117 src0_sel:WORD_1
	v_cvt_pk_f32_fp8_e32 v[152:153], v118
	v_cvt_pk_f32_fp8_sdwa v[154:155], v118 src0_sel:WORD_1
	v_cvt_pk_f32_fp8_e32 v[156:157], v119
	v_cvt_pk_f32_fp8_sdwa v[158:159], v119 src0_sel:WORD_1
	v_fmac_f32_e32 v0, v57, v144
	v_fmac_f32_e32 v1, v57, v145
	v_fmac_f32_e32 v2, v57, v146
	v_fmac_f32_e32 v3, v57, v147
	v_fmac_f32_e32 v4, v57, v148
	v_fmac_f32_e32 v5, v57, v149
	v_fmac_f32_e32 v6, v57, v150
	v_fmac_f32_e32 v7, v57, v151
	v_fmac_f32_e32 v8, v57, v152
	v_fmac_f32_e32 v9, v57, v153
	v_fmac_f32_e32 v10, v57, v154
	v_fmac_f32_e32 v11, v57, v155
	v_fmac_f32_e32 v12, v57, v156
	v_fmac_f32_e32 v13, v57, v157
	v_fmac_f32_e32 v14, v57, v158
	v_fmac_f32_e32 v15, v57, v159
	v_lshl_add_u32 v161, v41, 7, v160
	global_load_dwordx4 v[116:119], v161, s[14:15]
	s_waitcnt vmcnt(15)
	v_cvt_pk_f32_fp8_e32 v[144:145], v120
	v_cvt_pk_f32_fp8_sdwa v[146:147], v120 src0_sel:WORD_1
	v_cvt_pk_f32_fp8_e32 v[148:149], v121
	v_cvt_pk_f32_fp8_sdwa v[150:151], v121 src0_sel:WORD_1
	v_cvt_pk_f32_fp8_e32 v[152:153], v122
	v_cvt_pk_f32_fp8_sdwa v[154:155], v122 src0_sel:WORD_1
	v_cvt_pk_f32_fp8_e32 v[156:157], v123
	v_cvt_pk_f32_fp8_sdwa v[158:159], v123 src0_sel:WORD_1
	v_fmac_f32_e32 v0, v58, v144
	v_fmac_f32_e32 v1, v58, v145
	v_fmac_f32_e32 v2, v58, v146
	v_fmac_f32_e32 v3, v58, v147
	v_fmac_f32_e32 v4, v58, v148
	v_fmac_f32_e32 v5, v58, v149
	v_fmac_f32_e32 v6, v58, v150
	v_fmac_f32_e32 v7, v58, v151
	v_fmac_f32_e32 v8, v58, v152
	v_fmac_f32_e32 v9, v58, v153
	v_fmac_f32_e32 v10, v58, v154
	v_fmac_f32_e32 v11, v58, v155
	v_fmac_f32_e32 v12, v58, v156
	v_fmac_f32_e32 v13, v58, v157
	v_fmac_f32_e32 v14, v58, v158
	v_fmac_f32_e32 v15, v58, v159
	v_lshl_add_u32 v161, v42, 7, v160
	global_load_dwordx4 v[120:123], v161, s[14:15]
	s_waitcnt vmcnt(15)
; DI void phase_peer_b(const Params& p, int layer, const float* gnext, bool last) {
;     ...
; #pragma unroll
;       for (int j = 0; j < 16; ++j) {
;         const int e = bt * 16 + j;
;         const int eidx = __builtin_amdgcn_readlane(e < 64 ? i0 : i1, e & 63);
;         vr[j] = *(const u32x4*)(EV + (size_t)eidx * DM + lane * 16);
;       }
; #pragma unroll
;       for (int j = 0; j < 16; ++j) {
;         const int e = bt * 16 + j;
;         const float wj = __int_as_float(__builtin_amdgcn_readlane(__float_as_int(e < 64 ? w0 : w1), e & 63));
; #pragma unroll
;         for (int w = 0; w < 4; ++w) {
;           const f32x2 lo = __builtin_amdgcn_cvt_pk_f32_fp8((int)vr[j][w], false);
;           const f32x2 hi = __builtin_amdgcn_cvt_pk_f32_fp8((int)vr[j][w], true);
;           acc[4 * w] += wj * lo[0]; acc[4 * w + 1] += wj * lo[1]; acc[4 * w + 2] += wj * hi[0]; acc[4 * w + 3] += wj * hi[1];
;         }
	v_cvt_pk_f32_fp8_e32 v[144:145], v124
	v_cvt_pk_f32_fp8_sdwa v[146:147], v124 src0_sel:WORD_1
	v_cvt_pk_f32_fp8_e32 v[148:149], v125
	v_cvt_pk_f32_fp8_sdwa v[150:151], v125 src0_sel:WORD_1
	v_cvt_pk_f32_fp8_e32 v[152:153], v126
	v_cvt_pk_f32_fp8_sdwa v[154:155], v126 src0_sel:WORD_1
	v_cvt_pk_f32_fp8_e32 v[156:157], v127
	v_cvt_pk_f32_fp8_sdwa v[158:159], v127 src0_sel:WORD_1
	v_fmac_f32_e32 v0, v59, v144
	v_fmac_f32_e32 v1, v59, v145
	v_fmac_f32_e32 v2, v59, v146
	v_fmac_f32_e32 v3, v59, v147
	v_fmac_f32_e32 v4, v59, v148
	v_fmac_f32_e32 v5, v59, v149
	v_fmac_f32_e32 v6, v59, v150
	v_fmac_f32_e32 v7, v59, v151
	v_fmac_f32_e32 v8, v59, v152
	v_fmac_f32_e32 v9, v59, v153
	v_fmac_f32_e32 v10, v59, v154
	v_fmac_f32_e32 v11, v59, v155
	v_fmac_f32_e32 v12, v59, v156
	v_fmac_f32_e32 v13, v59, v157
	v_fmac_f32_e32 v14, v59, v158
	v_fmac_f32_e32 v15, v59, v159
	v_lshl_add_u32 v161, v43, 7, v160
	global_load_dwordx4 v[124:127], v161, s[14:15]
	s_waitcnt vmcnt(15)
	v_cvt_pk_f32_fp8_e32 v[144:145], v128
	v_cvt_pk_f32_fp8_sdwa v[146:147], v128 src0_sel:WORD_1
	v_cvt_pk_f32_fp8_e32 v[148:149], v129
	v_cvt_pk_f32_fp8_sdwa v[150:151], v129 src0_sel:WORD_1
	v_cvt_pk_f32_fp8_e32 v[152:153], v130
	v_cvt_pk_f32_fp8_sdwa v[154:155], v130 src0_sel:WORD_1
	v_cvt_pk_f32_fp8_e32 v[156:157], v131
	v_cvt_pk_f32_fp8_sdwa v[158:159], v131 src0_sel:WORD_1
	v_fmac_f32_e32 v0, v60, v144
	v_fmac_f32_e32 v1, v60, v145
	v_fmac_f32_e32 v2, v60, v146
	v_fmac_f32_e32 v3, v60, v147
	v_fmac_f32_e32 v4, v60, v148
	v_fmac_f32_e32 v5, v60, v149
	v_fmac_f32_e32 v6, v60, v150
	v_fmac_f32_e32 v7, v60, v151
	v_fmac_f32_e32 v8, v60, v152
	v_fmac_f32_e32 v9, v60, v153
	v_fmac_f32_e32 v10, v60, v154
	v_fmac_f32_e32 v11, v60, v155
	v_fmac_f32_e32 v12, v60, v156
	v_fmac_f32_e32 v13, v60, v157
	v_fmac_f32_e32 v14, v60, v158
	v_fmac_f32_e32 v15, v60, v159
	v_lshl_add_u32 v161, v44, 7, v160
	global_load_dwordx4 v[128:131], v161, s[14:15]
	s_waitcnt vmcnt(15)
	v_cvt_pk_f32_fp8_e32 v[144:145], v132
	v_cvt_pk_f32_fp8_sdwa v[146:147], v132 src0_sel:WORD_1
	v_cvt_pk_f32_fp8_e32 v[148:149], v133
	v_cvt_pk_f32_fp8_sdwa v[150:151], v133 src0_sel:WORD_1
	v_cvt_pk_f32_fp8_e32 v[152:153], v134
	v_cvt_pk_f32_fp8_sdwa v[154:155], v134 src0_sel:WORD_1
	v_cvt_pk_f32_fp8_e32 v[156:157], v135
	v_cvt_pk_f32_fp8_sdwa v[158:159], v135 src0_sel:WORD_1
	v_fmac_f32_e32 v0, v61, v144
	v_fmac_f32_e32 v1, v61, v145
	v_fmac_f32_e32 v2, v61, v146
	v_fmac_f32_e32 v3, v61, v147
	v_fmac_f32_e32 v4, v61, v148
	v_fmac_f32_e32 v5, v61, v149
	v_fmac_f32_e32 v6, v61, v150
	v_fmac_f32_e32 v7, v61, v151
	v_fmac_f32_e32 v8, v61, v152
	v_fmac_f32_e32 v9, v61, v153
	v_fmac_f32_e32 v10, v61, v154
	v_fmac_f32_e32 v11, v61, v155
	v_fmac_f32_e32 v12, v61, v156
	v_fmac_f32_e32 v13, v61, v157
	v_fmac_f32_e32 v14, v61, v158
	v_fmac_f32_e32 v15, v61, v159
	v_lshl_add_u32 v161, v45, 7, v160
	global_load_dwordx4 v[132:135], v161, s[14:15]
	s_waitcnt vmcnt(15)
	v_cvt_pk_f32_fp8_e32 v[144:145], v136
	v_cvt_pk_f32_fp8_sdwa v[146:147], v136 src0_sel:WORD_1
	v_cvt_pk_f32_fp8_e32 v[148:149], v137
	v_cvt_pk_f32_fp8_sdwa v[150:151], v137 src0_sel:WORD_1
	v_cvt_pk_f32_fp8_e32 v[152:153], v138
	v_cvt_pk_f32_fp8_sdwa v[154:155], v138 src0_sel:WORD_1
	v_cvt_pk_f32_fp8_e32 v[156:157], v139
	v_cvt_pk_f32_fp8_sdwa v[158:159], v139 src0_sel:WORD_1
	v_fmac_f32_e32 v0, v62, v144
	v_fmac_f32_e32 v1, v62, v145
	v_fmac_f32_e32 v2, v62, v146
	v_fmac_f32_e32 v3, v62, v147
	v_fmac_f32_e32 v4, v62, v148
	v_fmac_f32_e32 v5, v62, v149
	v_fmac_f32_e32 v6, v62, v150
	v_fmac_f32_e32 v7, v62, v151
	v_fmac_f32_e32 v8, v62, v152
	v_fmac_f32_e32 v9, v62, v153
	v_fmac_f32_e32 v10, v62, v154
	v_fmac_f32_e32 v11, v62, v155
	v_fmac_f32_e32 v12, v62, v156
	v_fmac_f32_e32 v13, v62, v157
	v_fmac_f32_e32 v14, v62, v158
	v_fmac_f32_e32 v15, v62, v159
	v_lshl_add_u32 v161, v46, 7, v160
	global_load_dwordx4 v[136:139], v161, s[14:15]
	s_waitcnt vmcnt(15)
	v_cvt_pk_f32_fp8_e32 v[144:145], v140
	v_cvt_pk_f32_fp8_sdwa v[146:147], v140 src0_sel:WORD_1
	v_cvt_pk_f32_fp8_e32 v[148:149], v141
	v_cvt_pk_f32_fp8_sdwa v[150:151], v141 src0_sel:WORD_1
	v_cvt_pk_f32_fp8_e32 v[152:153], v142
	v_cvt_pk_f32_fp8_sdwa v[154:155], v142 src0_sel:WORD_1
	v_cvt_pk_f32_fp8_e32 v[156:157], v143
	v_cvt_pk_f32_fp8_sdwa v[158:159], v143 src0_sel:WORD_1
	v_fmac_f32_e32 v0, v63, v144
	v_fmac_f32_e32 v1, v63, v145
	v_fmac_f32_e32 v2, v63, v146
	v_fmac_f32_e32 v3, v63, v147
	v_fmac_f32_e32 v4, v63, v148
	v_fmac_f32_e32 v5, v63, v149
	v_fmac_f32_e32 v6, v63, v150
	v_fmac_f32_e32 v7, v63, v151
	v_fmac_f32_e32 v8, v63, v152
	v_fmac_f32_e32 v9, v63, v153
	v_fmac_f32_e32 v10, v63, v154
	v_fmac_f32_e32 v11, v63, v155
	v_fmac_f32_e32 v12, v63, v156
	v_fmac_f32_e32 v13, v63, v157
	v_fmac_f32_e32 v14, v63, v158
	v_fmac_f32_e32 v15, v63, v159
	v_lshl_add_u32 v161, v47, 7, v160
	global_load_dwordx4 v[140:143], v161, s[14:15]
	s_waitcnt lgkmcnt(0)
	ds_read_b128 v[32:35], v163 offset:448
	ds_read_b128 v[36:39], v163 offset:464
	ds_read_b128 v[40:43], v163 offset:480
	ds_read_b128 v[44:47], v163 offset:496
	ds_read_b128 v[48:51], v163 offset:896
	ds_read_b128 v[52:55], v163 offset:912
	ds_read_b128 v[56:59], v163 offset:928
	ds_read_b128 v[60:63], v163 offset:944
	s_waitcnt vmcnt(15)
; DI void phase_peer_b(const Params& p, int layer, const float* gnext, bool last) {
;     ...
; #pragma unroll
;       for (int j = 0; j < 16; ++j) {
;         const int e = bt * 16 + j;
;         const int eidx = __builtin_amdgcn_readlane(e < 64 ? i0 : i1, e & 63);
;         vr[j] = *(const u32x4*)(EV + (size_t)eidx * DM + lane * 16);
;       }
; #pragma unroll
;       for (int j = 0; j < 16; ++j) {
;         const int e = bt * 16 + j;
;         const float wj = __int_as_float(__builtin_amdgcn_readlane(__float_as_int(e < 64 ? w0 : w1), e & 63));
; #pragma unroll
;         for (int w = 0; w < 4; ++w) {
;           const f32x2 lo = __builtin_amdgcn_cvt_pk_f32_fp8((int)vr[j][w], false);
;           const f32x2 hi = __builtin_amdgcn_cvt_pk_f32_fp8((int)vr[j][w], true);
;           acc[4 * w] += wj * lo[0]; acc[4 * w + 1] += wj * lo[1]; acc[4 * w + 2] += wj * hi[0]; acc[4 * w + 3] += wj * hi[1];
;         }
	v_cvt_pk_f32_fp8_e32 v[144:145], v80
	v_cvt_pk_f32_fp8_sdwa v[146:147], v80 src0_sel:WORD_1
	v_cvt_pk_f32_fp8_e32 v[148:149], v81
	v_cvt_pk_f32_fp8_sdwa v[150:151], v81 src0_sel:WORD_1
	v_cvt_pk_f32_fp8_e32 v[152:153], v82
	v_cvt_pk_f32_fp8_sdwa v[154:155], v82 src0_sel:WORD_1
	v_cvt_pk_f32_fp8_e32 v[156:157], v83
	v_cvt_pk_f32_fp8_sdwa v[158:159], v83 src0_sel:WORD_1
	v_fmac_f32_e32 v0, v64, v144
	v_fmac_f32_e32 v1, v64, v145
	v_fmac_f32_e32 v2, v64, v146
	v_fmac_f32_e32 v3, v64, v147
	v_fmac_f32_e32 v4, v64, v148
	v_fmac_f32_e32 v5, v64, v149
	v_fmac_f32_e32 v6, v64, v150
	v_fmac_f32_e32 v7, v64, v151
	v_fmac_f32_e32 v8, v64, v152
	v_fmac_f32_e32 v9, v64, v153
	v_fmac_f32_e32 v10, v64, v154
	v_fmac_f32_e32 v11, v64, v155
	v_fmac_f32_e32 v12, v64, v156
	v_fmac_f32_e32 v13, v64, v157
	v_fmac_f32_e32 v14, v64, v158
	v_fmac_f32_e32 v15, v64, v159
	v_lshl_add_u32 v161, v16, 7, v160
	global_load_dwordx4 v[80:83], v161, s[14:15]
	s_waitcnt vmcnt(15)
	v_cvt_pk_f32_fp8_e32 v[144:145], v84
	v_cvt_pk_f32_fp8_sdwa v[146:147], v84 src0_sel:WORD_1
	v_cvt_pk_f32_fp8_e32 v[148:149], v85
	v_cvt_pk_f32_fp8_sdwa v[150:151], v85 src0_sel:WORD_1
	v_cvt_pk_f32_fp8_e32 v[152:153], v86
	v_cvt_pk_f32_fp8_sdwa v[154:155], v86 src0_sel:WORD_1
	v_cvt_pk_f32_fp8_e32 v[156:157], v87
	v_cvt_pk_f32_fp8_sdwa v[158:159], v87 src0_sel:WORD_1
	v_fmac_f32_e32 v0, v65, v144
	v_fmac_f32_e32 v1, v65, v145
	v_fmac_f32_e32 v2, v65, v146
	v_fmac_f32_e32 v3, v65, v147
	v_fmac_f32_e32 v4, v65, v148
	v_fmac_f32_e32 v5, v65, v149
	v_fmac_f32_e32 v6, v65, v150
	v_fmac_f32_e32 v7, v65, v151
	v_fmac_f32_e32 v8, v65, v152
	v_fmac_f32_e32 v9, v65, v153
	v_fmac_f32_e32 v10, v65, v154
	v_fmac_f32_e32 v11, v65, v155
	v_fmac_f32_e32 v12, v65, v156
	v_fmac_f32_e32 v13, v65, v157
	v_fmac_f32_e32 v14, v65, v158
	v_fmac_f32_e32 v15, v65, v159
	v_lshl_add_u32 v161, v17, 7, v160
	global_load_dwordx4 v[84:87], v161, s[14:15]
	s_waitcnt vmcnt(15)
	v_cvt_pk_f32_fp8_e32 v[144:145], v88
	v_cvt_pk_f32_fp8_sdwa v[146:147], v88 src0_sel:WORD_1
	v_cvt_pk_f32_fp8_e32 v[148:149], v89
	v_cvt_pk_f32_fp8_sdwa v[150:151], v89 src0_sel:WORD_1
	v_cvt_pk_f32_fp8_e32 v[152:153], v90
	v_cvt_pk_f32_fp8_sdwa v[154:155], v90 src0_sel:WORD_1
	v_cvt_pk_f32_fp8_e32 v[156:157], v91
	v_cvt_pk_f32_fp8_sdwa v[158:159], v91 src0_sel:WORD_1
	v_fmac_f32_e32 v0, v66, v144
	v_fmac_f32_e32 v1, v66, v145
	v_fmac_f32_e32 v2, v66, v146
	v_fmac_f32_e32 v3, v66, v147
	v_fmac_f32_e32 v4, v66, v148
	v_fmac_f32_e32 v5, v66, v149
	v_fmac_f32_e32 v6, v66, v150
	v_fmac_f32_e32 v7, v66, v151
	v_fmac_f32_e32 v8, v66, v152
	v_fmac_f32_e32 v9, v66, v153
	v_fmac_f32_e32 v10, v66, v154
	v_fmac_f32_e32 v11, v66, v155
	v_fmac_f32_e32 v12, v66, v156
	v_fmac_f32_e32 v13, v66, v157
	v_fmac_f32_e32 v14, v66, v158
	v_fmac_f32_e32 v15, v66, v159
	v_lshl_add_u32 v161, v18, 7, v160
	global_load_dwordx4 v[88:91], v161, s[14:15]
	s_waitcnt vmcnt(15)
	v_cvt_pk_f32_fp8_e32 v[144:145], v92
	v_cvt_pk_f32_fp8_sdwa v[146:147], v92 src0_sel:WORD_1
	v_cvt_pk_f32_fp8_e32 v[148:149], v93
	v_cvt_pk_f32_fp8_sdwa v[150:151], v93 src0_sel:WORD_1
	v_cvt_pk_f32_fp8_e32 v[152:153], v94
	v_cvt_pk_f32_fp8_sdwa v[154:155], v94 src0_sel:WORD_1
	v_cvt_pk_f32_fp8_e32 v[156:157], v95
	v_cvt_pk_f32_fp8_sdwa v[158:159], v95 src0_sel:WORD_1
	v_fmac_f32_e32 v0, v67, v144
	v_fmac_f32_e32 v1, v67, v145
	v_fmac_f32_e32 v2, v67, v146
	v_fmac_f32_e32 v3, v67, v147
	v_fmac_f32_e32 v4, v67, v148
	v_fmac_f32_e32 v5, v67, v149
	v_fmac_f32_e32 v6, v67, v150
	v_fmac_f32_e32 v7, v67, v151
	v_fmac_f32_e32 v8, v67, v152
	v_fmac_f32_e32 v9, v67, v153
	v_fmac_f32_e32 v10, v67, v154
	v_fmac_f32_e32 v11, v67, v155
	v_fmac_f32_e32 v12, v67, v156
	v_fmac_f32_e32 v13, v67, v157
	v_fmac_f32_e32 v14, v67, v158
	v_fmac_f32_e32 v15, v67, v159
	v_lshl_add_u32 v161, v19, 7, v160
	global_load_dwordx4 v[92:95], v161, s[14:15]
	s_waitcnt vmcnt(15)
	v_cvt_pk_f32_fp8_e32 v[144:145], v96
	v_cvt_pk_f32_fp8_sdwa v[146:147], v96 src0_sel:WORD_1
	v_cvt_pk_f32_fp8_e32 v[148:149], v97
	v_cvt_pk_f32_fp8_sdwa v[150:151], v97 src0_sel:WORD_1
	v_cvt_pk_f32_fp8_e32 v[152:153], v98
	v_cvt_pk_f32_fp8_sdwa v[154:155], v98 src0_sel:WORD_1
	v_cvt_pk_f32_fp8_e32 v[156:157], v99
	v_cvt_pk_f32_fp8_sdwa v[158:159], v99 src0_sel:WORD_1
	v_fmac_f32_e32 v0, v68, v144
	v_fmac_f32_e32 v1, v68, v145
	v_fmac_f32_e32 v2, v68, v146
	v_fmac_f32_e32 v3, v68, v147
	v_fmac_f32_e32 v4, v68, v148
	v_fmac_f32_e32 v5, v68, v149
	v_fmac_f32_e32 v6, v68, v150
	v_fmac_f32_e32 v7, v68, v151
	v_fmac_f32_e32 v8, v68, v152
	v_fmac_f32_e32 v9, v68, v153
	v_fmac_f32_e32 v10, v68, v154
	v_fmac_f32_e32 v11, v68, v155
	v_fmac_f32_e32 v12, v68, v156
	v_fmac_f32_e32 v13, v68, v157
	v_fmac_f32_e32 v14, v68, v158
	v_fmac_f32_e32 v15, v68, v159
	v_lshl_add_u32 v161, v20, 7, v160
	global_load_dwordx4 v[96:99], v161, s[14:15]
	s_waitcnt vmcnt(15)
	v_cvt_pk_f32_fp8_e32 v[144:145], v100
	v_cvt_pk_f32_fp8_sdwa v[146:147], v100 src0_sel:WORD_1
	v_cvt_pk_f32_fp8_e32 v[148:149], v101
	v_cvt_pk_f32_fp8_sdwa v[150:151], v101 src0_sel:WORD_1
	v_cvt_pk_f32_fp8_e32 v[152:153], v102
	v_cvt_pk_f32_fp8_sdwa v[154:155], v102 src0_sel:WORD_1
	v_cvt_pk_f32_fp8_e32 v[156:157], v103
	v_cvt_pk_f32_fp8_sdwa v[158:159], v103 src0_sel:WORD_1
	v_fmac_f32_e32 v0, v69, v144
	v_fmac_f32_e32 v1, v69, v145
	v_fmac_f32_e32 v2, v69, v146
	v_fmac_f32_e32 v3, v69, v147
	v_fmac_f32_e32 v4, v69, v148
	v_fmac_f32_e32 v5, v69, v149
	v_fmac_f32_e32 v6, v69, v150
	v_fmac_f32_e32 v7, v69, v151
	v_fmac_f32_e32 v8, v69, v152
	v_fmac_f32_e32 v9, v69, v153
	v_fmac_f32_e32 v10, v69, v154
	v_fmac_f32_e32 v11, v69, v155
	v_fmac_f32_e32 v12, v69, v156
	v_fmac_f32_e32 v13, v69, v157
	v_fmac_f32_e32 v14, v69, v158
	v_fmac_f32_e32 v15, v69, v159
	v_lshl_add_u32 v161, v21, 7, v160
	global_load_dwordx4 v[100:103], v161, s[14:15]
	s_waitcnt vmcnt(15)
; DI void phase_peer_b(const Params& p, int layer, const float* gnext, bool last) {
;     ...
; #pragma unroll
;       for (int j = 0; j < 16; ++j) {
;         const int e = bt * 16 + j;
;         const int eidx = __builtin_amdgcn_readlane(e < 64 ? i0 : i1, e & 63);
;         vr[j] = *(const u32x4*)(EV + (size_t)eidx * DM + lane * 16);
;       }
; #pragma unroll
;       for (int j = 0; j < 16; ++j) {
;         const int e = bt * 16 + j;
;         const float wj = __int_as_float(__builtin_amdgcn_readlane(__float_as_int(e < 64 ? w0 : w1), e & 63));
; #pragma unroll
;         for (int w = 0; w < 4; ++w) {
;           const f32x2 lo = __builtin_amdgcn_cvt_pk_f32_fp8((int)vr[j][w], false);
;           const f32x2 hi = __builtin_amdgcn_cvt_pk_f32_fp8((int)vr[j][w], true);
;           acc[4 * w] += wj * lo[0]; acc[4 * w + 1] += wj * lo[1]; acc[4 * w + 2] += wj * hi[0]; acc[4 * w + 3] += wj * hi[1];
;         }
	v_cvt_pk_f32_fp8_e32 v[144:145], v104
	v_cvt_pk_f32_fp8_sdwa v[146:147], v104 src0_sel:WORD_1
	v_cvt_pk_f32_fp8_e32 v[148:149], v105
	v_cvt_pk_f32_fp8_sdwa v[150:151], v105 src0_sel:WORD_1
	v_cvt_pk_f32_fp8_e32 v[152:153], v106
	v_cvt_pk_f32_fp8_sdwa v[154:155], v106 src0_sel:WORD_1
	v_cvt_pk_f32_fp8_e32 v[156:157], v107
	v_cvt_pk_f32_fp8_sdwa v[158:159], v107 src0_sel:WORD_1
	v_fmac_f32_e32 v0, v70, v144
	v_fmac_f32_e32 v1, v70, v145
	v_fmac_f32_e32 v2, v70, v146
	v_fmac_f32_e32 v3, v70, v147
	v_fmac_f32_e32 v4, v70, v148
	v_fmac_f32_e32 v5, v70, v149
	v_fmac_f32_e32 v6, v70, v150
	v_fmac_f32_e32 v7, v70, v151
	v_fmac_f32_e32 v8, v70, v152
	v_fmac_f32_e32 v9, v70, v153
	v_fmac_f32_e32 v10, v70, v154
	v_fmac_f32_e32 v11, v70, v155
	v_fmac_f32_e32 v12, v70, v156
	v_fmac_f32_e32 v13, v70, v157
	v_fmac_f32_e32 v14, v70, v158
	v_fmac_f32_e32 v15, v70, v159
	v_lshl_add_u32 v161, v22, 7, v160
	global_load_dwordx4 v[104:107], v161, s[14:15]
	s_waitcnt vmcnt(15)
	v_cvt_pk_f32_fp8_e32 v[144:145], v108
	v_cvt_pk_f32_fp8_sdwa v[146:147], v108 src0_sel:WORD_1
	v_cvt_pk_f32_fp8_e32 v[148:149], v109
	v_cvt_pk_f32_fp8_sdwa v[150:151], v109 src0_sel:WORD_1
	v_cvt_pk_f32_fp8_e32 v[152:153], v110
	v_cvt_pk_f32_fp8_sdwa v[154:155], v110 src0_sel:WORD_1
	v_cvt_pk_f32_fp8_e32 v[156:157], v111
	v_cvt_pk_f32_fp8_sdwa v[158:159], v111 src0_sel:WORD_1
	v_fmac_f32_e32 v0, v71, v144
	v_fmac_f32_e32 v1, v71, v145
	v_fmac_f32_e32 v2, v71, v146
	v_fmac_f32_e32 v3, v71, v147
	v_fmac_f32_e32 v4, v71, v148
	v_fmac_f32_e32 v5, v71, v149
	v_fmac_f32_e32 v6, v71, v150
	v_fmac_f32_e32 v7, v71, v151
	v_fmac_f32_e32 v8, v71, v152
	v_fmac_f32_e32 v9, v71, v153
	v_fmac_f32_e32 v10, v71, v154
	v_fmac_f32_e32 v11, v71, v155
	v_fmac_f32_e32 v12, v71, v156
	v_fmac_f32_e32 v13, v71, v157
	v_fmac_f32_e32 v14, v71, v158
	v_fmac_f32_e32 v15, v71, v159
	v_lshl_add_u32 v161, v23, 7, v160
	global_load_dwordx4 v[108:111], v161, s[14:15]
	s_waitcnt vmcnt(15)
	v_cvt_pk_f32_fp8_e32 v[144:145], v112
	v_cvt_pk_f32_fp8_sdwa v[146:147], v112 src0_sel:WORD_1
	v_cvt_pk_f32_fp8_e32 v[148:149], v113
	v_cvt_pk_f32_fp8_sdwa v[150:151], v113 src0_sel:WORD_1
	v_cvt_pk_f32_fp8_e32 v[152:153], v114
	v_cvt_pk_f32_fp8_sdwa v[154:155], v114 src0_sel:WORD_1
	v_cvt_pk_f32_fp8_e32 v[156:157], v115
	v_cvt_pk_f32_fp8_sdwa v[158:159], v115 src0_sel:WORD_1
	v_fmac_f32_e32 v0, v72, v144
	v_fmac_f32_e32 v1, v72, v145
	v_fmac_f32_e32 v2, v72, v146
	v_fmac_f32_e32 v3, v72, v147
	v_fmac_f32_e32 v4, v72, v148
	v_fmac_f32_e32 v5, v72, v149
	v_fmac_f32_e32 v6, v72, v150
	v_fmac_f32_e32 v7, v72, v151
	v_fmac_f32_e32 v8, v72, v152
	v_fmac_f32_e32 v9, v72, v153
	v_fmac_f32_e32 v10, v72, v154
	v_fmac_f32_e32 v11, v72, v155
	v_fmac_f32_e32 v12, v72, v156
	v_fmac_f32_e32 v13, v72, v157
	v_fmac_f32_e32 v14, v72, v158
	v_fmac_f32_e32 v15, v72, v159
	v_lshl_add_u32 v161, v24, 7, v160
	global_load_dwordx4 v[112:115], v161, s[14:15]
	s_waitcnt vmcnt(15)
	v_cvt_pk_f32_fp8_e32 v[144:145], v116
	v_cvt_pk_f32_fp8_sdwa v[146:147], v116 src0_sel:WORD_1
	v_cvt_pk_f32_fp8_e32 v[148:149], v117
	v_cvt_pk_f32_fp8_sdwa v[150:151], v117 src0_sel:WORD_1
	v_cvt_pk_f32_fp8_e32 v[152:153], v118
	v_cvt_pk_f32_fp8_sdwa v[154:155], v118 src0_sel:WORD_1
	v_cvt_pk_f32_fp8_e32 v[156:157], v119
	v_cvt_pk_f32_fp8_sdwa v[158:159], v119 src0_sel:WORD_1
	v_fmac_f32_e32 v0, v73, v144
	v_fmac_f32_e32 v1, v73, v145
	v_fmac_f32_e32 v2, v73, v146
	v_fmac_f32_e32 v3, v73, v147
	v_fmac_f32_e32 v4, v73, v148
	v_fmac_f32_e32 v5, v73, v149
	v_fmac_f32_e32 v6, v73, v150
	v_fmac_f32_e32 v7, v73, v151
	v_fmac_f32_e32 v8, v73, v152
	v_fmac_f32_e32 v9, v73, v153
	v_fmac_f32_e32 v10, v73, v154
	v_fmac_f32_e32 v11, v73, v155
	v_fmac_f32_e32 v12, v73, v156
	v_fmac_f32_e32 v13, v73, v157
	v_fmac_f32_e32 v14, v73, v158
	v_fmac_f32_e32 v15, v73, v159
	v_lshl_add_u32 v161, v25, 7, v160
	global_load_dwordx4 v[116:119], v161, s[14:15]
	s_waitcnt vmcnt(15)
	v_cvt_pk_f32_fp8_e32 v[144:145], v120
	v_cvt_pk_f32_fp8_sdwa v[146:147], v120 src0_sel:WORD_1
	v_cvt_pk_f32_fp8_e32 v[148:149], v121
	v_cvt_pk_f32_fp8_sdwa v[150:151], v121 src0_sel:WORD_1
	v_cvt_pk_f32_fp8_e32 v[152:153], v122
	v_cvt_pk_f32_fp8_sdwa v[154:155], v122 src0_sel:WORD_1
	v_cvt_pk_f32_fp8_e32 v[156:157], v123
	v_cvt_pk_f32_fp8_sdwa v[158:159], v123 src0_sel:WORD_1
	v_fmac_f32_e32 v0, v74, v144
	v_fmac_f32_e32 v1, v74, v145
	v_fmac_f32_e32 v2, v74, v146
	v_fmac_f32_e32 v3, v74, v147
	v_fmac_f32_e32 v4, v74, v148
	v_fmac_f32_e32 v5, v74, v149
	v_fmac_f32_e32 v6, v74, v150
	v_fmac_f32_e32 v7, v74, v151
	v_fmac_f32_e32 v8, v74, v152
	v_fmac_f32_e32 v9, v74, v153
	v_fmac_f32_e32 v10, v74, v154
	v_fmac_f32_e32 v11, v74, v155
	v_fmac_f32_e32 v12, v74, v156
	v_fmac_f32_e32 v13, v74, v157
	v_fmac_f32_e32 v14, v74, v158
	v_fmac_f32_e32 v15, v74, v159
	v_lshl_add_u32 v161, v26, 7, v160
	global_load_dwordx4 v[120:123], v161, s[14:15]
	s_waitcnt vmcnt(15)
	v_cvt_pk_f32_fp8_e32 v[144:145], v124
	v_cvt_pk_f32_fp8_sdwa v[146:147], v124 src0_sel:WORD_1
	v_cvt_pk_f32_fp8_e32 v[148:149], v125
	v_cvt_pk_f32_fp8_sdwa v[150:151], v125 src0_sel:WORD_1
	v_cvt_pk_f32_fp8_e32 v[152:153], v126
	v_cvt_pk_f32_fp8_sdwa v[154:155], v126 src0_sel:WORD_1
	v_cvt_pk_f32_fp8_e32 v[156:157], v127
	v_cvt_pk_f32_fp8_sdwa v[158:159], v127 src0_sel:WORD_1
	v_fmac_f32_e32 v0, v75, v144
	v_fmac_f32_e32 v1, v75, v145
	v_fmac_f32_e32 v2, v75, v146
	v_fmac_f32_e32 v3, v75, v147
	v_fmac_f32_e32 v4, v75, v148
	v_fmac_f32_e32 v5, v75, v149
	v_fmac_f32_e32 v6, v75, v150
	v_fmac_f32_e32 v7, v75, v151
	v_fmac_f32_e32 v8, v75, v152
	v_fmac_f32_e32 v9, v75, v153
	v_fmac_f32_e32 v10, v75, v154
	v_fmac_f32_e32 v11, v75, v155
	v_fmac_f32_e32 v12, v75, v156
	v_fmac_f32_e32 v13, v75, v157
	v_fmac_f32_e32 v14, v75, v158
	v_fmac_f32_e32 v15, v75, v159
	v_lshl_add_u32 v161, v27, 7, v160
	global_load_dwordx4 v[124:127], v161, s[14:15]
	s_waitcnt vmcnt(15)
; DI void phase_peer_b(const Params& p, int layer, const float* gnext, bool last) {
;     ...
; #pragma unroll
;       for (int j = 0; j < 16; ++j) {
;         const int e = bt * 16 + j;
;         const int eidx = __builtin_amdgcn_readlane(e < 64 ? i0 : i1, e & 63);
;         vr[j] = *(const u32x4*)(EV + (size_t)eidx * DM + lane * 16);
;       }
; #pragma unroll
;       for (int j = 0; j < 16; ++j) {
;         const int e = bt * 16 + j;
;         const float wj = __int_as_float(__builtin_amdgcn_readlane(__float_as_int(e < 64 ? w0 : w1), e & 63));
; #pragma unroll
;         for (int w = 0; w < 4; ++w) {
;           const f32x2 lo = __builtin_amdgcn_cvt_pk_f32_fp8((int)vr[j][w], false);
;           const f32x2 hi = __builtin_amdgcn_cvt_pk_f32_fp8((int)vr[j][w], true);
;           acc[4 * w] += wj * lo[0]; acc[4 * w + 1] += wj * lo[1]; acc[4 * w + 2] += wj * hi[0]; acc[4 * w + 3] += wj * hi[1];
;         }
	v_cvt_pk_f32_fp8_e32 v[144:145], v128
	v_cvt_pk_f32_fp8_sdwa v[146:147], v128 src0_sel:WORD_1
	v_cvt_pk_f32_fp8_e32 v[148:149], v129
	v_cvt_pk_f32_fp8_sdwa v[150:151], v129 src0_sel:WORD_1
	v_cvt_pk_f32_fp8_e32 v[152:153], v130
	v_cvt_pk_f32_fp8_sdwa v[154:155], v130 src0_sel:WORD_1
	v_cvt_pk_f32_fp8_e32 v[156:157], v131
	v_cvt_pk_f32_fp8_sdwa v[158:159], v131 src0_sel:WORD_1
	v_fmac_f32_e32 v0, v76, v144
	v_fmac_f32_e32 v1, v76, v145
	v_fmac_f32_e32 v2, v76, v146
	v_fmac_f32_e32 v3, v76, v147
	v_fmac_f32_e32 v4, v76, v148
	v_fmac_f32_e32 v5, v76, v149
	v_fmac_f32_e32 v6, v76, v150
	v_fmac_f32_e32 v7, v76, v151
	v_fmac_f32_e32 v8, v76, v152
	v_fmac_f32_e32 v9, v76, v153
	v_fmac_f32_e32 v10, v76, v154
	v_fmac_f32_e32 v11, v76, v155
	v_fmac_f32_e32 v12, v76, v156
	v_fmac_f32_e32 v13, v76, v157
	v_fmac_f32_e32 v14, v76, v158
	v_fmac_f32_e32 v15, v76, v159
	v_lshl_add_u32 v161, v28, 7, v160
	global_load_dwordx4 v[128:131], v161, s[14:15]
	s_waitcnt vmcnt(15)
	v_cvt_pk_f32_fp8_e32 v[144:145], v132
	v_cvt_pk_f32_fp8_sdwa v[146:147], v132 src0_sel:WORD_1
	v_cvt_pk_f32_fp8_e32 v[148:149], v133
	v_cvt_pk_f32_fp8_sdwa v[150:151], v133 src0_sel:WORD_1
	v_cvt_pk_f32_fp8_e32 v[152:153], v134
	v_cvt_pk_f32_fp8_sdwa v[154:155], v134 src0_sel:WORD_1
	v_cvt_pk_f32_fp8_e32 v[156:157], v135
	v_cvt_pk_f32_fp8_sdwa v[158:159], v135 src0_sel:WORD_1
	v_fmac_f32_e32 v0, v77, v144
	v_fmac_f32_e32 v1, v77, v145
	v_fmac_f32_e32 v2, v77, v146
	v_fmac_f32_e32 v3, v77, v147
	v_fmac_f32_e32 v4, v77, v148
	v_fmac_f32_e32 v5, v77, v149
	v_fmac_f32_e32 v6, v77, v150
	v_fmac_f32_e32 v7, v77, v151
	v_fmac_f32_e32 v8, v77, v152
	v_fmac_f32_e32 v9, v77, v153
	v_fmac_f32_e32 v10, v77, v154
	v_fmac_f32_e32 v11, v77, v155
	v_fmac_f32_e32 v12, v77, v156
	v_fmac_f32_e32 v13, v77, v157
	v_fmac_f32_e32 v14, v77, v158
	v_fmac_f32_e32 v15, v77, v159
	v_lshl_add_u32 v161, v29, 7, v160
	global_load_dwordx4 v[132:135], v161, s[14:15]
	s_waitcnt vmcnt(15)
	v_cvt_pk_f32_fp8_e32 v[144:145], v136
	v_cvt_pk_f32_fp8_sdwa v[146:147], v136 src0_sel:WORD_1
	v_cvt_pk_f32_fp8_e32 v[148:149], v137
	v_cvt_pk_f32_fp8_sdwa v[150:151], v137 src0_sel:WORD_1
	v_cvt_pk_f32_fp8_e32 v[152:153], v138
	v_cvt_pk_f32_fp8_sdwa v[154:155], v138 src0_sel:WORD_1
	v_cvt_pk_f32_fp8_e32 v[156:157], v139
	v_cvt_pk_f32_fp8_sdwa v[158:159], v139 src0_sel:WORD_1
	v_fmac_f32_e32 v0, v78, v144
	v_fmac_f32_e32 v1, v78, v145
	v_fmac_f32_e32 v2, v78, v146
	v_fmac_f32_e32 v3, v78, v147
	v_fmac_f32_e32 v4, v78, v148
	v_fmac_f32_e32 v5, v78, v149
	v_fmac_f32_e32 v6, v78, v150
	v_fmac_f32_e32 v7, v78, v151
	v_fmac_f32_e32 v8, v78, v152
	v_fmac_f32_e32 v9, v78, v153
	v_fmac_f32_e32 v10, v78, v154
	v_fmac_f32_e32 v11, v78, v155
	v_fmac_f32_e32 v12, v78, v156
	v_fmac_f32_e32 v13, v78, v157
	v_fmac_f32_e32 v14, v78, v158
	v_fmac_f32_e32 v15, v78, v159
	v_lshl_add_u32 v161, v30, 7, v160
	global_load_dwordx4 v[136:139], v161, s[14:15]
	s_waitcnt vmcnt(15)
	v_cvt_pk_f32_fp8_e32 v[144:145], v140
	v_cvt_pk_f32_fp8_sdwa v[146:147], v140 src0_sel:WORD_1
	v_cvt_pk_f32_fp8_e32 v[148:149], v141
	v_cvt_pk_f32_fp8_sdwa v[150:151], v141 src0_sel:WORD_1
	v_cvt_pk_f32_fp8_e32 v[152:153], v142
	v_cvt_pk_f32_fp8_sdwa v[154:155], v142 src0_sel:WORD_1
	v_cvt_pk_f32_fp8_e32 v[156:157], v143
	v_cvt_pk_f32_fp8_sdwa v[158:159], v143 src0_sel:WORD_1
	v_fmac_f32_e32 v0, v79, v144
	v_fmac_f32_e32 v1, v79, v145
	v_fmac_f32_e32 v2, v79, v146
	v_fmac_f32_e32 v3, v79, v147
	v_fmac_f32_e32 v4, v79, v148
	v_fmac_f32_e32 v5, v79, v149
	v_fmac_f32_e32 v6, v79, v150
	v_fmac_f32_e32 v7, v79, v151
	v_fmac_f32_e32 v8, v79, v152
	v_fmac_f32_e32 v9, v79, v153
	v_fmac_f32_e32 v10, v79, v154
	v_fmac_f32_e32 v11, v79, v155
	v_fmac_f32_e32 v12, v79, v156
	v_fmac_f32_e32 v13, v79, v157
	v_fmac_f32_e32 v14, v79, v158
	v_fmac_f32_e32 v15, v79, v159
	v_lshl_add_u32 v161, v31, 7, v160
	global_load_dwordx4 v[140:143], v161, s[14:15]
	s_waitcnt lgkmcnt(0)
	ds_read_b128 v[64:67], v163 offset:960
	ds_read_b128 v[68:71], v163 offset:976
	ds_read_b128 v[72:75], v163 offset:992
	ds_read_b128 v[76:79], v163 offset:1008
	s_waitcnt vmcnt(15)
	v_cvt_pk_f32_fp8_e32 v[144:145], v80
	v_cvt_pk_f32_fp8_sdwa v[146:147], v80 src0_sel:WORD_1
	v_cvt_pk_f32_fp8_e32 v[148:149], v81
	v_cvt_pk_f32_fp8_sdwa v[150:151], v81 src0_sel:WORD_1
	v_cvt_pk_f32_fp8_e32 v[152:153], v82
	v_cvt_pk_f32_fp8_sdwa v[154:155], v82 src0_sel:WORD_1
	v_cvt_pk_f32_fp8_e32 v[156:157], v83
	v_cvt_pk_f32_fp8_sdwa v[158:159], v83 src0_sel:WORD_1
	v_fmac_f32_e32 v0, v48, v144
	v_fmac_f32_e32 v1, v48, v145
	v_fmac_f32_e32 v2, v48, v146
	v_fmac_f32_e32 v3, v48, v147
	v_fmac_f32_e32 v4, v48, v148
	v_fmac_f32_e32 v5, v48, v149
	v_fmac_f32_e32 v6, v48, v150
	v_fmac_f32_e32 v7, v48, v151
	v_fmac_f32_e32 v8, v48, v152
	v_fmac_f32_e32 v9, v48, v153
	v_fmac_f32_e32 v10, v48, v154
	v_fmac_f32_e32 v11, v48, v155
	v_fmac_f32_e32 v12, v48, v156
	v_fmac_f32_e32 v13, v48, v157
	v_fmac_f32_e32 v14, v48, v158
	v_fmac_f32_e32 v15, v48, v159
	v_lshl_add_u32 v161, v32, 7, v160
	global_load_dwordx4 v[80:83], v161, s[14:15]
	s_waitcnt vmcnt(15)
	v_cvt_pk_f32_fp8_e32 v[144:145], v84
	v_cvt_pk_f32_fp8_sdwa v[146:147], v84 src0_sel:WORD_1
	v_cvt_pk_f32_fp8_e32 v[148:149], v85
	v_cvt_pk_f32_fp8_sdwa v[150:151], v85 src0_sel:WORD_1
	v_cvt_pk_f32_fp8_e32 v[152:153], v86
	v_cvt_pk_f32_fp8_sdwa v[154:155], v86 src0_sel:WORD_1
	v_cvt_pk_f32_fp8_e32 v[156:157], v87
	v_cvt_pk_f32_fp8_sdwa v[158:159], v87 src0_sel:WORD_1
	v_fmac_f32_e32 v0, v49, v144
	v_fmac_f32_e32 v1, v49, v145
	v_fmac_f32_e32 v2, v49, v146
	v_fmac_f32_e32 v3, v49, v147
	v_fmac_f32_e32 v4, v49, v148
	v_fmac_f32_e32 v5, v49, v149
	v_fmac_f32_e32 v6, v49, v150
	v_fmac_f32_e32 v7, v49, v151
	v_fmac_f32_e32 v8, v49, v152
	v_fmac_f32_e32 v9, v49, v153
	v_fmac_f32_e32 v10, v49, v154
	v_fmac_f32_e32 v11, v49, v155
	v_fmac_f32_e32 v12, v49, v156
	v_fmac_f32_e32 v13, v49, v157
	v_fmac_f32_e32 v14, v49, v158
	v_fmac_f32_e32 v15, v49, v159
	v_lshl_add_u32 v161, v33, 7, v160
	global_load_dwordx4 v[84:87], v161, s[14:15]
	s_waitcnt vmcnt(15)
; DI void phase_peer_b(const Params& p, int layer, const float* gnext, bool last) {
;     ...
; #pragma unroll
;       for (int j = 0; j < 16; ++j) {
;         const int e = bt * 16 + j;
;         const int eidx = __builtin_amdgcn_readlane(e < 64 ? i0 : i1, e & 63);
;         vr[j] = *(const u32x4*)(EV + (size_t)eidx * DM + lane * 16);
;       }
; #pragma unroll
;       for (int j = 0; j < 16; ++j) {
;         const int e = bt * 16 + j;
;         const float wj = __int_as_float(__builtin_amdgcn_readlane(__float_as_int(e < 64 ? w0 : w1), e & 63));
; #pragma unroll
;         for (int w = 0; w < 4; ++w) {
;           const f32x2 lo = __builtin_amdgcn_cvt_pk_f32_fp8((int)vr[j][w], false);
;           const f32x2 hi = __builtin_amdgcn_cvt_pk_f32_fp8((int)vr[j][w], true);
;           acc[4 * w] += wj * lo[0]; acc[4 * w + 1] += wj * lo[1]; acc[4 * w + 2] += wj * hi[0]; acc[4 * w + 3] += wj * hi[1];
;         }
	v_cvt_pk_f32_fp8_e32 v[144:145], v88
	v_cvt_pk_f32_fp8_sdwa v[146:147], v88 src0_sel:WORD_1
	v_cvt_pk_f32_fp8_e32 v[148:149], v89
	v_cvt_pk_f32_fp8_sdwa v[150:151], v89 src0_sel:WORD_1
	v_cvt_pk_f32_fp8_e32 v[152:153], v90
	v_cvt_pk_f32_fp8_sdwa v[154:155], v90 src0_sel:WORD_1
	v_cvt_pk_f32_fp8_e32 v[156:157], v91
	v_cvt_pk_f32_fp8_sdwa v[158:159], v91 src0_sel:WORD_1
	v_fmac_f32_e32 v0, v50, v144
	v_fmac_f32_e32 v1, v50, v145
	v_fmac_f32_e32 v2, v50, v146
	v_fmac_f32_e32 v3, v50, v147
	v_fmac_f32_e32 v4, v50, v148
	v_fmac_f32_e32 v5, v50, v149
	v_fmac_f32_e32 v6, v50, v150
	v_fmac_f32_e32 v7, v50, v151
	v_fmac_f32_e32 v8, v50, v152
	v_fmac_f32_e32 v9, v50, v153
	v_fmac_f32_e32 v10, v50, v154
	v_fmac_f32_e32 v11, v50, v155
	v_fmac_f32_e32 v12, v50, v156
	v_fmac_f32_e32 v13, v50, v157
	v_fmac_f32_e32 v14, v50, v158
	v_fmac_f32_e32 v15, v50, v159
	v_lshl_add_u32 v161, v34, 7, v160
	global_load_dwordx4 v[88:91], v161, s[14:15]
	s_waitcnt vmcnt(15)
	v_cvt_pk_f32_fp8_e32 v[144:145], v92
	v_cvt_pk_f32_fp8_sdwa v[146:147], v92 src0_sel:WORD_1
	v_cvt_pk_f32_fp8_e32 v[148:149], v93
	v_cvt_pk_f32_fp8_sdwa v[150:151], v93 src0_sel:WORD_1
	v_cvt_pk_f32_fp8_e32 v[152:153], v94
	v_cvt_pk_f32_fp8_sdwa v[154:155], v94 src0_sel:WORD_1
	v_cvt_pk_f32_fp8_e32 v[156:157], v95
	v_cvt_pk_f32_fp8_sdwa v[158:159], v95 src0_sel:WORD_1
	v_fmac_f32_e32 v0, v51, v144
	v_fmac_f32_e32 v1, v51, v145
	v_fmac_f32_e32 v2, v51, v146
	v_fmac_f32_e32 v3, v51, v147
	v_fmac_f32_e32 v4, v51, v148
	v_fmac_f32_e32 v5, v51, v149
	v_fmac_f32_e32 v6, v51, v150
	v_fmac_f32_e32 v7, v51, v151
	v_fmac_f32_e32 v8, v51, v152
	v_fmac_f32_e32 v9, v51, v153
	v_fmac_f32_e32 v10, v51, v154
	v_fmac_f32_e32 v11, v51, v155
	v_fmac_f32_e32 v12, v51, v156
	v_fmac_f32_e32 v13, v51, v157
	v_fmac_f32_e32 v14, v51, v158
	v_fmac_f32_e32 v15, v51, v159
	v_lshl_add_u32 v161, v35, 7, v160
	global_load_dwordx4 v[92:95], v161, s[14:15]
	s_waitcnt vmcnt(15)
	v_cvt_pk_f32_fp8_e32 v[144:145], v96
	v_cvt_pk_f32_fp8_sdwa v[146:147], v96 src0_sel:WORD_1
	v_cvt_pk_f32_fp8_e32 v[148:149], v97
	v_cvt_pk_f32_fp8_sdwa v[150:151], v97 src0_sel:WORD_1
	v_cvt_pk_f32_fp8_e32 v[152:153], v98
	v_cvt_pk_f32_fp8_sdwa v[154:155], v98 src0_sel:WORD_1
	v_cvt_pk_f32_fp8_e32 v[156:157], v99
	v_cvt_pk_f32_fp8_sdwa v[158:159], v99 src0_sel:WORD_1
	v_fmac_f32_e32 v0, v52, v144
	v_fmac_f32_e32 v1, v52, v145
	v_fmac_f32_e32 v2, v52, v146
	v_fmac_f32_e32 v3, v52, v147
	v_fmac_f32_e32 v4, v52, v148
	v_fmac_f32_e32 v5, v52, v149
	v_fmac_f32_e32 v6, v52, v150
	v_fmac_f32_e32 v7, v52, v151
	v_fmac_f32_e32 v8, v52, v152
	v_fmac_f32_e32 v9, v52, v153
	v_fmac_f32_e32 v10, v52, v154
	v_fmac_f32_e32 v11, v52, v155
	v_fmac_f32_e32 v12, v52, v156
	v_fmac_f32_e32 v13, v52, v157
	v_fmac_f32_e32 v14, v52, v158
	v_fmac_f32_e32 v15, v52, v159
	v_lshl_add_u32 v161, v36, 7, v160
	global_load_dwordx4 v[96:99], v161, s[14:15]
	s_waitcnt vmcnt(15)
	v_cvt_pk_f32_fp8_e32 v[144:145], v100
	v_cvt_pk_f32_fp8_sdwa v[146:147], v100 src0_sel:WORD_1
	v_cvt_pk_f32_fp8_e32 v[148:149], v101
	v_cvt_pk_f32_fp8_sdwa v[150:151], v101 src0_sel:WORD_1
	v_cvt_pk_f32_fp8_e32 v[152:153], v102
	v_cvt_pk_f32_fp8_sdwa v[154:155], v102 src0_sel:WORD_1
	v_cvt_pk_f32_fp8_e32 v[156:157], v103
	v_cvt_pk_f32_fp8_sdwa v[158:159], v103 src0_sel:WORD_1
	v_fmac_f32_e32 v0, v53, v144
	v_fmac_f32_e32 v1, v53, v145
	v_fmac_f32_e32 v2, v53, v146
	v_fmac_f32_e32 v3, v53, v147
	v_fmac_f32_e32 v4, v53, v148
	v_fmac_f32_e32 v5, v53, v149
	v_fmac_f32_e32 v6, v53, v150
	v_fmac_f32_e32 v7, v53, v151
	v_fmac_f32_e32 v8, v53, v152
	v_fmac_f32_e32 v9, v53, v153
	v_fmac_f32_e32 v10, v53, v154
	v_fmac_f32_e32 v11, v53, v155
	v_fmac_f32_e32 v12, v53, v156
	v_fmac_f32_e32 v13, v53, v157
	v_fmac_f32_e32 v14, v53, v158
	v_fmac_f32_e32 v15, v53, v159
	v_lshl_add_u32 v161, v37, 7, v160
	global_load_dwordx4 v[100:103], v161, s[14:15]
	s_waitcnt vmcnt(15)
	v_cvt_pk_f32_fp8_e32 v[144:145], v104
	v_cvt_pk_f32_fp8_sdwa v[146:147], v104 src0_sel:WORD_1
	v_cvt_pk_f32_fp8_e32 v[148:149], v105
	v_cvt_pk_f32_fp8_sdwa v[150:151], v105 src0_sel:WORD_1
	v_cvt_pk_f32_fp8_e32 v[152:153], v106
	v_cvt_pk_f32_fp8_sdwa v[154:155], v106 src0_sel:WORD_1
	v_cvt_pk_f32_fp8_e32 v[156:157], v107
	v_cvt_pk_f32_fp8_sdwa v[158:159], v107 src0_sel:WORD_1
	v_fmac_f32_e32 v0, v54, v144
	v_fmac_f32_e32 v1, v54, v145
	v_fmac_f32_e32 v2, v54, v146
	v_fmac_f32_e32 v3, v54, v147
	v_fmac_f32_e32 v4, v54, v148
	v_fmac_f32_e32 v5, v54, v149
	v_fmac_f32_e32 v6, v54, v150
	v_fmac_f32_e32 v7, v54, v151
	v_fmac_f32_e32 v8, v54, v152
	v_fmac_f32_e32 v9, v54, v153
	v_fmac_f32_e32 v10, v54, v154
	v_fmac_f32_e32 v11, v54, v155
	v_fmac_f32_e32 v12, v54, v156
	v_fmac_f32_e32 v13, v54, v157
	v_fmac_f32_e32 v14, v54, v158
	v_fmac_f32_e32 v15, v54, v159
	v_lshl_add_u32 v161, v38, 7, v160
	global_load_dwordx4 v[104:107], v161, s[14:15]
	s_waitcnt vmcnt(15)
	v_cvt_pk_f32_fp8_e32 v[144:145], v108
	v_cvt_pk_f32_fp8_sdwa v[146:147], v108 src0_sel:WORD_1
	v_cvt_pk_f32_fp8_e32 v[148:149], v109
	v_cvt_pk_f32_fp8_sdwa v[150:151], v109 src0_sel:WORD_1
	v_cvt_pk_f32_fp8_e32 v[152:153], v110
	v_cvt_pk_f32_fp8_sdwa v[154:155], v110 src0_sel:WORD_1
	v_cvt_pk_f32_fp8_e32 v[156:157], v111
	v_cvt_pk_f32_fp8_sdwa v[158:159], v111 src0_sel:WORD_1
	v_fmac_f32_e32 v0, v55, v144
	v_fmac_f32_e32 v1, v55, v145
	v_fmac_f32_e32 v2, v55, v146
	v_fmac_f32_e32 v3, v55, v147
	v_fmac_f32_e32 v4, v55, v148
	v_fmac_f32_e32 v5, v55, v149
	v_fmac_f32_e32 v6, v55, v150
	v_fmac_f32_e32 v7, v55, v151
	v_fmac_f32_e32 v8, v55, v152
	v_fmac_f32_e32 v9, v55, v153
	v_fmac_f32_e32 v10, v55, v154
	v_fmac_f32_e32 v11, v55, v155
	v_fmac_f32_e32 v12, v55, v156
	v_fmac_f32_e32 v13, v55, v157
	v_fmac_f32_e32 v14, v55, v158
	v_fmac_f32_e32 v15, v55, v159
	v_lshl_add_u32 v161, v39, 7, v160
	global_load_dwordx4 v[108:111], v161, s[14:15]
	s_waitcnt vmcnt(15)
; DI void phase_peer_b(const Params& p, int layer, const float* gnext, bool last) {
;     ...
; #pragma unroll
;       for (int j = 0; j < 16; ++j) {
;         const int e = bt * 16 + j;
;         const int eidx = __builtin_amdgcn_readlane(e < 64 ? i0 : i1, e & 63);
;         vr[j] = *(const u32x4*)(EV + (size_t)eidx * DM + lane * 16);
;       }
; #pragma unroll
;       for (int j = 0; j < 16; ++j) {
;         const int e = bt * 16 + j;
;         const float wj = __int_as_float(__builtin_amdgcn_readlane(__float_as_int(e < 64 ? w0 : w1), e & 63));
; #pragma unroll
;         for (int w = 0; w < 4; ++w) {
;           const f32x2 lo = __builtin_amdgcn_cvt_pk_f32_fp8((int)vr[j][w], false);
;           const f32x2 hi = __builtin_amdgcn_cvt_pk_f32_fp8((int)vr[j][w], true);
;           acc[4 * w] += wj * lo[0]; acc[4 * w + 1] += wj * lo[1]; acc[4 * w + 2] += wj * hi[0]; acc[4 * w + 3] += wj * hi[1];
;         }
	v_cvt_pk_f32_fp8_e32 v[144:145], v112
	v_cvt_pk_f32_fp8_sdwa v[146:147], v112 src0_sel:WORD_1
	v_cvt_pk_f32_fp8_e32 v[148:149], v113
	v_cvt_pk_f32_fp8_sdwa v[150:151], v113 src0_sel:WORD_1
	v_cvt_pk_f32_fp8_e32 v[152:153], v114
	v_cvt_pk_f32_fp8_sdwa v[154:155], v114 src0_sel:WORD_1
	v_cvt_pk_f32_fp8_e32 v[156:157], v115
	v_cvt_pk_f32_fp8_sdwa v[158:159], v115 src0_sel:WORD_1
	v_fmac_f32_e32 v0, v56, v144
	v_fmac_f32_e32 v1, v56, v145
	v_fmac_f32_e32 v2, v56, v146
	v_fmac_f32_e32 v3, v56, v147
	v_fmac_f32_e32 v4, v56, v148
	v_fmac_f32_e32 v5, v56, v149
	v_fmac_f32_e32 v6, v56, v150
	v_fmac_f32_e32 v7, v56, v151
	v_fmac_f32_e32 v8, v56, v152
	v_fmac_f32_e32 v9, v56, v153
	v_fmac_f32_e32 v10, v56, v154
	v_fmac_f32_e32 v11, v56, v155
	v_fmac_f32_e32 v12, v56, v156
	v_fmac_f32_e32 v13, v56, v157
	v_fmac_f32_e32 v14, v56, v158
	v_fmac_f32_e32 v15, v56, v159
	v_lshl_add_u32 v161, v40, 7, v160
	global_load_dwordx4 v[112:115], v161, s[14:15]
	s_waitcnt vmcnt(15)
	v_cvt_pk_f32_fp8_e32 v[144:145], v116
	v_cvt_pk_f32_fp8_sdwa v[146:147], v116 src0_sel:WORD_1
	v_cvt_pk_f32_fp8_e32 v[148:149], v117
	v_cvt_pk_f32_fp8_sdwa v[150:151], v117 src0_sel:WORD_1
	v_cvt_pk_f32_fp8_e32 v[152:153], v118
	v_cvt_pk_f32_fp8_sdwa v[154:155], v118 src0_sel:WORD_1
	v_cvt_pk_f32_fp8_e32 v[156:157], v119
	v_cvt_pk_f32_fp8_sdwa v[158:159], v119 src0_sel:WORD_1
	v_fmac_f32_e32 v0, v57, v144
	v_fmac_f32_e32 v1, v57, v145
	v_fmac_f32_e32 v2, v57, v146
	v_fmac_f32_e32 v3, v57, v147
	v_fmac_f32_e32 v4, v57, v148
	v_fmac_f32_e32 v5, v57, v149
	v_fmac_f32_e32 v6, v57, v150
	v_fmac_f32_e32 v7, v57, v151
	v_fmac_f32_e32 v8, v57, v152
	v_fmac_f32_e32 v9, v57, v153
	v_fmac_f32_e32 v10, v57, v154
	v_fmac_f32_e32 v11, v57, v155
	v_fmac_f32_e32 v12, v57, v156
	v_fmac_f32_e32 v13, v57, v157
	v_fmac_f32_e32 v14, v57, v158
	v_fmac_f32_e32 v15, v57, v159
	v_lshl_add_u32 v161, v41, 7, v160
	global_load_dwordx4 v[116:119], v161, s[14:15]
	s_waitcnt vmcnt(15)
	v_cvt_pk_f32_fp8_e32 v[144:145], v120
	v_cvt_pk_f32_fp8_sdwa v[146:147], v120 src0_sel:WORD_1
	v_cvt_pk_f32_fp8_e32 v[148:149], v121
	v_cvt_pk_f32_fp8_sdwa v[150:151], v121 src0_sel:WORD_1
	v_cvt_pk_f32_fp8_e32 v[152:153], v122
	v_cvt_pk_f32_fp8_sdwa v[154:155], v122 src0_sel:WORD_1
	v_cvt_pk_f32_fp8_e32 v[156:157], v123
	v_cvt_pk_f32_fp8_sdwa v[158:159], v123 src0_sel:WORD_1
	v_fmac_f32_e32 v0, v58, v144
	v_fmac_f32_e32 v1, v58, v145
	v_fmac_f32_e32 v2, v58, v146
	v_fmac_f32_e32 v3, v58, v147
	v_fmac_f32_e32 v4, v58, v148
	v_fmac_f32_e32 v5, v58, v149
	v_fmac_f32_e32 v6, v58, v150
	v_fmac_f32_e32 v7, v58, v151
	v_fmac_f32_e32 v8, v58, v152
	v_fmac_f32_e32 v9, v58, v153
	v_fmac_f32_e32 v10, v58, v154
	v_fmac_f32_e32 v11, v58, v155
	v_fmac_f32_e32 v12, v58, v156
	v_fmac_f32_e32 v13, v58, v157
	v_fmac_f32_e32 v14, v58, v158
	v_fmac_f32_e32 v15, v58, v159
	v_lshl_add_u32 v161, v42, 7, v160
	global_load_dwordx4 v[120:123], v161, s[14:15]
	s_waitcnt vmcnt(15)
	v_cvt_pk_f32_fp8_e32 v[144:145], v124
	v_cvt_pk_f32_fp8_sdwa v[146:147], v124 src0_sel:WORD_1
	v_cvt_pk_f32_fp8_e32 v[148:149], v125
	v_cvt_pk_f32_fp8_sdwa v[150:151], v125 src0_sel:WORD_1
	v_cvt_pk_f32_fp8_e32 v[152:153], v126
	v_cvt_pk_f32_fp8_sdwa v[154:155], v126 src0_sel:WORD_1
	v_cvt_pk_f32_fp8_e32 v[156:157], v127
	v_cvt_pk_f32_fp8_sdwa v[158:159], v127 src0_sel:WORD_1
	v_fmac_f32_e32 v0, v59, v144
	v_fmac_f32_e32 v1, v59, v145
	v_fmac_f32_e32 v2, v59, v146
	v_fmac_f32_e32 v3, v59, v147
	v_fmac_f32_e32 v4, v59, v148
	v_fmac_f32_e32 v5, v59, v149
	v_fmac_f32_e32 v6, v59, v150
	v_fmac_f32_e32 v7, v59, v151
	v_fmac_f32_e32 v8, v59, v152
	v_fmac_f32_e32 v9, v59, v153
	v_fmac_f32_e32 v10, v59, v154
	v_fmac_f32_e32 v11, v59, v155
	v_fmac_f32_e32 v12, v59, v156
	v_fmac_f32_e32 v13, v59, v157
	v_fmac_f32_e32 v14, v59, v158
	v_fmac_f32_e32 v15, v59, v159
	v_lshl_add_u32 v161, v43, 7, v160
	global_load_dwordx4 v[124:127], v161, s[14:15]
	s_waitcnt vmcnt(15)
	v_cvt_pk_f32_fp8_e32 v[144:145], v128
	v_cvt_pk_f32_fp8_sdwa v[146:147], v128 src0_sel:WORD_1
	v_cvt_pk_f32_fp8_e32 v[148:149], v129
	v_cvt_pk_f32_fp8_sdwa v[150:151], v129 src0_sel:WORD_1
	v_cvt_pk_f32_fp8_e32 v[152:153], v130
	v_cvt_pk_f32_fp8_sdwa v[154:155], v130 src0_sel:WORD_1
	v_cvt_pk_f32_fp8_e32 v[156:157], v131
	v_cvt_pk_f32_fp8_sdwa v[158:159], v131 src0_sel:WORD_1
	v_fmac_f32_e32 v0, v60, v144
	v_fmac_f32_e32 v1, v60, v145
	v_fmac_f32_e32 v2, v60, v146
	v_fmac_f32_e32 v3, v60, v147
	v_fmac_f32_e32 v4, v60, v148
	v_fmac_f32_e32 v5, v60, v149
	v_fmac_f32_e32 v6, v60, v150
	v_fmac_f32_e32 v7, v60, v151
	v_fmac_f32_e32 v8, v60, v152
	v_fmac_f32_e32 v9, v60, v153
	v_fmac_f32_e32 v10, v60, v154
	v_fmac_f32_e32 v11, v60, v155
	v_fmac_f32_e32 v12, v60, v156
	v_fmac_f32_e32 v13, v60, v157
	v_fmac_f32_e32 v14, v60, v158
	v_fmac_f32_e32 v15, v60, v159
	v_lshl_add_u32 v161, v44, 7, v160
	global_load_dwordx4 v[128:131], v161, s[14:15]
	s_waitcnt vmcnt(15)
	v_cvt_pk_f32_fp8_e32 v[144:145], v132
	v_cvt_pk_f32_fp8_sdwa v[146:147], v132 src0_sel:WORD_1
	v_cvt_pk_f32_fp8_e32 v[148:149], v133
	v_cvt_pk_f32_fp8_sdwa v[150:151], v133 src0_sel:WORD_1
	v_cvt_pk_f32_fp8_e32 v[152:153], v134
	v_cvt_pk_f32_fp8_sdwa v[154:155], v134 src0_sel:WORD_1
	v_cvt_pk_f32_fp8_e32 v[156:157], v135
	v_cvt_pk_f32_fp8_sdwa v[158:159], v135 src0_sel:WORD_1
	v_fmac_f32_e32 v0, v61, v144
	v_fmac_f32_e32 v1, v61, v145
	v_fmac_f32_e32 v2, v61, v146
	v_fmac_f32_e32 v3, v61, v147
	v_fmac_f32_e32 v4, v61, v148
	v_fmac_f32_e32 v5, v61, v149
	v_fmac_f32_e32 v6, v61, v150
	v_fmac_f32_e32 v7, v61, v151
	v_fmac_f32_e32 v8, v61, v152
	v_fmac_f32_e32 v9, v61, v153
	v_fmac_f32_e32 v10, v61, v154
	v_fmac_f32_e32 v11, v61, v155
	v_fmac_f32_e32 v12, v61, v156
	v_fmac_f32_e32 v13, v61, v157
	v_fmac_f32_e32 v14, v61, v158
	v_fmac_f32_e32 v15, v61, v159
	v_lshl_add_u32 v161, v45, 7, v160
	global_load_dwordx4 v[132:135], v161, s[14:15]
	s_waitcnt vmcnt(15)
; DI void phase_peer_b(const Params& p, int layer, const float* gnext, bool last) {
;     ...
; #pragma unroll
;       for (int j = 0; j < 16; ++j) {
;         const int e = bt * 16 + j;
;         const int eidx = __builtin_amdgcn_readlane(e < 64 ? i0 : i1, e & 63);
;         vr[j] = *(const u32x4*)(EV + (size_t)eidx * DM + lane * 16);
;       }
; #pragma unroll
;       for (int j = 0; j < 16; ++j) {
;         const int e = bt * 16 + j;
;         const float wj = __int_as_float(__builtin_amdgcn_readlane(__float_as_int(e < 64 ? w0 : w1), e & 63));
; #pragma unroll
;         for (int w = 0; w < 4; ++w) {
;           const f32x2 lo = __builtin_amdgcn_cvt_pk_f32_fp8((int)vr[j][w], false);
;           const f32x2 hi = __builtin_amdgcn_cvt_pk_f32_fp8((int)vr[j][w], true);
;           acc[4 * w] += wj * lo[0]; acc[4 * w + 1] += wj * lo[1]; acc[4 * w + 2] += wj * hi[0]; acc[4 * w + 3] += wj * hi[1];
;         }
	v_cvt_pk_f32_fp8_e32 v[144:145], v136
	v_cvt_pk_f32_fp8_sdwa v[146:147], v136 src0_sel:WORD_1
	v_cvt_pk_f32_fp8_e32 v[148:149], v137
	v_cvt_pk_f32_fp8_sdwa v[150:151], v137 src0_sel:WORD_1
	v_cvt_pk_f32_fp8_e32 v[152:153], v138
	v_cvt_pk_f32_fp8_sdwa v[154:155], v138 src0_sel:WORD_1
	v_cvt_pk_f32_fp8_e32 v[156:157], v139
	v_cvt_pk_f32_fp8_sdwa v[158:159], v139 src0_sel:WORD_1
	v_fmac_f32_e32 v0, v62, v144
	v_fmac_f32_e32 v1, v62, v145
	v_fmac_f32_e32 v2, v62, v146
	v_fmac_f32_e32 v3, v62, v147
	v_fmac_f32_e32 v4, v62, v148
	v_fmac_f32_e32 v5, v62, v149
	v_fmac_f32_e32 v6, v62, v150
	v_fmac_f32_e32 v7, v62, v151
	v_fmac_f32_e32 v8, v62, v152
	v_fmac_f32_e32 v9, v62, v153
	v_fmac_f32_e32 v10, v62, v154
	v_fmac_f32_e32 v11, v62, v155
	v_fmac_f32_e32 v12, v62, v156
	v_fmac_f32_e32 v13, v62, v157
	v_fmac_f32_e32 v14, v62, v158
	v_fmac_f32_e32 v15, v62, v159
	v_lshl_add_u32 v161, v46, 7, v160
	global_load_dwordx4 v[136:139], v161, s[14:15]
	s_waitcnt vmcnt(15)
	v_cvt_pk_f32_fp8_e32 v[144:145], v140
	v_cvt_pk_f32_fp8_sdwa v[146:147], v140 src0_sel:WORD_1
	v_cvt_pk_f32_fp8_e32 v[148:149], v141
	v_cvt_pk_f32_fp8_sdwa v[150:151], v141 src0_sel:WORD_1
	v_cvt_pk_f32_fp8_e32 v[152:153], v142
	v_cvt_pk_f32_fp8_sdwa v[154:155], v142 src0_sel:WORD_1
	v_cvt_pk_f32_fp8_e32 v[156:157], v143
	v_cvt_pk_f32_fp8_sdwa v[158:159], v143 src0_sel:WORD_1
	v_fmac_f32_e32 v0, v63, v144
	v_fmac_f32_e32 v1, v63, v145
	v_fmac_f32_e32 v2, v63, v146
	v_fmac_f32_e32 v3, v63, v147
	v_fmac_f32_e32 v4, v63, v148
	v_fmac_f32_e32 v5, v63, v149
	v_fmac_f32_e32 v6, v63, v150
	v_fmac_f32_e32 v7, v63, v151
	v_fmac_f32_e32 v8, v63, v152
	v_fmac_f32_e32 v9, v63, v153
	v_fmac_f32_e32 v10, v63, v154
	v_fmac_f32_e32 v11, v63, v155
	v_fmac_f32_e32 v12, v63, v156
	v_fmac_f32_e32 v13, v63, v157
	v_fmac_f32_e32 v14, v63, v158
	v_fmac_f32_e32 v15, v63, v159
	v_lshl_add_u32 v161, v47, 7, v160
	global_load_dwordx4 v[140:143], v161, s[14:15]
	s_waitcnt lgkmcnt(0)
	s_waitcnt vmcnt(15)
	v_cvt_pk_f32_fp8_e32 v[144:145], v80
	v_cvt_pk_f32_fp8_sdwa v[146:147], v80 src0_sel:WORD_1
	v_cvt_pk_f32_fp8_e32 v[148:149], v81
	v_cvt_pk_f32_fp8_sdwa v[150:151], v81 src0_sel:WORD_1
	v_cvt_pk_f32_fp8_e32 v[152:153], v82
	v_cvt_pk_f32_fp8_sdwa v[154:155], v82 src0_sel:WORD_1
	v_cvt_pk_f32_fp8_e32 v[156:157], v83
	v_cvt_pk_f32_fp8_sdwa v[158:159], v83 src0_sel:WORD_1
	v_fmac_f32_e32 v0, v64, v144
	v_fmac_f32_e32 v1, v64, v145
	v_fmac_f32_e32 v2, v64, v146
	v_fmac_f32_e32 v3, v64, v147
	v_fmac_f32_e32 v4, v64, v148
	v_fmac_f32_e32 v5, v64, v149
	v_fmac_f32_e32 v6, v64, v150
	v_fmac_f32_e32 v7, v64, v151
	v_fmac_f32_e32 v8, v64, v152
	v_fmac_f32_e32 v9, v64, v153
	v_fmac_f32_e32 v10, v64, v154
	v_fmac_f32_e32 v11, v64, v155
	v_fmac_f32_e32 v12, v64, v156
	v_fmac_f32_e32 v13, v64, v157
	v_fmac_f32_e32 v14, v64, v158
	v_fmac_f32_e32 v15, v64, v159
	s_waitcnt vmcnt(14)
	v_cvt_pk_f32_fp8_e32 v[144:145], v84
	v_cvt_pk_f32_fp8_sdwa v[146:147], v84 src0_sel:WORD_1
	v_cvt_pk_f32_fp8_e32 v[148:149], v85
	v_cvt_pk_f32_fp8_sdwa v[150:151], v85 src0_sel:WORD_1
	v_cvt_pk_f32_fp8_e32 v[152:153], v86
	v_cvt_pk_f32_fp8_sdwa v[154:155], v86 src0_sel:WORD_1
	v_cvt_pk_f32_fp8_e32 v[156:157], v87
	v_cvt_pk_f32_fp8_sdwa v[158:159], v87 src0_sel:WORD_1
	v_fmac_f32_e32 v0, v65, v144
	v_fmac_f32_e32 v1, v65, v145
	v_fmac_f32_e32 v2, v65, v146
	v_fmac_f32_e32 v3, v65, v147
	v_fmac_f32_e32 v4, v65, v148
	v_fmac_f32_e32 v5, v65, v149
	v_fmac_f32_e32 v6, v65, v150
	v_fmac_f32_e32 v7, v65, v151
	v_fmac_f32_e32 v8, v65, v152
	v_fmac_f32_e32 v9, v65, v153
	v_fmac_f32_e32 v10, v65, v154
	v_fmac_f32_e32 v11, v65, v155
	v_fmac_f32_e32 v12, v65, v156
	v_fmac_f32_e32 v13, v65, v157
	v_fmac_f32_e32 v14, v65, v158
	v_fmac_f32_e32 v15, v65, v159
	s_waitcnt vmcnt(13)
	v_cvt_pk_f32_fp8_e32 v[144:145], v88
	v_cvt_pk_f32_fp8_sdwa v[146:147], v88 src0_sel:WORD_1
	v_cvt_pk_f32_fp8_e32 v[148:149], v89
	v_cvt_pk_f32_fp8_sdwa v[150:151], v89 src0_sel:WORD_1
	v_cvt_pk_f32_fp8_e32 v[152:153], v90
	v_cvt_pk_f32_fp8_sdwa v[154:155], v90 src0_sel:WORD_1
	v_cvt_pk_f32_fp8_e32 v[156:157], v91
	v_cvt_pk_f32_fp8_sdwa v[158:159], v91 src0_sel:WORD_1
	v_fmac_f32_e32 v0, v66, v144
	v_fmac_f32_e32 v1, v66, v145
	v_fmac_f32_e32 v2, v66, v146
	v_fmac_f32_e32 v3, v66, v147
	v_fmac_f32_e32 v4, v66, v148
	v_fmac_f32_e32 v5, v66, v149
	v_fmac_f32_e32 v6, v66, v150
	v_fmac_f32_e32 v7, v66, v151
	v_fmac_f32_e32 v8, v66, v152
	v_fmac_f32_e32 v9, v66, v153
	v_fmac_f32_e32 v10, v66, v154
	v_fmac_f32_e32 v11, v66, v155
	v_fmac_f32_e32 v12, v66, v156
	v_fmac_f32_e32 v13, v66, v157
	v_fmac_f32_e32 v14, v66, v158
	v_fmac_f32_e32 v15, v66, v159
	s_waitcnt vmcnt(12)
	v_cvt_pk_f32_fp8_e32 v[144:145], v92
	v_cvt_pk_f32_fp8_sdwa v[146:147], v92 src0_sel:WORD_1
	v_cvt_pk_f32_fp8_e32 v[148:149], v93
	v_cvt_pk_f32_fp8_sdwa v[150:151], v93 src0_sel:WORD_1
	v_cvt_pk_f32_fp8_e32 v[152:153], v94
	v_cvt_pk_f32_fp8_sdwa v[154:155], v94 src0_sel:WORD_1
	v_cvt_pk_f32_fp8_e32 v[156:157], v95
	v_cvt_pk_f32_fp8_sdwa v[158:159], v95 src0_sel:WORD_1
	v_fmac_f32_e32 v0, v67, v144
	v_fmac_f32_e32 v1, v67, v145
	v_fmac_f32_e32 v2, v67, v146
	v_fmac_f32_e32 v3, v67, v147
	v_fmac_f32_e32 v4, v67, v148
	v_fmac_f32_e32 v5, v67, v149
	v_fmac_f32_e32 v6, v67, v150
	v_fmac_f32_e32 v7, v67, v151
	v_fmac_f32_e32 v8, v67, v152
	v_fmac_f32_e32 v9, v67, v153
	v_fmac_f32_e32 v10, v67, v154
	v_fmac_f32_e32 v11, v67, v155
	v_fmac_f32_e32 v12, v67, v156
	v_fmac_f32_e32 v13, v67, v157
	v_fmac_f32_e32 v14, v67, v158
	v_fmac_f32_e32 v15, v67, v159
	s_waitcnt vmcnt(11)
; DI void phase_peer_b(const Params& p, int layer, const float* gnext, bool last) {
;     ...
; #pragma unroll
;       for (int j = 0; j < 16; ++j) {
;         const int e = bt * 16 + j;
;         const int eidx = __builtin_amdgcn_readlane(e < 64 ? i0 : i1, e & 63);
;         vr[j] = *(const u32x4*)(EV + (size_t)eidx * DM + lane * 16);
;       }
; #pragma unroll
;       for (int j = 0; j < 16; ++j) {
;         const int e = bt * 16 + j;
;         const float wj = __int_as_float(__builtin_amdgcn_readlane(__float_as_int(e < 64 ? w0 : w1), e & 63));
; #pragma unroll
;         for (int w = 0; w < 4; ++w) {
;           const f32x2 lo = __builtin_amdgcn_cvt_pk_f32_fp8((int)vr[j][w], false);
;           const f32x2 hi = __builtin_amdgcn_cvt_pk_f32_fp8((int)vr[j][w], true);
;           acc[4 * w] += wj * lo[0]; acc[4 * w + 1] += wj * lo[1]; acc[4 * w + 2] += wj * hi[0]; acc[4 * w + 3] += wj * hi[1];
;         }
	v_cvt_pk_f32_fp8_e32 v[144:145], v96
	v_cvt_pk_f32_fp8_sdwa v[146:147], v96 src0_sel:WORD_1
	v_cvt_pk_f32_fp8_e32 v[148:149], v97
	v_cvt_pk_f32_fp8_sdwa v[150:151], v97 src0_sel:WORD_1
	v_cvt_pk_f32_fp8_e32 v[152:153], v98
	v_cvt_pk_f32_fp8_sdwa v[154:155], v98 src0_sel:WORD_1
	v_cvt_pk_f32_fp8_e32 v[156:157], v99
	v_cvt_pk_f32_fp8_sdwa v[158:159], v99 src0_sel:WORD_1
	v_fmac_f32_e32 v0, v68, v144
	v_fmac_f32_e32 v1, v68, v145
	v_fmac_f32_e32 v2, v68, v146
	v_fmac_f32_e32 v3, v68, v147
	v_fmac_f32_e32 v4, v68, v148
	v_fmac_f32_e32 v5, v68, v149
	v_fmac_f32_e32 v6, v68, v150
	v_fmac_f32_e32 v7, v68, v151
	v_fmac_f32_e32 v8, v68, v152
	v_fmac_f32_e32 v9, v68, v153
	v_fmac_f32_e32 v10, v68, v154
	v_fmac_f32_e32 v11, v68, v155
	v_fmac_f32_e32 v12, v68, v156
	v_fmac_f32_e32 v13, v68, v157
	v_fmac_f32_e32 v14, v68, v158
	v_fmac_f32_e32 v15, v68, v159
	s_waitcnt vmcnt(10)
	v_cvt_pk_f32_fp8_e32 v[144:145], v100
	v_cvt_pk_f32_fp8_sdwa v[146:147], v100 src0_sel:WORD_1
	v_cvt_pk_f32_fp8_e32 v[148:149], v101
	v_cvt_pk_f32_fp8_sdwa v[150:151], v101 src0_sel:WORD_1
	v_cvt_pk_f32_fp8_e32 v[152:153], v102
	v_cvt_pk_f32_fp8_sdwa v[154:155], v102 src0_sel:WORD_1
	v_cvt_pk_f32_fp8_e32 v[156:157], v103
	v_cvt_pk_f32_fp8_sdwa v[158:159], v103 src0_sel:WORD_1
	v_fmac_f32_e32 v0, v69, v144
	v_fmac_f32_e32 v1, v69, v145
	v_fmac_f32_e32 v2, v69, v146
	v_fmac_f32_e32 v3, v69, v147
	v_fmac_f32_e32 v4, v69, v148
	v_fmac_f32_e32 v5, v69, v149
	v_fmac_f32_e32 v6, v69, v150
	v_fmac_f32_e32 v7, v69, v151
	v_fmac_f32_e32 v8, v69, v152
	v_fmac_f32_e32 v9, v69, v153
	v_fmac_f32_e32 v10, v69, v154
	v_fmac_f32_e32 v11, v69, v155
	v_fmac_f32_e32 v12, v69, v156
	v_fmac_f32_e32 v13, v69, v157
	v_fmac_f32_e32 v14, v69, v158
	v_fmac_f32_e32 v15, v69, v159
	s_waitcnt vmcnt(9)
	v_cvt_pk_f32_fp8_e32 v[144:145], v104
	v_cvt_pk_f32_fp8_sdwa v[146:147], v104 src0_sel:WORD_1
	v_cvt_pk_f32_fp8_e32 v[148:149], v105
	v_cvt_pk_f32_fp8_sdwa v[150:151], v105 src0_sel:WORD_1
	v_cvt_pk_f32_fp8_e32 v[152:153], v106
	v_cvt_pk_f32_fp8_sdwa v[154:155], v106 src0_sel:WORD_1
	v_cvt_pk_f32_fp8_e32 v[156:157], v107
	v_cvt_pk_f32_fp8_sdwa v[158:159], v107 src0_sel:WORD_1
	v_fmac_f32_e32 v0, v70, v144
	v_fmac_f32_e32 v1, v70, v145
	v_fmac_f32_e32 v2, v70, v146
	v_fmac_f32_e32 v3, v70, v147
	v_fmac_f32_e32 v4, v70, v148
	v_fmac_f32_e32 v5, v70, v149
	v_fmac_f32_e32 v6, v70, v150
	v_fmac_f32_e32 v7, v70, v151
	v_fmac_f32_e32 v8, v70, v152
	v_fmac_f32_e32 v9, v70, v153
	v_fmac_f32_e32 v10, v70, v154
	v_fmac_f32_e32 v11, v70, v155
	v_fmac_f32_e32 v12, v70, v156
	v_fmac_f32_e32 v13, v70, v157
	v_fmac_f32_e32 v14, v70, v158
	v_fmac_f32_e32 v15, v70, v159
	s_waitcnt vmcnt(8)
	v_cvt_pk_f32_fp8_e32 v[144:145], v108
	v_cvt_pk_f32_fp8_sdwa v[146:147], v108 src0_sel:WORD_1
	v_cvt_pk_f32_fp8_e32 v[148:149], v109
	v_cvt_pk_f32_fp8_sdwa v[150:151], v109 src0_sel:WORD_1
	v_cvt_pk_f32_fp8_e32 v[152:153], v110
	v_cvt_pk_f32_fp8_sdwa v[154:155], v110 src0_sel:WORD_1
	v_cvt_pk_f32_fp8_e32 v[156:157], v111
	v_cvt_pk_f32_fp8_sdwa v[158:159], v111 src0_sel:WORD_1
	v_fmac_f32_e32 v0, v71, v144
	v_fmac_f32_e32 v1, v71, v145
	v_fmac_f32_e32 v2, v71, v146
	v_fmac_f32_e32 v3, v71, v147
	v_fmac_f32_e32 v4, v71, v148
	v_fmac_f32_e32 v5, v71, v149
	v_fmac_f32_e32 v6, v71, v150
	v_fmac_f32_e32 v7, v71, v151
	v_fmac_f32_e32 v8, v71, v152
	v_fmac_f32_e32 v9, v71, v153
	v_fmac_f32_e32 v10, v71, v154
	v_fmac_f32_e32 v11, v71, v155
	v_fmac_f32_e32 v12, v71, v156
	v_fmac_f32_e32 v13, v71, v157
	v_fmac_f32_e32 v14, v71, v158
	v_fmac_f32_e32 v15, v71, v159
	s_waitcnt vmcnt(7)
	v_cvt_pk_f32_fp8_e32 v[144:145], v112
	v_cvt_pk_f32_fp8_sdwa v[146:147], v112 src0_sel:WORD_1
	v_cvt_pk_f32_fp8_e32 v[148:149], v113
	v_cvt_pk_f32_fp8_sdwa v[150:151], v113 src0_sel:WORD_1
	v_cvt_pk_f32_fp8_e32 v[152:153], v114
	v_cvt_pk_f32_fp8_sdwa v[154:155], v114 src0_sel:WORD_1
	v_cvt_pk_f32_fp8_e32 v[156:157], v115
	v_cvt_pk_f32_fp8_sdwa v[158:159], v115 src0_sel:WORD_1
	v_fmac_f32_e32 v0, v72, v144
	v_fmac_f32_e32 v1, v72, v145
	v_fmac_f32_e32 v2, v72, v146
	v_fmac_f32_e32 v3, v72, v147
	v_fmac_f32_e32 v4, v72, v148
	v_fmac_f32_e32 v5, v72, v149
	v_fmac_f32_e32 v6, v72, v150
	v_fmac_f32_e32 v7, v72, v151
	v_fmac_f32_e32 v8, v72, v152
	v_fmac_f32_e32 v9, v72, v153
	v_fmac_f32_e32 v10, v72, v154
	v_fmac_f32_e32 v11, v72, v155
	v_fmac_f32_e32 v12, v72, v156
	v_fmac_f32_e32 v13, v72, v157
	v_fmac_f32_e32 v14, v72, v158
	v_fmac_f32_e32 v15, v72, v159
	s_waitcnt vmcnt(6)
	v_cvt_pk_f32_fp8_e32 v[144:145], v116
	v_cvt_pk_f32_fp8_sdwa v[146:147], v116 src0_sel:WORD_1
	v_cvt_pk_f32_fp8_e32 v[148:149], v117
	v_cvt_pk_f32_fp8_sdwa v[150:151], v117 src0_sel:WORD_1
	v_cvt_pk_f32_fp8_e32 v[152:153], v118
	v_cvt_pk_f32_fp8_sdwa v[154:155], v118 src0_sel:WORD_1
	v_cvt_pk_f32_fp8_e32 v[156:157], v119
	v_cvt_pk_f32_fp8_sdwa v[158:159], v119 src0_sel:WORD_1
	v_fmac_f32_e32 v0, v73, v144
	v_fmac_f32_e32 v1, v73, v145
	v_fmac_f32_e32 v2, v73, v146
	v_fmac_f32_e32 v3, v73, v147
	v_fmac_f32_e32 v4, v73, v148
	v_fmac_f32_e32 v5, v73, v149
	v_fmac_f32_e32 v6, v73, v150
	v_fmac_f32_e32 v7, v73, v151
	v_fmac_f32_e32 v8, v73, v152
	v_fmac_f32_e32 v9, v73, v153
	v_fmac_f32_e32 v10, v73, v154
	v_fmac_f32_e32 v11, v73, v155
	v_fmac_f32_e32 v12, v73, v156
	v_fmac_f32_e32 v13, v73, v157
	v_fmac_f32_e32 v14, v73, v158
	v_fmac_f32_e32 v15, v73, v159
	s_waitcnt vmcnt(5)
; DI void phase_peer_b(const Params& p, int layer, const float* gnext, bool last) {
;     ...
;       for (int j = 0; j < 16; ++j) {
;         const int e = bt * 16 + j;
;         const float wj = __int_as_float(__builtin_amdgcn_readlane(__float_as_int(e < 64 ? w0 : w1), e & 63));
; #pragma unroll
;         for (int w = 0; w < 4; ++w) {
;           const f32x2 lo = __builtin_amdgcn_cvt_pk_f32_fp8((int)vr[j][w], false);
;           const f32x2 hi = __builtin_amdgcn_cvt_pk_f32_fp8((int)vr[j][w], true);
;           acc[4 * w] += wj * lo[0]; acc[4 * w + 1] += wj * lo[1]; acc[4 * w + 2] += wj * hi[0]; acc[4 * w + 3] += wj * hi[1];
;         }
;       }
;     }
;       float* hp = hbuf + row * DM;
;       float hn[16];
; #pragma unroll
;       for (int q = 0; q < 2; ++q) {
;         const float4 a = *(const float4*)(hp + lane * 16 + q * 8);
;         const float4 bq = *(const float4*)(hp + lane * 16 + q * 8 + 4);
;         hn[q * 8 + 0] = a.x + acc[q * 8 + 0]; hn[q * 8 + 1] = a.y + acc[q * 8 + 1]; hn[q * 8 + 2] = a.z + acc[q * 8 + 2]; hn[q * 8 + 3] = a.w + acc[q * 8 + 3];
;         hn[q * 8 + 4] = bq.x + acc[q * 8 + 4]; hn[q * 8 + 5] = bq.y + acc[q * 8 + 5]; hn[q * 8 + 6] = bq.z + acc[q * 8 + 6]; hn[q * 8 + 7] = bq.w + acc[q * 8 + 7];
	v_cvt_pk_f32_fp8_e32 v[144:145], v120
	v_cvt_pk_f32_fp8_sdwa v[146:147], v120 src0_sel:WORD_1
	v_cvt_pk_f32_fp8_e32 v[148:149], v121
	v_cvt_pk_f32_fp8_sdwa v[150:151], v121 src0_sel:WORD_1
	v_cvt_pk_f32_fp8_e32 v[152:153], v122
	v_cvt_pk_f32_fp8_sdwa v[154:155], v122 src0_sel:WORD_1
	v_cvt_pk_f32_fp8_e32 v[156:157], v123
	v_cvt_pk_f32_fp8_sdwa v[158:159], v123 src0_sel:WORD_1
	v_fmac_f32_e32 v0, v74, v144
	v_fmac_f32_e32 v1, v74, v145
	v_fmac_f32_e32 v2, v74, v146
	v_fmac_f32_e32 v3, v74, v147
	v_fmac_f32_e32 v4, v74, v148
	v_fmac_f32_e32 v5, v74, v149
	v_fmac_f32_e32 v6, v74, v150
	v_fmac_f32_e32 v7, v74, v151
	v_fmac_f32_e32 v8, v74, v152
	v_fmac_f32_e32 v9, v74, v153
	v_fmac_f32_e32 v10, v74, v154
	v_fmac_f32_e32 v11, v74, v155
	v_fmac_f32_e32 v12, v74, v156
	v_fmac_f32_e32 v13, v74, v157
	v_fmac_f32_e32 v14, v74, v158
	v_fmac_f32_e32 v15, v74, v159
	s_waitcnt vmcnt(4)
	v_cvt_pk_f32_fp8_e32 v[144:145], v124
	v_cvt_pk_f32_fp8_sdwa v[146:147], v124 src0_sel:WORD_1
	v_cvt_pk_f32_fp8_e32 v[148:149], v125
	v_cvt_pk_f32_fp8_sdwa v[150:151], v125 src0_sel:WORD_1
	v_cvt_pk_f32_fp8_e32 v[152:153], v126
	v_cvt_pk_f32_fp8_sdwa v[154:155], v126 src0_sel:WORD_1
	v_cvt_pk_f32_fp8_e32 v[156:157], v127
	v_cvt_pk_f32_fp8_sdwa v[158:159], v127 src0_sel:WORD_1
	v_fmac_f32_e32 v0, v75, v144
	v_fmac_f32_e32 v1, v75, v145
	v_fmac_f32_e32 v2, v75, v146
	v_fmac_f32_e32 v3, v75, v147
	v_fmac_f32_e32 v4, v75, v148
	v_fmac_f32_e32 v5, v75, v149
	v_fmac_f32_e32 v6, v75, v150
	v_fmac_f32_e32 v7, v75, v151
	v_fmac_f32_e32 v8, v75, v152
	v_fmac_f32_e32 v9, v75, v153
	v_fmac_f32_e32 v10, v75, v154
	v_fmac_f32_e32 v11, v75, v155
	v_fmac_f32_e32 v12, v75, v156
	v_fmac_f32_e32 v13, v75, v157
	v_fmac_f32_e32 v14, v75, v158
	v_fmac_f32_e32 v15, v75, v159
	s_waitcnt vmcnt(3)
	v_cvt_pk_f32_fp8_e32 v[144:145], v128
	v_cvt_pk_f32_fp8_sdwa v[146:147], v128 src0_sel:WORD_1
	v_cvt_pk_f32_fp8_e32 v[148:149], v129
	v_cvt_pk_f32_fp8_sdwa v[150:151], v129 src0_sel:WORD_1
	v_cvt_pk_f32_fp8_e32 v[152:153], v130
	v_cvt_pk_f32_fp8_sdwa v[154:155], v130 src0_sel:WORD_1
	v_cvt_pk_f32_fp8_e32 v[156:157], v131
	v_cvt_pk_f32_fp8_sdwa v[158:159], v131 src0_sel:WORD_1
	v_fmac_f32_e32 v0, v76, v144
	v_fmac_f32_e32 v1, v76, v145
	v_fmac_f32_e32 v2, v76, v146
	v_fmac_f32_e32 v3, v76, v147
	v_fmac_f32_e32 v4, v76, v148
	v_fmac_f32_e32 v5, v76, v149
	v_fmac_f32_e32 v6, v76, v150
	v_fmac_f32_e32 v7, v76, v151
	v_fmac_f32_e32 v8, v76, v152
	v_fmac_f32_e32 v9, v76, v153
	v_fmac_f32_e32 v10, v76, v154
	v_fmac_f32_e32 v11, v76, v155
	v_fmac_f32_e32 v12, v76, v156
	v_fmac_f32_e32 v13, v76, v157
	v_fmac_f32_e32 v14, v76, v158
	v_fmac_f32_e32 v15, v76, v159
	s_waitcnt vmcnt(2)
	v_cvt_pk_f32_fp8_e32 v[144:145], v132
	v_cvt_pk_f32_fp8_sdwa v[146:147], v132 src0_sel:WORD_1
	v_cvt_pk_f32_fp8_e32 v[148:149], v133
	v_cvt_pk_f32_fp8_sdwa v[150:151], v133 src0_sel:WORD_1
	v_cvt_pk_f32_fp8_e32 v[152:153], v134
	v_cvt_pk_f32_fp8_sdwa v[154:155], v134 src0_sel:WORD_1
	v_cvt_pk_f32_fp8_e32 v[156:157], v135
	v_cvt_pk_f32_fp8_sdwa v[158:159], v135 src0_sel:WORD_1
	v_fmac_f32_e32 v0, v77, v144
	v_fmac_f32_e32 v1, v77, v145
	v_fmac_f32_e32 v2, v77, v146
	v_fmac_f32_e32 v3, v77, v147
	v_fmac_f32_e32 v4, v77, v148
	v_fmac_f32_e32 v5, v77, v149
	v_fmac_f32_e32 v6, v77, v150
	v_fmac_f32_e32 v7, v77, v151
	v_fmac_f32_e32 v8, v77, v152
	v_fmac_f32_e32 v9, v77, v153
	v_fmac_f32_e32 v10, v77, v154
	v_fmac_f32_e32 v11, v77, v155
	v_fmac_f32_e32 v12, v77, v156
	v_fmac_f32_e32 v13, v77, v157
	v_fmac_f32_e32 v14, v77, v158
	v_fmac_f32_e32 v15, v77, v159
	s_waitcnt vmcnt(1)
	v_cvt_pk_f32_fp8_e32 v[144:145], v136
	v_cvt_pk_f32_fp8_sdwa v[146:147], v136 src0_sel:WORD_1
	v_cvt_pk_f32_fp8_e32 v[148:149], v137
	v_cvt_pk_f32_fp8_sdwa v[150:151], v137 src0_sel:WORD_1
	v_cvt_pk_f32_fp8_e32 v[152:153], v138
	v_cvt_pk_f32_fp8_sdwa v[154:155], v138 src0_sel:WORD_1
	v_cvt_pk_f32_fp8_e32 v[156:157], v139
	v_cvt_pk_f32_fp8_sdwa v[158:159], v139 src0_sel:WORD_1
	v_fmac_f32_e32 v0, v78, v144
	v_fmac_f32_e32 v1, v78, v145
	v_fmac_f32_e32 v2, v78, v146
	v_fmac_f32_e32 v3, v78, v147
	v_fmac_f32_e32 v4, v78, v148
	v_fmac_f32_e32 v5, v78, v149
	v_fmac_f32_e32 v6, v78, v150
	v_fmac_f32_e32 v7, v78, v151
	v_fmac_f32_e32 v8, v78, v152
	v_fmac_f32_e32 v9, v78, v153
	v_fmac_f32_e32 v10, v78, v154
	v_fmac_f32_e32 v11, v78, v155
	v_fmac_f32_e32 v12, v78, v156
	v_fmac_f32_e32 v13, v78, v157
	v_fmac_f32_e32 v14, v78, v158
	v_fmac_f32_e32 v15, v78, v159
	s_waitcnt vmcnt(0)
	v_cvt_pk_f32_fp8_e32 v[144:145], v140
	v_cvt_pk_f32_fp8_sdwa v[146:147], v140 src0_sel:WORD_1
	v_cvt_pk_f32_fp8_e32 v[148:149], v141
	v_cvt_pk_f32_fp8_sdwa v[150:151], v141 src0_sel:WORD_1
	v_cvt_pk_f32_fp8_e32 v[152:153], v142
	v_cvt_pk_f32_fp8_sdwa v[154:155], v142 src0_sel:WORD_1
	v_cvt_pk_f32_fp8_e32 v[156:157], v143
	v_cvt_pk_f32_fp8_sdwa v[158:159], v143 src0_sel:WORD_1
	v_fmac_f32_e32 v0, v79, v144
	v_fmac_f32_e32 v1, v79, v145
	v_fmac_f32_e32 v2, v79, v146
	v_fmac_f32_e32 v3, v79, v147
	v_fmac_f32_e32 v4, v79, v148
	v_fmac_f32_e32 v5, v79, v149
	v_fmac_f32_e32 v6, v79, v150
	v_fmac_f32_e32 v7, v79, v151
	v_fmac_f32_e32 v8, v79, v152
	v_fmac_f32_e32 v9, v79, v153
	v_fmac_f32_e32 v10, v79, v154
	v_fmac_f32_e32 v11, v79, v155
	v_fmac_f32_e32 v12, v79, v156
	v_fmac_f32_e32 v13, v79, v157
	v_fmac_f32_e32 v14, v79, v158
	v_fmac_f32_e32 v15, v79, v159
	global_load_dwordx4 v[80:83], v164, s[20:21] offset:0
	global_load_dwordx4 v[84:87], v164, s[20:21] offset:16
	global_load_dwordx4 v[88:91], v164, s[20:21] offset:32
	global_load_dwordx4 v[92:95], v164, s[20:21] offset:48
	s_waitcnt vmcnt(0)
	v_add_f32_e32 v80, v80, v0
	v_add_f32_e32 v81, v81, v1
	v_add_f32_e32 v82, v82, v2
	v_add_f32_e32 v83, v83, v3
	v_add_f32_e32 v84, v84, v4
	v_add_f32_e32 v85, v85, v5
	v_add_f32_e32 v86, v86, v6
	v_add_f32_e32 v87, v87, v7
	v_add_f32_e32 v88, v88, v8
	v_add_f32_e32 v89, v89, v9
	v_add_f32_e32 v90, v90, v10
	v_add_f32_e32 v91, v91, v11
	v_add_f32_e32 v92, v92, v12
	v_add_f32_e32 v93, v93, v13
	v_add_f32_e32 v94, v94, v14
	v_add_f32_e32 v95, v95, v15
	global_store_dwordx4 v164, v[80:83], s[20:21] offset:0
	global_store_dwordx4 v164, v[84:87], s[20:21] offset:16
	global_store_dwordx4 v164, v[88:91], s[20:21] offset:32
	global_store_dwordx4 v164, v[92:95], s[20:21] offset:48
	s_add_u32 s22, s22, s23
	s_cmpk_lt_u32 s22, 0x2010
	s_cbranch_scc1 .Lpv0_item

; DI void phase_peer_b(const Params& p, int layer, const float* gnext, bool last) {
;   const int tid = threadIdx.x, lane = tid & 63, wave = tid >> 6;
;   const float* wbuf = (const float*)(p.ws + OFF_R + R_WBUF);
;   const int* ibuf = (const int*)(p.ws + OFF_R + R_IBUF);
;   u16* xnw = (u16*)(p.ws + OFF_XN);
;   float* hbuf = (float*)(p.ws + OFF_H);
;   const unsigned char* EV = (const unsigned char*)(p.ws + OFF_EXP) + (size_t)(layer * 2 + 1) * NEXP * DM;
; #pragma unroll 1
;   for (size_t row = (size_t)blockIdx.x * 4 + wave; row < (size_t)T; row += (size_t)gridDim.x * 4) {
;     const int i0 = ibuf[row * 128 + lane], i1 = ibuf[row * 128 + 64 + lane];
;     const float w0 = wbuf[row * 128 + lane], w1 = wbuf[row * 128 + 64 + lane];
.LBB0_722:
	s_or_b64 exec, exec, s[2:3]
	s_barrier
	s_mov_b64 exec, -1
	v_mbcnt_lo_u32_b32 v165, -1, 0
	v_mbcnt_hi_u32_b32 v165, -1, v165
	v_and_b32_e32 v160, 7, v165
	v_lshlrev_b32_e32 v167, 6, v160
	v_lshlrev_b32_e32 v160, 4, v160
	v_lshrrev_b32_e32 v166, 3, v165
	s_and_b32 s24, s95, 7
	s_lshr_b32 s22, s95, 3
	s_lshr_b32 s23, s70, 3
	s_cmp_ge_u32 s22, s23
	s_cbranch_scc1 .Lpv1_end
	s_lshl_b32 s22, s22, 2
	s_add_u32 s22, s22, s94
	s_lshl_b32 s23, s23, 2
	s_lshl_b32 s25, s24, 21
	s_add_u32 s25, s25, 0x1b0c0000
	s_add_u32 s14, s68, s25
	s_addc_u32 s15, s69, 0
	s_add_u32 s16, s68, 0x2b4b0800
	s_addc_u32 s17, s69, 0
	s_add_u32 s18, s68, 0x294a0800
	s_addc_u32 s19, s69, 0
	s_lshl_b32 s25, s24, 9
	s_add_u32 s20, s68, s25
	s_addc_u32 s21, s69, 0
	s_mul_i32 s25, s94, 8320
	v_lshlrev_b32_e32 v162, 4, v165
	v_add_u32_e32 v162, s25, v162
	v_mul_u32_u24_e32 v163, 1040, v166
	v_add_u32_e32 v163, s25, v163
	v_and_b32_e32 v161, 31, v165
	v_lshlrev_b32_e32 v161, 4, v161
	v_mov_b32_e32 v168, s16
	v_mov_b32_e32 v169, s17
	v_mov_b32_e32 v170, s18
	v_mov_b32_e32 v171, s19
	v_cmp_gt_u32_e32 vcc, 32, v165
	s_nop 1
	v_cndmask_b32_e32 v168, v170, v168, vcc
	v_cndmask_b32_e32 v169, v171, v169, vcc
	v_add_co_u32_e32 v168, vcc, v168, v161
	s_nop 1
	v_addc_co_u32_e32 v169, vcc, 0, v169, vcc
	s_cmpk_ge_u32 s22, 0x2010
	s_cbranch_scc1 .Lpv1_end
